# in-proj rewritten as well (routed epilogues: rotary, silu, scaled rows, transposed V, glr); rowpass a/c hn stores and wt_in conversion now k-blocked; dead baseline GEMM bodies deleted
# speedup vs baseline: 1.0509x; 1.0200x over previous
_Z11mega_kernel6Params:
	s_add_u32 s4, s0, 0x138
	v_writelane_b32 v244, s2, 0
	s_load_dwordx2 s[8:9], s[0:1], 0x0
	s_load_dwordx2 s[2:3], s[0:1], 0x138
	v_and_b32_e32 v154, 0x3ff, v0
	v_cmp_gt_u32_e32 vcc, 4, v154
	s_waitcnt lgkmcnt(0)
	v_writelane_b32 v244, s2, 1
	s_nop 1
	v_writelane_b32 v244, s3, 2
	v_writelane_b32 v244, s0, 3
	s_addc_u32 s5, s1, 0
	s_nop 0
	v_writelane_b32 v244, s1, 4
	s_and_saveexec_b64 s[6:7], vcc
	v_mov_b32_e32 v1, 0x12000
	v_lshl_or_b32 v1, v154, 2, v1
	v_mov_b32_e32 v2, 0
	ds_write_b32 v1, v2
	s_or_b64 exec, exec, s[6:7]
	v_readlane_b32 s0, v244, 3
	v_readlane_b32 s1, v244, 4
	s_load_dwordx2 s[64:65], s[0:1], 0x130
	s_load_dwordx4 s[12:15], s[0:1], 0xa8
	s_load_dwordx2 s[10:11], s[0:1], 0xc0
	s_load_dwordx2 s[16:17], s[0:1], 0x98
	s_cmp_lg_u64 s[8:9], 0
	s_waitcnt lgkmcnt(0)
	v_writelane_b32 v244, s12, 58
	v_writelane_b32 v244, s14, 59
	v_writelane_b32 v244, s10, 60
	v_writelane_b32 v244, s11, 61
	v_writelane_b32 v244, s16, 62
	s_barrier
	s_cbranch_scc1 .LBB0_14
	v_lshrrev_b32_e32 v1, 20, v0
	v_lshrrev_b32_e32 v0, 10, v0
	v_or_b32_e32 v0, v0, v1
	s_movk_i32 s0, 0x3ff
	v_and_or_b32 v0, v0, s0, v154
	v_cmp_eq_u32_e32 vcc, 0, v0
	s_barrier
	s_and_saveexec_b64 s[0:1], vcc
	s_cbranch_execz .LBB0_13
	buffer_wbl2 sc1
	s_load_dwordx2 s[4:5], s[4:5], 0x58
	s_mov_b64 s[6:7], exec
	v_mbcnt_lo_u32_b32 v0, s6, 0
	v_mbcnt_hi_u32_b32 v0, s7, v0
	v_cmp_eq_u32_e32 vcc, 0, v0
	s_waitcnt lgkmcnt(0)
	s_load_dword s2, s[4:5], 0x28
	s_and_saveexec_b64 s[8:9], vcc
	s_cbranch_execz .LBB0_6
	s_bcnt1_i32_b64 s3, s[6:7]
	v_mov_b32_e32 v1, 0
	v_mov_b32_e32 v2, s3
	global_atomic_add v1, v1, v2, s[4:5] offset:32 sc0

.LBB0_21:
	v_readlane_b32 s6, v244, 1
	v_readlane_b32 s7, v244, 2
	s_cmp_lt_u32 s70, 11
	v_readlane_b32 s0, v244, 3
	s_mov_b32 s71, s6
	s_cselect_b64 s[6:7], -1, 0
	s_add_i32 s20, s70, -9
	v_readlane_b32 s1, v244, 4
	v_readlane_b32 s3, v244, 0
	s_cmp_gt_u32 s70, 10
	s_cselect_b64 s[22:23], -1, 0
	s_waitcnt lgkmcnt(0)
	s_load_dwordx2 s[24:25], s[0:1], 0xb8
	s_and_b64 s[18:19], s[22:23], exec
	s_cselect_b32 s18, s20, s70
	s_cmp_lt_u32 s70, 2
	s_cselect_b32 s19, s70, s18
	s_cmp_eq_u32 s19, 9
	s_cbranch_scc1 .Lgy_entry
	s_cmp_eq_u32 s19, 8
	s_cbranch_scc1 .Lup_entry
	s_cmp_eq_u32 s19, 2
	s_cbranch_scc1 .Lpj_entry
	s_cmp_lt_i32 s19, 5
	s_cbranch_scc1 .LBB0_46
	s_and_b64 s[20:21], s[22:23], exec
	s_cselect_b32 s18, 0x18000, 0
	s_waitcnt lgkmcnt(0)
	s_add_u32 s66, s24, s18
	s_addc_u32 s80, s25, 0
	s_cmp_gt_i32 s19, 7
	s_cbranch_scc0 .LBB0_47
	s_cmp_gt_i32 s19, 8
	s_cbranch_scc0 .LBB0_48
	s_cmp_gt_i32 s19, 9
	s_cbranch_scc0 .LBB0_64
	s_mov_b64 s[20:21], 0
	s_mov_b64 s[24:25], 0
	s_cmp_eq_u32 s19, 10
	v_writelane_b32 v244, s20, 56
	s_nop 1
	v_writelane_b32 v244, s21, 57
	s_cbranch_scc0 .LBB0_65
	s_load_dwordx2 s[30:31], s[0:1], 0x68
	s_and_b64 vcc, exec, s[6:7]
	s_cbranch_vccz .LBB0_334
	s_lshl_b32 s18, s71, 2
	s_abs_i32 s6, s18
	v_cvt_f32_u32_e32 v0, s6
	s_waitcnt vmcnt(0)
	v_mov_b32_e32 v34, v154
	v_mov_b32_e32 v2, v154
	s_sub_i32 s26, 0, s6
	v_rcp_iflag_f32_e32 v0, v0
	s_nop 0
	v_mul_f32_e32 v0, 0x4f7ffffe, v0
	v_cvt_u32_f32_e32 v0, v0
	v_readfirstlane_b32 s7, v2
	s_ashr_i32 s20, s7, 6
	s_add_i32 s7, s18, 0x3fff
	v_readfirstlane_b32 s27, v0
	s_mul_i32 s26, s26, s27
	s_mul_hi_u32 s26, s27, s26
	s_xor_b32 s21, s7, s18
	s_abs_i32 s7, s7
	s_add_i32 s27, s27, s26
	s_mul_hi_u32 s26, s7, s27
	s_mul_i32 s27, s26, s6
	s_sub_i32 s7, s7, s27
	s_ashr_i32 s21, s21, 31
	s_add_i32 s27, s26, 1
	s_sub_i32 s28, s7, s6
	s_cmp_ge_u32 s7, s6
	s_cselect_b32 s26, s27, s26
	s_cselect_b32 s7, s28, s7
	s_add_i32 s27, s26, 1
	s_cmp_ge_u32 s7, s6
	s_cselect_b32 s6, s27, s26
	s_xor_b32 s6, s6, s21
	s_lshl_b32 s52, s3, 2
	s_sub_i32 s7, s6, s21
	s_add_i32 s6, s20, s52
	s_mul_i32 s6, s6, s7
	s_cmpk_gt_i32 s6, 0x3fff
	s_cbranch_scc1 .LBB0_335
	s_load_dwordx2 s[26:27], s[0:1], 0x110
	s_ashr_i32 s20, s6, 12
	s_mulk_i32 s20, 0x1800
	v_lshlrev_b32_e32 v0, 2, v34
	v_and_b32_e32 v35, 0xfc, v0
	s_waitcnt lgkmcnt(0)
	s_cmp_lg_u64 s[26:27], 0
	s_cselect_b64 s[40:41], -1, 0
	s_ashr_i32 s21, s20, 31
	s_lshl_b64 s[34:35], s[20:21], 2
	s_add_u32 s20, s66, s34
	s_addc_u32 s21, s80, s35
	s_add_u32 s36, s20, 0x5000
	s_addc_u32 s37, s21, 0
	s_and_b64 vcc, exec, s[40:41]
	v_lshlrev_b32_e32 v0, 2, v35
	s_cbranch_vccz .LBB0_30
	v_lshl_add_u64 v[10:11], s[36:37], 0, v[0:1]
	v_add_co_u32_e32 v6, vcc, 0x30000, v10
	global_load_dwordx4 v[2:5], v0, s[36:37]
	s_nop 0
	v_addc_co_u32_e32 v7, vcc, 0, v11, vcc
	global_load_dwordx4 v[6:9], v[6:7], off
	s_waitcnt vmcnt(0)
	v_pk_add_f32 v[6:7], v[2:3], v[6:7]
	v_add_co_u32_e32 v2, vcc, 0x60000, v10
	v_pk_add_f32 v[8:9], v[4:5], v[8:9]
	s_nop 0
	v_addc_co_u32_e32 v3, vcc, 0, v11, vcc
	global_load_dwordx4 v[2:5], v[2:3], off
	s_waitcnt vmcnt(0)
	v_pk_add_f32 v[6:7], v[6:7], v[2:3]
	v_add_co_u32_e32 v2, vcc, 0x90000, v10
	v_pk_add_f32 v[8:9], v[8:9], v[4:5]
	s_nop 0
	v_addc_co_u32_e32 v3, vcc, 0, v11, vcc
	global_load_dwordx4 v[2:5], v[2:3], off
	s_waitcnt vmcnt(0)
	v_pk_add_f32 v[68:69], v[8:9], v[4:5]
	v_pk_add_f32 v[66:67], v[6:7], v[2:3]
	global_load_dwordx4 v[2:5], v0, s[30:31]

.LBB0_57:
	s_and_b64 vcc, exec, s[40:41]
	s_cbranch_vccnz .LBB0_59
	s_waitcnt vmcnt(2)
	v_mov_b32_e32 v152, v59
	v_mov_b32_e32 v153, v63
	v_mov_b32_e32 v150, v58
	v_mov_b32_e32 v151, v62
	v_pk_mul_f32 v[152:153], v[152:153], v[152:153]
	s_waitcnt vmcnt(0)
	v_mov_b32_e32 v168, v51
	v_pk_fma_f32 v[150:151], v[150:151], v[150:151], v[152:153]
	v_mov_b32_e32 v152, v60
	v_mov_b32_e32 v153, v64
	v_pk_fma_f32 v[150:151], v[152:153], v[152:153], v[150:151]
	v_mov_b32_e32 v152, v61
	v_mov_b32_e32 v153, v65
	v_mov_b32_e32 v169, v55
	v_pk_fma_f32 v[150:151], v[152:153], v[152:153], v[150:151]
	v_mov_b32_e32 v152, v50
	v_mov_b32_e32 v153, v54
	v_pk_mul_f32 v[168:169], v[168:169], v[168:169]
	v_and_b32_e32 v99, 64, v159
	v_pk_fma_f32 v[152:153], v[152:153], v[152:153], v[168:169]
	v_mov_b32_e32 v168, v52
	v_mov_b32_e32 v169, v56
	v_pk_fma_f32 v[152:153], v[168:169], v[168:169], v[152:153]
	v_mov_b32_e32 v168, v53
	v_mov_b32_e32 v169, v57
	v_add_u32_e32 v99, 64, v99
	v_xor_b32_e32 v101, 32, v159
	v_pk_fma_f32 v[152:153], v[168:169], v[168:169], v[152:153]
	v_add_f32_e32 v0, v150, v151
	v_cmp_lt_i32_e32 vcc, v101, v99
	v_add_f32_e32 v0, v153, v0
	v_add_f32_e32 v0, v152, v0
	v_cndmask_b32_e32 v101, v159, v101, vcc
	v_lshlrev_b32_e32 v101, 2, v101
	ds_bpermute_b32 v101, v101, v0
	s_waitcnt lgkmcnt(0)
	v_add_f32_e32 v0, v0, v101
	v_xor_b32_e32 v101, 16, v159
	v_cmp_lt_i32_e32 vcc, v101, v99
	s_nop 1
	v_cndmask_b32_e32 v101, v159, v101, vcc
	v_lshlrev_b32_e32 v101, 2, v101
	ds_bpermute_b32 v101, v101, v0
	s_waitcnt lgkmcnt(0)
	v_add_f32_e32 v0, v0, v101
	v_xor_b32_e32 v101, 8, v159
	v_cmp_lt_i32_e32 vcc, v101, v99
	s_nop 1
	v_cndmask_b32_e32 v101, v159, v101, vcc
	v_lshlrev_b32_e32 v101, 2, v101
	ds_bpermute_b32 v101, v101, v0
	s_waitcnt lgkmcnt(0)
	v_add_f32_e32 v0, v0, v101
	v_xor_b32_e32 v101, 4, v159
	v_cmp_lt_i32_e32 vcc, v101, v99
	s_nop 1
	v_cndmask_b32_e32 v101, v159, v101, vcc
	v_lshlrev_b32_e32 v101, 2, v101
	ds_bpermute_b32 v101, v101, v0
	s_waitcnt lgkmcnt(0)
	v_add_f32_e32 v0, v0, v101
	v_xor_b32_e32 v101, 2, v159
	v_cmp_lt_i32_e32 vcc, v101, v99
	s_nop 1
	v_cndmask_b32_e32 v101, v159, v101, vcc
	v_lshlrev_b32_e32 v101, 2, v101
	ds_bpermute_b32 v101, v101, v0
	s_waitcnt lgkmcnt(0)
	v_add_f32_e32 v0, v0, v101
	v_xor_b32_e32 v101, 1, v159
	v_cmp_lt_i32_e32 vcc, v101, v99
	s_nop 1
	v_cndmask_b32_e32 v99, v159, v101, vcc
	v_lshlrev_b32_e32 v99, 2, v99
	ds_bpermute_b32 v99, v99, v0
	s_waitcnt lgkmcnt(0)
	v_add_f32_e32 v0, v0, v99
	v_fmamk_f32 v0, v0, 0x3a800000, v155
	v_mul_f32_e32 v99, 0x4b800000, v0
	v_cmp_gt_f32_e32 vcc, s84, v0
	s_nop 1
	v_cndmask_b32_e32 v0, v0, v99, vcc
	v_rsq_f32_e32 v0, v0
	s_nop 0
	v_mul_f32_e32 v99, 0x45800000, v0
	v_cndmask_b32_e32 v0, v0, v99, vcc
	v_pk_mul_f32 v[64:65], v[64:65], v[0:1] op_sel_hi:[1,0]
	v_pk_mul_f32 v[62:63], v[62:63], v[0:1] op_sel_hi:[1,0]
	v_pk_mul_f32 v[60:61], v[60:61], v[0:1] op_sel_hi:[1,0]
	v_pk_mul_f32 v[58:59], v[58:59], v[0:1] op_sel_hi:[1,0]
	v_pk_mul_f32 v[56:57], v[56:57], v[0:1] op_sel_hi:[1,0]
	v_pk_mul_f32 v[54:55], v[54:55], v[0:1] op_sel_hi:[1,0]
	v_pk_mul_f32 v[52:53], v[52:53], v[0:1] op_sel_hi:[1,0]
	v_pk_mul_f32 v[50:51], v[50:51], v[0:1] op_sel_hi:[1,0]
	v_pk_mul_f32 v[62:63], v[6:7], v[62:63]
	v_pk_mul_f32 v[64:65], v[8:9], v[64:65]
	v_pk_mul_f32 v[58:59], v[14:15], v[58:59]
	v_pk_mul_f32 v[60:61], v[16:17], v[60:61]
	v_pk_mul_f32 v[54:55], v[22:23], v[54:55]
	v_pk_mul_f32 v[56:57], v[24:25], v[56:57]
	v_pk_mul_f32 v[50:51], v[30:31], v[50:51]
	v_pk_mul_f32 v[52:53], v[32:33], v[52:53]
	v_pk_fma_f32 v[64:65], v[72:73], v[64:65], v[76:77]
	v_pk_fma_f32 v[62:63], v[70:71], v[62:63], v[74:75]
	v_pk_fma_f32 v[60:61], v[84:85], v[60:61], v[88:89]
	v_pk_fma_f32 v[58:59], v[82:83], v[58:59], v[86:87]
	v_pk_fma_f32 v[56:57], v[96:97], v[56:57], v[108:109]
	v_pk_fma_f32 v[54:55], v[94:95], v[54:55], v[106:107]
	v_pk_fma_f32 v[52:53], v[116:117], v[52:53], v[120:121]
	v_pk_fma_f32 v[50:51], v[114:115], v[50:51], v[118:119]
	v_cvt_pk_bf16_f32 v62, v62, v63
	v_cvt_pk_bf16_f32 v63, v64, v65
	v_cvt_pk_bf16_f32 v58, v58, v59
	v_cvt_pk_bf16_f32 v59, v60, v61
	v_cvt_pk_bf16_f32 v54, v54, v55
	v_cvt_pk_bf16_f32 v55, v56, v57
	v_cvt_pk_bf16_f32 v50, v50, v51
	v_cvt_pk_bf16_f32 v51, v52, v53
	v_readlane_b32 vcc_lo, v244, 60
	v_readlane_b32 vcc_hi, v244, 61
	s_nop 3
	v_subrev_u32_e32 v64, vcc_lo, v132
	v_add_u32_e32 v64, 0xfffffc00, v64
	v_and_b32_e32 v60, 0x7ff, v64
	v_lshrrev_b32_e32 v64, 11, v64
	v_lshlrev_b32_e32 v64, 6, v64
	v_lshrrev_b32_e32 v61, 6, v60
	v_lshl_or_b32 v64, v61, 20, v64
	v_and_or_b32 v64, v60, 63, v64
	v_mov_b32_e32 v65, 0
	v_lshl_add_u64 v[64:65], vcc, 0, v[64:65]
	global_store_dwordx2 v[64:65], v[62:63], off
	v_subrev_u32_e32 v64, vcc_lo, v132
	v_add_u32_e32 v64, 0xfffffe00, v64
	v_and_b32_e32 v60, 0x7ff, v64
	v_lshrrev_b32_e32 v64, 11, v64
	v_lshlrev_b32_e32 v64, 6, v64
	v_lshrrev_b32_e32 v61, 6, v60
	v_lshl_or_b32 v64, v61, 20, v64
	v_and_or_b32 v64, v60, 63, v64
	v_mov_b32_e32 v65, 0
	v_lshl_add_u64 v[64:65], vcc, 0, v[64:65]
	global_store_dwordx2 v[64:65], v[58:59], off
	v_subrev_u32_e32 v64, vcc_lo, v132
	v_and_b32_e32 v60, 0x7ff, v64
	v_lshrrev_b32_e32 v64, 11, v64
	v_lshlrev_b32_e32 v64, 6, v64
	v_lshrrev_b32_e32 v61, 6, v60
	v_lshl_or_b32 v64, v61, 20, v64
	v_and_or_b32 v64, v60, 63, v64
	v_mov_b32_e32 v65, 0
	v_lshl_add_u64 v[64:65], vcc, 0, v[64:65]
	global_store_dwordx2 v[64:65], v[54:55], off
	v_subrev_u32_e32 v64, vcc_lo, v132
	v_add_u32_e32 v64, 0x200, v64
	v_and_b32_e32 v60, 0x7ff, v64
	v_lshrrev_b32_e32 v64, 11, v64
	v_lshlrev_b32_e32 v64, 6, v64
	v_lshrrev_b32_e32 v61, 6, v60
	v_lshl_or_b32 v64, v61, 20, v64
	v_and_or_b32 v64, v60, 63, v64
	v_mov_b32_e32 v65, 0
	v_lshl_add_u64 v[64:65], vcc, 0, v[64:65]
	global_store_dwordx2 v[64:65], v[50:51], off

.LBB0_62:
	s_and_b64 vcc, exec, s[40:41]
	s_cbranch_vccnz .LBB0_49
	s_waitcnt vmcnt(0)
	v_mov_b32_e32 v52, v39
	v_mov_b32_e32 v53, v35
	v_mov_b32_e32 v50, v38
	v_mov_b32_e32 v51, v34
	v_pk_mul_f32 v[52:53], v[52:53], v[52:53]
	v_mov_b32_e32 v54, v47
	v_pk_fma_f32 v[50:51], v[50:51], v[50:51], v[52:53]
	v_mov_b32_e32 v52, v40
	v_mov_b32_e32 v53, v36
	v_pk_fma_f32 v[50:51], v[52:53], v[52:53], v[50:51]
	v_mov_b32_e32 v52, v41
	v_mov_b32_e32 v53, v37
	v_mov_b32_e32 v55, v43
	v_pk_fma_f32 v[50:51], v[52:53], v[52:53], v[50:51]
	v_mov_b32_e32 v52, v46
	v_mov_b32_e32 v53, v42
	v_pk_mul_f32 v[54:55], v[54:55], v[54:55]
	v_add_f32_e32 v0, v50, v51
	v_pk_fma_f32 v[52:53], v[52:53], v[52:53], v[54:55]
	v_mov_b32_e32 v54, v48
	v_mov_b32_e32 v55, v44
	v_and_b32_e32 v50, 64, v159
	v_pk_fma_f32 v[52:53], v[54:55], v[54:55], v[52:53]
	v_mov_b32_e32 v54, v49
	v_mov_b32_e32 v55, v45
	v_add_u32_e32 v50, 64, v50
	v_xor_b32_e32 v51, 32, v159
	v_pk_fma_f32 v[52:53], v[54:55], v[54:55], v[52:53]
	v_cmp_lt_i32_e32 vcc, v51, v50
	v_add_f32_e32 v0, v53, v0
	v_add_f32_e32 v0, v52, v0
	v_cndmask_b32_e32 v51, v159, v51, vcc
	v_lshlrev_b32_e32 v51, 2, v51
	ds_bpermute_b32 v51, v51, v0
	s_ashr_i32 s21, s20, 31
	s_lshl_b64 s[20:21], s[20:21], 11
	s_waitcnt lgkmcnt(0)
	v_add_f32_e32 v0, v0, v51
	v_xor_b32_e32 v51, 16, v159
	v_cmp_lt_i32_e32 vcc, v51, v50
	s_nop 1
	v_cndmask_b32_e32 v51, v159, v51, vcc
	v_lshlrev_b32_e32 v51, 2, v51
	ds_bpermute_b32 v51, v51, v0
	s_waitcnt lgkmcnt(0)
	v_add_f32_e32 v0, v0, v51
	v_xor_b32_e32 v51, 8, v159
	v_cmp_lt_i32_e32 vcc, v51, v50
	s_nop 1
	v_cndmask_b32_e32 v51, v159, v51, vcc
	v_lshlrev_b32_e32 v51, 2, v51
	ds_bpermute_b32 v51, v51, v0
	s_waitcnt lgkmcnt(0)
	v_add_f32_e32 v0, v0, v51
	v_xor_b32_e32 v51, 4, v159
	v_cmp_lt_i32_e32 vcc, v51, v50
	s_nop 1
	v_cndmask_b32_e32 v51, v159, v51, vcc
	v_lshlrev_b32_e32 v51, 2, v51
	ds_bpermute_b32 v51, v51, v0
	s_waitcnt lgkmcnt(0)
	v_add_f32_e32 v0, v0, v51
	v_xor_b32_e32 v51, 2, v159
	v_cmp_lt_i32_e32 vcc, v51, v50
	s_nop 1
	v_cndmask_b32_e32 v51, v159, v51, vcc
	v_lshlrev_b32_e32 v51, 2, v51
	ds_bpermute_b32 v51, v51, v0
	s_waitcnt lgkmcnt(0)
	v_add_f32_e32 v0, v0, v51
	v_xor_b32_e32 v51, 1, v159
	v_cmp_lt_i32_e32 vcc, v51, v50
	s_nop 1
	v_cndmask_b32_e32 v50, v159, v51, vcc
	v_lshlrev_b32_e32 v50, 2, v50
	ds_bpermute_b32 v50, v50, v0
	s_waitcnt lgkmcnt(0)
	v_add_f32_e32 v0, v0, v50
	v_fmamk_f32 v0, v0, 0x3a800000, v155
	v_mul_f32_e32 v50, 0x4b800000, v0
	v_cmp_gt_f32_e32 vcc, s84, v0
	s_nop 1
	v_cndmask_b32_e32 v0, v0, v50, vcc
	v_rsq_f32_e32 v0, v0
	s_nop 0
	v_mul_f32_e32 v50, 0x45800000, v0
	v_cndmask_b32_e32 v0, v0, v50, vcc
	v_pk_mul_f32 v[52:53], v[36:37], v[0:1] op_sel_hi:[1,0]
	v_pk_mul_f32 v[54:55], v[34:35], v[0:1] op_sel_hi:[1,0]
	v_pk_mul_f32 v[52:53], v[8:9], v[52:53]
	v_pk_mul_f32 v[54:55], v[6:7], v[54:55]
	v_pk_fma_f32 v[52:53], v[72:73], v[52:53], v[76:77]
	v_pk_fma_f32 v[54:55], v[70:71], v[54:55], v[74:75]
	v_lshl_add_u64 v[50:51], v[126:127], 0, s[20:21]
	v_cvt_pk_bf16_f32 v54, v54, v55
	v_cvt_pk_bf16_f32 v55, v52, v53
	v_readlane_b32 vcc_lo, v244, 60
	v_readlane_b32 vcc_hi, v244, 61
	s_nop 3
	v_subrev_u32_e32 v34, vcc_lo, v50
	v_and_b32_e32 v36, 0x7ff, v34
	v_lshrrev_b32_e32 v34, 11, v34
	v_lshlrev_b32_e32 v34, 6, v34
	v_lshrrev_b32_e32 v37, 6, v36
	v_lshl_or_b32 v34, v37, 20, v34
	v_and_or_b32 v34, v36, 63, v34
	v_mov_b32_e32 v35, 0
	v_lshl_add_u64 v[34:35], vcc, 0, v[34:35]
	global_store_dwordx2 v[34:35], v[54:55], off
	v_pk_mul_f32 v[52:53], v[40:41], v[0:1] op_sel_hi:[1,0]
	v_pk_mul_f32 v[54:55], v[38:39], v[0:1] op_sel_hi:[1,0]
	v_pk_mul_f32 v[52:53], v[16:17], v[52:53]
	v_pk_mul_f32 v[54:55], v[14:15], v[54:55]
	v_pk_fma_f32 v[52:53], v[84:85], v[52:53], v[88:89]
	v_pk_fma_f32 v[54:55], v[82:83], v[54:55], v[86:87]
	s_nop 0
	v_cvt_pk_bf16_f32 v54, v54, v55
	v_cvt_pk_bf16_f32 v55, v52, v53
	v_subrev_u32_e32 v34, vcc_lo, v50
	v_add_u32_e32 v34, 0x200, v34
	v_and_b32_e32 v36, 0x7ff, v34
	v_lshrrev_b32_e32 v34, 11, v34
	v_lshlrev_b32_e32 v34, 6, v34
	v_lshrrev_b32_e32 v37, 6, v36
	v_lshl_or_b32 v34, v37, 20, v34
	v_and_or_b32 v34, v36, 63, v34
	v_mov_b32_e32 v35, 0
	v_lshl_add_u64 v[34:35], vcc, 0, v[34:35]
	global_store_dwordx2 v[34:35], v[54:55], off
	v_pk_mul_f32 v[52:53], v[44:45], v[0:1] op_sel_hi:[1,0]
	v_pk_mul_f32 v[54:55], v[42:43], v[0:1] op_sel_hi:[1,0]
	v_pk_mul_f32 v[52:53], v[24:25], v[52:53]
	v_pk_mul_f32 v[54:55], v[22:23], v[54:55]
	v_pk_fma_f32 v[52:53], v[96:97], v[52:53], v[108:109]
	v_pk_fma_f32 v[54:55], v[94:95], v[54:55], v[106:107]
	s_nop 0
	v_cvt_pk_bf16_f32 v54, v54, v55
	v_cvt_pk_bf16_f32 v55, v52, v53
	v_subrev_u32_e32 v34, vcc_lo, v50
	v_add_u32_e32 v34, 0x400, v34
	v_and_b32_e32 v36, 0x7ff, v34
	v_lshrrev_b32_e32 v34, 11, v34
	v_lshlrev_b32_e32 v34, 6, v34
	v_lshrrev_b32_e32 v37, 6, v36
	v_lshl_or_b32 v34, v37, 20, v34
	v_and_or_b32 v34, v36, 63, v34
	v_mov_b32_e32 v35, 0
	v_lshl_add_u64 v[34:35], vcc, 0, v[34:35]
	global_store_dwordx2 v[34:35], v[54:55], off
	v_pk_mul_f32 v[52:53], v[48:49], v[0:1] op_sel_hi:[1,0]
	v_pk_mul_f32 v[54:55], v[46:47], v[0:1] op_sel_hi:[1,0]
	v_pk_mul_f32 v[52:53], v[32:33], v[52:53]
	v_pk_mul_f32 v[54:55], v[30:31], v[54:55]
	v_pk_fma_f32 v[52:53], v[116:117], v[52:53], v[120:121]
	v_pk_fma_f32 v[54:55], v[114:115], v[54:55], v[118:119]
	s_nop 0
	v_cvt_pk_bf16_f32 v54, v54, v55
	v_cvt_pk_bf16_f32 v55, v52, v53
	v_subrev_u32_e32 v34, vcc_lo, v50
	v_add_u32_e32 v34, 0x600, v34
	v_and_b32_e32 v36, 0x7ff, v34
	v_lshrrev_b32_e32 v34, 11, v34
	v_lshlrev_b32_e32 v34, 6, v34
	v_lshrrev_b32_e32 v37, 6, v36
	v_lshl_or_b32 v34, v37, 20, v34
	v_and_or_b32 v34, v36, 63, v34
	v_mov_b32_e32 v35, 0
	v_lshl_add_u64 v[34:35], vcc, 0, v[34:35]
	global_store_dwordx2 v[34:35], v[54:55], off
	s_branch .LBB0_49

.LBB0_65:
	s_and_b64 vcc, exec, s[24:25]
	s_cbranch_vccz .LBB0_81
.LBB0_81:
	s_branch .LBB0_120

.LBB0_226:
	s_andn2_b64 vcc, exec, s[6:7]
	s_cbranch_vccnz .LBB0_303
.LBB0_303:
	s_mov_b64 s[6:7], 0

.LBB0_322:
	s_waitcnt vmcnt(3)
	v_mov_b32_e32 v86, v47
	s_waitcnt vmcnt(2)
	v_mov_b32_e32 v87, v43
	v_mov_b32_e32 v84, v46
	v_mov_b32_e32 v85, v42
	v_pk_mul_f32 v[86:87], v[86:87], v[86:87]
	s_waitcnt vmcnt(1)
	v_mov_b32_e32 v88, v39
	v_pk_fma_f32 v[84:85], v[84:85], v[84:85], v[86:87]
	v_mov_b32_e32 v86, v48
	v_mov_b32_e32 v87, v44
	v_pk_fma_f32 v[84:85], v[86:87], v[86:87], v[84:85]
	v_mov_b32_e32 v86, v49
	v_mov_b32_e32 v87, v45
	s_waitcnt vmcnt(0)
	v_mov_b32_e32 v89, v35
	v_pk_fma_f32 v[84:85], v[86:87], v[86:87], v[84:85]
	v_mov_b32_e32 v86, v38
	v_mov_b32_e32 v87, v34
	v_pk_mul_f32 v[88:89], v[88:89], v[88:89]
	v_add_f32_e32 v84, v84, v85
	v_pk_fma_f32 v[86:87], v[86:87], v[86:87], v[88:89]
	v_mov_b32_e32 v88, v40
	v_mov_b32_e32 v89, v36
	v_pk_fma_f32 v[86:87], v[88:89], v[88:89], v[86:87]
	v_mov_b32_e32 v88, v41
	v_mov_b32_e32 v89, v37
	v_pk_fma_f32 v[86:87], v[88:89], v[88:89], v[86:87]
	v_and_b32_e32 v85, 64, v159
	v_add_f32_e32 v84, v84, v86
	v_add_u32_e32 v85, 64, v85
	v_xor_b32_e32 v86, 32, v159
	v_cmp_lt_i32_e32 vcc, v86, v85
	v_add_f32_e32 v84, v84, v87
	s_nop 0
	v_cndmask_b32_e32 v86, v159, v86, vcc
	v_lshlrev_b32_e32 v86, 2, v86
	ds_bpermute_b32 v86, v86, v84
	s_waitcnt lgkmcnt(0)
	v_add_f32_e32 v84, v84, v86
	v_xor_b32_e32 v86, 16, v159
	v_cmp_lt_i32_e32 vcc, v86, v85
	s_nop 1
	v_cndmask_b32_e32 v86, v159, v86, vcc
	v_lshlrev_b32_e32 v86, 2, v86
	ds_bpermute_b32 v86, v86, v84
	s_waitcnt lgkmcnt(0)
	v_add_f32_e32 v84, v84, v86
	v_xor_b32_e32 v86, 8, v159
	v_cmp_lt_i32_e32 vcc, v86, v85
	s_nop 1
	v_cndmask_b32_e32 v86, v159, v86, vcc
	v_lshlrev_b32_e32 v86, 2, v86
	ds_bpermute_b32 v86, v86, v84
	s_waitcnt lgkmcnt(0)
	v_add_f32_e32 v84, v84, v86
	v_xor_b32_e32 v86, 4, v159
	v_cmp_lt_i32_e32 vcc, v86, v85
	s_nop 1
	v_cndmask_b32_e32 v86, v159, v86, vcc
	v_lshlrev_b32_e32 v86, 2, v86
	ds_bpermute_b32 v86, v86, v84
	s_waitcnt lgkmcnt(0)
	v_add_f32_e32 v84, v84, v86
	v_xor_b32_e32 v86, 2, v159
	v_cmp_lt_i32_e32 vcc, v86, v85
	s_nop 1
	v_cndmask_b32_e32 v86, v159, v86, vcc
	v_lshlrev_b32_e32 v86, 2, v86
	ds_bpermute_b32 v86, v86, v84
	s_waitcnt lgkmcnt(0)
	v_add_f32_e32 v84, v84, v86
	v_xor_b32_e32 v86, 1, v159
	v_cmp_lt_i32_e32 vcc, v86, v85
	s_nop 1
	v_cndmask_b32_e32 v85, v159, v86, vcc
	v_lshlrev_b32_e32 v85, 2, v85
	ds_bpermute_b32 v85, v85, v84
	v_lshl_add_u64 v[86:87], s[24:25], 0, v[82:83]
	s_waitcnt lgkmcnt(0)
	v_add_f32_e32 v84, v84, v85
	v_fmamk_f32 v84, v84, 0x3a800000, v155
	v_mul_f32_e32 v85, 0x4b800000, v84
	v_cmp_gt_f32_e32 vcc, s84, v84
	s_nop 1
	v_cndmask_b32_e32 v84, v84, v85, vcc
	v_rsq_f32_e32 v84, v84
	s_nop 0
	v_mul_f32_e32 v85, 0x45800000, v84
	v_cndmask_b32_e32 v84, v84, v85, vcc
	v_pk_mul_f32 v[48:49], v[48:49], v[84:85] op_sel_hi:[1,0]
	v_pk_mul_f32 v[46:47], v[46:47], v[84:85] op_sel_hi:[1,0]
	v_pk_mul_f32 v[44:45], v[44:45], v[84:85] op_sel_hi:[1,0]
	v_pk_mul_f32 v[42:43], v[42:43], v[84:85] op_sel_hi:[1,0]
	v_pk_mul_f32 v[40:41], v[40:41], v[84:85] op_sel_hi:[1,0]
	v_pk_mul_f32 v[38:39], v[38:39], v[84:85] op_sel_hi:[1,0]
	v_pk_mul_f32 v[36:37], v[36:37], v[84:85] op_sel_hi:[1,0]
	v_pk_mul_f32 v[34:35], v[34:35], v[84:85] op_sel_hi:[1,0]
	v_pk_mul_f32 v[46:47], v[2:3], v[46:47]
	v_pk_mul_f32 v[48:49], v[4:5], v[48:49]
	v_pk_mul_f32 v[42:43], v[6:7], v[42:43]
	v_pk_mul_f32 v[44:45], v[8:9], v[44:45]
	v_pk_mul_f32 v[38:39], v[10:11], v[38:39]
	v_pk_mul_f32 v[40:41], v[12:13], v[40:41]
	v_pk_mul_f32 v[34:35], v[14:15], v[34:35]
	v_pk_mul_f32 v[36:37], v[16:17], v[36:37]
	v_pk_fma_f32 v[48:49], v[52:53], v[48:49], v[56:57]
	v_pk_fma_f32 v[46:47], v[50:51], v[46:47], v[54:55]
	v_pk_fma_f32 v[44:45], v[60:61], v[44:45], v[64:65]
	v_pk_fma_f32 v[42:43], v[58:59], v[42:43], v[62:63]
	v_pk_fma_f32 v[40:41], v[68:69], v[40:41], v[72:73]
	v_pk_fma_f32 v[38:39], v[66:67], v[38:39], v[70:71]
	v_pk_fma_f32 v[36:37], v[76:77], v[36:37], v[80:81]
	v_pk_fma_f32 v[34:35], v[74:75], v[34:35], v[78:79]
	v_cvt_pk_bf16_f32 v46, v46, v47
	v_cvt_pk_bf16_f32 v47, v48, v49
	v_cvt_pk_bf16_f32 v42, v42, v43
	v_cvt_pk_bf16_f32 v43, v44, v45
	v_cvt_pk_bf16_f32 v38, v38, v39
	v_cvt_pk_bf16_f32 v39, v40, v41
	v_cvt_pk_bf16_f32 v34, v34, v35
	v_cvt_pk_bf16_f32 v35, v36, v37
	v_readlane_b32 vcc_lo, v244, 60
	v_readlane_b32 vcc_hi, v244, 61
	s_nop 3
	v_subrev_u32_e32 v48, vcc_lo, v86
	v_and_b32_e32 v44, 0x7ff, v48
	v_lshrrev_b32_e32 v48, 11, v48
	v_lshlrev_b32_e32 v48, 6, v48
	v_lshrrev_b32_e32 v45, 6, v44
	v_lshl_or_b32 v48, v45, 20, v48
	v_and_or_b32 v48, v44, 63, v48
	v_mov_b32_e32 v49, 0
	v_lshl_add_u64 v[48:49], vcc, 0, v[48:49]
	global_store_dwordx2 v[48:49], v[46:47], off
	v_subrev_u32_e32 v48, vcc_lo, v86
	v_add_u32_e32 v48, 0x200, v48
	v_and_b32_e32 v44, 0x7ff, v48
	v_lshrrev_b32_e32 v48, 11, v48
	v_lshlrev_b32_e32 v48, 6, v48
	v_lshrrev_b32_e32 v45, 6, v44
	v_lshl_or_b32 v48, v45, 20, v48
	v_and_or_b32 v48, v44, 63, v48
	v_mov_b32_e32 v49, 0
	v_lshl_add_u64 v[48:49], vcc, 0, v[48:49]
	global_store_dwordx2 v[48:49], v[42:43], off
	v_subrev_u32_e32 v48, vcc_lo, v86
	v_add_u32_e32 v48, 0x400, v48
	v_and_b32_e32 v44, 0x7ff, v48
	v_lshrrev_b32_e32 v48, 11, v48
	v_lshlrev_b32_e32 v48, 6, v48
	v_lshrrev_b32_e32 v45, 6, v44
	v_lshl_or_b32 v48, v45, 20, v48
	v_and_or_b32 v48, v44, 63, v48
	v_mov_b32_e32 v49, 0
	v_lshl_add_u64 v[48:49], vcc, 0, v[48:49]
	global_store_dwordx2 v[48:49], v[38:39], off
	v_subrev_u32_e32 v48, vcc_lo, v86
	v_add_u32_e32 v48, 0x600, v48
	v_and_b32_e32 v44, 0x7ff, v48
	v_lshrrev_b32_e32 v48, 11, v48
	v_lshlrev_b32_e32 v48, 6, v48
	v_lshrrev_b32_e32 v45, 6, v44
	v_lshl_or_b32 v48, v45, 20, v48
	v_and_or_b32 v48, v44, 63, v48
	v_mov_b32_e32 v49, 0
	v_lshl_add_u64 v[48:49], vcc, 0, v[48:49]
	global_store_dwordx2 v[48:49], v[34:35], off
	s_or_b64 s[20:21], s[22:23], s[34:35]
	s_and_b64 vcc, exec, s[20:21]
	s_cbranch_vccnz .LBB0_317
.LBB0_323:
	s_waitcnt vmcnt(0)
	v_mov_b32_e32 v36, v27
	v_mov_b32_e32 v37, v31
	v_mov_b32_e32 v34, v26
	v_mov_b32_e32 v35, v30
	v_pk_mul_f32 v[36:37], v[36:37], v[36:37]
	v_mov_b32_e32 v38, v19
	v_pk_fma_f32 v[34:35], v[34:35], v[34:35], v[36:37]
	v_mov_b32_e32 v36, v28
	v_mov_b32_e32 v37, v32
	v_pk_fma_f32 v[34:35], v[36:37], v[36:37], v[34:35]
	v_mov_b32_e32 v36, v29
	v_mov_b32_e32 v37, v33
	v_mov_b32_e32 v39, v23
	v_pk_fma_f32 v[34:35], v[36:37], v[36:37], v[34:35]
	v_mov_b32_e32 v36, v18
	v_mov_b32_e32 v37, v22
	v_pk_mul_f32 v[38:39], v[38:39], v[38:39]
	v_add_f32_e32 v34, v34, v35
	v_pk_fma_f32 v[36:37], v[36:37], v[36:37], v[38:39]
	v_mov_b32_e32 v38, v20
	v_mov_b32_e32 v39, v24
	v_pk_fma_f32 v[36:37], v[38:39], v[38:39], v[36:37]
	v_mov_b32_e32 v38, v21
	v_mov_b32_e32 v39, v25
	v_pk_fma_f32 v[36:37], v[38:39], v[38:39], v[36:37]
	v_and_b32_e32 v35, 64, v159
	v_add_f32_e32 v34, v37, v34
	v_add_f32_e32 v34, v36, v34
	v_add_u32_e32 v35, 64, v35
	v_xor_b32_e32 v36, 32, v159
	v_cmp_lt_i32_e32 vcc, v36, v35
	s_nop 1
	v_cndmask_b32_e32 v36, v159, v36, vcc
	v_lshlrev_b32_e32 v36, 2, v36
	ds_bpermute_b32 v36, v36, v34
	s_waitcnt lgkmcnt(0)
	v_add_f32_e32 v34, v34, v36
	v_xor_b32_e32 v36, 16, v159
	v_cmp_lt_i32_e32 vcc, v36, v35
	s_nop 1
	v_cndmask_b32_e32 v36, v159, v36, vcc
	v_lshlrev_b32_e32 v36, 2, v36
	ds_bpermute_b32 v36, v36, v34
	s_waitcnt lgkmcnt(0)
	v_add_f32_e32 v34, v34, v36
	v_xor_b32_e32 v36, 8, v159
	v_cmp_lt_i32_e32 vcc, v36, v35
	s_nop 1
	v_cndmask_b32_e32 v36, v159, v36, vcc
	v_lshlrev_b32_e32 v36, 2, v36
	ds_bpermute_b32 v36, v36, v34
	s_waitcnt lgkmcnt(0)
	v_add_f32_e32 v34, v34, v36
	v_xor_b32_e32 v36, 4, v159
	v_cmp_lt_i32_e32 vcc, v36, v35
	s_nop 1
	v_cndmask_b32_e32 v36, v159, v36, vcc
	v_lshlrev_b32_e32 v36, 2, v36
	ds_bpermute_b32 v36, v36, v34
	s_waitcnt lgkmcnt(0)
	v_add_f32_e32 v34, v34, v36
	v_xor_b32_e32 v36, 2, v159
	v_cmp_lt_i32_e32 vcc, v36, v35
	s_nop 1
	v_cndmask_b32_e32 v36, v159, v36, vcc
	v_lshlrev_b32_e32 v36, 2, v36
	ds_bpermute_b32 v36, v36, v34
	s_waitcnt lgkmcnt(0)
	v_add_f32_e32 v34, v34, v36
	v_xor_b32_e32 v36, 1, v159
	v_cmp_lt_i32_e32 vcc, v36, v35
	s_nop 1
	v_cndmask_b32_e32 v35, v159, v36, vcc
	v_lshlrev_b32_e32 v35, 2, v35
	ds_bpermute_b32 v35, v35, v34
	v_lshl_add_u64 v[36:37], s[28:29], 0, v[82:83]
	s_waitcnt lgkmcnt(0)
	v_add_f32_e32 v34, v34, v35
	v_fmamk_f32 v34, v34, 0x3a800000, v155
	v_mul_f32_e32 v35, 0x4b800000, v34
	v_cmp_gt_f32_e32 vcc, s84, v34
	s_nop 1
	v_cndmask_b32_e32 v34, v34, v35, vcc
	v_rsq_f32_e32 v34, v34
	s_nop 0
	v_mul_f32_e32 v35, 0x45800000, v34
	v_cndmask_b32_e32 v34, v34, v35, vcc
	v_pk_mul_f32 v[38:39], v[32:33], v[34:35] op_sel_hi:[1,0]
	v_pk_mul_f32 v[40:41], v[30:31], v[34:35] op_sel_hi:[1,0]
	v_pk_mul_f32 v[38:39], v[4:5], v[38:39]
	v_pk_mul_f32 v[40:41], v[2:3], v[40:41]
	v_pk_fma_f32 v[38:39], v[52:53], v[38:39], v[56:57]
	v_pk_fma_f32 v[40:41], v[50:51], v[40:41], v[54:55]
	s_nop 0
	v_cvt_pk_bf16_f32 v40, v40, v41
	v_cvt_pk_bf16_f32 v41, v38, v39
	v_readlane_b32 vcc_lo, v244, 60
	v_readlane_b32 vcc_hi, v244, 61
	s_nop 3
	v_subrev_u32_e32 v30, vcc_lo, v36
	v_and_b32_e32 v32, 0x7ff, v30
	v_lshrrev_b32_e32 v30, 11, v30
	v_lshlrev_b32_e32 v30, 6, v30
	v_lshrrev_b32_e32 v33, 6, v32
	v_lshl_or_b32 v30, v33, 20, v30
	v_and_or_b32 v30, v32, 63, v30
	v_mov_b32_e32 v31, 0
	v_lshl_add_u64 v[30:31], vcc, 0, v[30:31]
	global_store_dwordx2 v[30:31], v[40:41], off
	v_pk_mul_f32 v[38:39], v[28:29], v[34:35] op_sel_hi:[1,0]
	v_pk_mul_f32 v[40:41], v[26:27], v[34:35] op_sel_hi:[1,0]
	v_pk_mul_f32 v[38:39], v[8:9], v[38:39]
	v_pk_mul_f32 v[40:41], v[6:7], v[40:41]
	v_pk_fma_f32 v[38:39], v[60:61], v[38:39], v[64:65]
	v_pk_fma_f32 v[40:41], v[58:59], v[40:41], v[62:63]
	s_nop 0
	v_cvt_pk_bf16_f32 v40, v40, v41
	v_cvt_pk_bf16_f32 v41, v38, v39
	v_subrev_u32_e32 v30, vcc_lo, v36
	v_add_u32_e32 v30, 0x200, v30
	v_and_b32_e32 v32, 0x7ff, v30
	v_lshrrev_b32_e32 v30, 11, v30
	v_lshlrev_b32_e32 v30, 6, v30
	v_lshrrev_b32_e32 v33, 6, v32
	v_lshl_or_b32 v30, v33, 20, v30
	v_and_or_b32 v30, v32, 63, v30
	v_mov_b32_e32 v31, 0
	v_lshl_add_u64 v[30:31], vcc, 0, v[30:31]
	global_store_dwordx2 v[30:31], v[40:41], off
	v_pk_mul_f32 v[38:39], v[24:25], v[34:35] op_sel_hi:[1,0]
	v_pk_mul_f32 v[40:41], v[22:23], v[34:35] op_sel_hi:[1,0]
	v_pk_mul_f32 v[38:39], v[12:13], v[38:39]
	v_pk_mul_f32 v[40:41], v[10:11], v[40:41]
	v_pk_fma_f32 v[38:39], v[68:69], v[38:39], v[72:73]
	v_pk_fma_f32 v[40:41], v[66:67], v[40:41], v[70:71]
	s_nop 0
	v_cvt_pk_bf16_f32 v40, v40, v41
	v_cvt_pk_bf16_f32 v41, v38, v39
	v_pk_mul_f32 v[38:39], v[20:21], v[34:35] op_sel_hi:[1,0]
	v_pk_mul_f32 v[34:35], v[18:19], v[34:35] op_sel_hi:[1,0]
	v_pk_mul_f32 v[38:39], v[16:17], v[38:39]
	v_pk_mul_f32 v[34:35], v[14:15], v[34:35]
	v_pk_fma_f32 v[38:39], v[76:77], v[38:39], v[80:81]
	v_pk_fma_f32 v[34:35], v[74:75], v[34:35], v[78:79]
	v_subrev_u32_e32 v30, vcc_lo, v36
	v_add_u32_e32 v30, 0x400, v30
	v_and_b32_e32 v32, 0x7ff, v30
	v_lshrrev_b32_e32 v30, 11, v30
	v_lshlrev_b32_e32 v30, 6, v30
	v_lshrrev_b32_e32 v33, 6, v32
	v_lshl_or_b32 v30, v33, 20, v30
	v_and_or_b32 v30, v32, 63, v30
	v_mov_b32_e32 v31, 0
	v_lshl_add_u64 v[30:31], vcc, 0, v[30:31]
	global_store_dwordx2 v[30:31], v[40:41], off
	v_cvt_pk_bf16_f32 v34, v34, v35
	v_cvt_pk_bf16_f32 v35, v38, v39
	v_subrev_u32_e32 v30, vcc_lo, v36
	v_add_u32_e32 v30, 0x600, v30
	v_and_b32_e32 v32, 0x7ff, v30
	v_lshrrev_b32_e32 v30, 11, v30
	v_lshlrev_b32_e32 v30, 6, v30
	v_lshrrev_b32_e32 v33, 6, v32
	v_lshl_or_b32 v30, v33, 20, v30
	v_and_or_b32 v30, v32, 63, v30
	v_mov_b32_e32 v31, 0
	v_lshl_add_u64 v[30:31], vcc, 0, v[30:31]
	global_store_dwordx2 v[30:31], v[34:35], off
	s_branch .LBB0_317

.LBB0_355:
	v_lshlrev_b32_e32 v0, 2, v31
	v_add3_u32 v19, s59, v0, v33
	v_add3_u32 v0, s59, v33, v0
	ds_read2_b32 v[24:25], v19 offset1:130
	ds_read2_b32 v[34:35], v0 offset0:65 offset1:195
	v_add_u32_e32 v36, 0x400, v0
	ds_read2_b32 v[36:37], v36 offset0:69 offset1:199
	v_add_u32_e32 v38, 0x800, v0
	ds_read2_b32 v[38:39], v38 offset0:73 offset1:203
	s_waitcnt lgkmcnt(2)
	v_cvt_pk_bf16_f32 v34, v24, v34
	v_add_u32_e32 v24, 0x400, v19
	v_cvt_pk_bf16_f32 v35, v25, v35
	ds_read2_b32 v[24:25], v24 offset0:4 offset1:134
	v_add_u32_e32 v0, 0xc00, v0
	ds_read2_b32 v[40:41], v0 offset0:77 offset1:207
	v_add_u32_e32 v0, s21, v31
	s_add_i32 s19, s43, s19
	s_waitcnt lgkmcnt(1)
	v_cvt_pk_bf16_f32 v36, v24, v36
	v_add_u32_e32 v24, 0x800, v19
	v_cvt_pk_bf16_f32 v37, v25, v37
	ds_read2_b32 v[24:25], v24 offset0:8 offset1:138
	v_add_u32_e32 v19, 0xc00, v19
	s_xor_b32 s55, s55, 1
	s_add_i32 s48, s48, s43
	s_add_i32 s49, s49, s50
	s_waitcnt lgkmcnt(0)
	v_cvt_pk_bf16_f32 v38, v24, v38
	v_cvt_pk_bf16_f32 v39, v25, v39
	ds_read2_b32 v[24:25], v19 offset0:12 offset1:142
	v_ashrrev_i32_e32 v19, 31, v0
	s_add_i32 s51, s51, s52
	s_add_i32 s53, s53, s54
	s_cmp_ge_i32 s19, s20
	s_waitcnt lgkmcnt(0)
	v_cvt_pk_bf16_f32 v40, v24, v40
	v_cvt_pk_bf16_f32 v41, v25, v41
	v_readlane_b32 s30, v244, 59
	s_nop 3
	v_cmp_eq_u32_e32 vcc, s30, v20
	s_nop 3
	s_cbranch_vccnz .Lcvt_dn_0
	v_readlane_b32 s30, v244, 58
	s_nop 3
	v_cmp_eq_u32_e32 vcc, s30, v20
	s_nop 3
	s_cbranch_vccnz .Lcvt_up_0
	v_readlane_b32 s30, v244, 62
	s_nop 3
	v_cmp_eq_u32_e32 vcc, s30, v20
	s_nop 3
	s_cbranch_vccnz .Lcvt_in_0
	v_mad_u64_u32 v[24:25], s[30:31], v0, s42, 0
	v_mov_b32_e32 v0, v25
	v_mad_u64_u32 v[42:43], s[30:31], v19, s42, v[0:1]
	v_mov_b32_e32 v25, v42
	v_lshl_add_u64 v[20:21], v[24:25], 1, v[20:21]
	v_lshl_add_u64 v[20:21], s[66:67], 1, v[20:21]
	v_mov_b32_e32 v19, v1
	v_lshl_add_u64 v[20:21], v[20:21], 0, v[18:19]
	s_branch .Lcvt_st_0

.Lcvt_up_0:
	v_lshrrev_b32_e64 v24, 5, s66
	v_lshrrev_b32_e32 v25, 6, v18
	v_add_u32_e32 v24, v24, v25
	v_mul_u32_u24_e32 v24, 0x58000, v24
	v_lshl_add_u32 v24, v0, 6, v24
	v_and_b32_e32 v25, 63, v18
	v_add_u32_e32 v24, v24, v25
	v_mov_b32_e32 v25, 0
	v_mov_b32_e32 v19, v1
	v_lshl_add_u64 v[20:21], v[24:25], 0, v[20:21]
	s_branch .Lcvt_st_0
.Lcvt_in_0:
	v_lshrrev_b32_e64 v24, 5, s66
	v_lshrrev_b32_e32 v25, 6, v18
	v_add_u32_e32 v24, v24, v25
	v_mul_u32_u24_e32 v24, 0x3c000, v24
	v_lshl_add_u32 v24, v0, 6, v24
	v_and_b32_e32 v25, 63, v18
	v_add_u32_e32 v24, v24, v25
	v_mov_b32_e32 v25, 0
	v_mov_b32_e32 v19, v1
	v_lshl_add_u64 v[20:21], v[24:25], 0, v[20:21]

.LBB0_413:
	v_lshlrev_b32_e32 v0, 2, v31
	v_add3_u32 v19, s61, v0, v33
	v_add3_u32 v0, s61, v33, v0
	ds_read2_b32 v[24:25], v19 offset1:130
	ds_read2_b32 v[34:35], v0 offset0:65 offset1:195
	v_add_u32_e32 v36, 0x400, v0
	ds_read2_b32 v[36:37], v36 offset0:69 offset1:199
	v_add_u32_e32 v38, 0x800, v0
	ds_read2_b32 v[38:39], v38 offset0:73 offset1:203
	s_waitcnt lgkmcnt(2)
	v_cvt_pk_bf16_f32 v34, v24, v34
	v_add_u32_e32 v24, 0x400, v19
	v_cvt_pk_bf16_f32 v35, v25, v35
	ds_read2_b32 v[24:25], v24 offset0:4 offset1:134
	v_add_u32_e32 v0, 0xc00, v0
	ds_read2_b32 v[40:41], v0 offset0:77 offset1:207
	v_add_u32_e32 v0, s3, v31
	s_xor_b32 s57, s57, 1
	s_waitcnt lgkmcnt(1)
	v_cvt_pk_bf16_f32 v36, v24, v36
	v_add_u32_e32 v24, 0x800, v19
	v_cvt_pk_bf16_f32 v37, v25, v37
	ds_read2_b32 v[24:25], v24 offset0:8 offset1:138
	v_add_u32_e32 v19, 0xc00, v19
	s_add_i32 s51, s51, s52
	s_add_i32 s53, s53, s54
	s_add_i32 s55, s55, s56
	s_waitcnt lgkmcnt(0)
	v_cvt_pk_bf16_f32 v38, v24, v38
	v_cvt_pk_bf16_f32 v39, v25, v39
	ds_read2_b32 v[24:25], v19 offset0:12 offset1:142
	v_ashrrev_i32_e32 v19, 31, v0
	s_and_b64 vcc, exec, s[34:35]
	s_mov_b32 s3, s58
	s_waitcnt lgkmcnt(0)
	v_cvt_pk_bf16_f32 v40, v24, v40
	v_cvt_pk_bf16_f32 v41, v25, v41
	v_readfirstlane_b32 s36, v20
	v_readlane_b32 s37, v244, 59
	s_nop 3
	s_cmp_eq_u32 s36, s37
	s_cbranch_scc1 .Lcvt_dn_1
	v_readlane_b32 s37, v244, 58
	s_nop 3
	s_cmp_eq_u32 s36, s37
	s_cbranch_scc1 .Lcvt_up_1
	v_readlane_b32 s37, v244, 62
	s_nop 3
	s_cmp_eq_u32 s36, s37
	s_cbranch_scc1 .Lcvt_in_1
	v_mad_u64_u32 v[24:25], s[36:37], v0, s7, 0
	v_mov_b32_e32 v0, v25
	v_mad_u64_u32 v[42:43], s[36:37], v19, s7, v[0:1]
	v_mov_b32_e32 v25, v42
	v_lshl_add_u64 v[20:21], v[24:25], 1, v[20:21]
	s_ashr_i32 s7, s6, 31
	v_lshl_add_u64 v[20:21], s[6:7], 1, v[20:21]
	v_mov_b32_e32 v19, v1
	v_lshl_add_u64 v[20:21], v[20:21], 0, v[18:19]
	s_branch .Lcvt_st_1

.Lcvt_up_1:
	v_lshrrev_b32_e64 v24, 5, s6
	v_lshrrev_b32_e32 v25, 6, v18
	v_add_u32_e32 v24, v24, v25
	v_mul_u32_u24_e32 v24, 0x58000, v24
	v_lshl_add_u32 v24, v0, 6, v24
	v_and_b32_e32 v25, 63, v18
	v_add_u32_e32 v24, v24, v25
	v_mov_b32_e32 v25, 0
	v_mov_b32_e32 v19, v1
	v_lshl_add_u64 v[20:21], v[24:25], 0, v[20:21]
	s_ashr_i32 s7, s6, 31
	s_branch .Lcvt_st_1
.Lcvt_in_1:
	v_lshrrev_b32_e64 v24, 5, s6
	v_lshrrev_b32_e32 v25, 6, v18
	v_add_u32_e32 v24, v24, v25
	v_mul_u32_u24_e32 v24, 0x3c000, v24
	v_lshl_add_u32 v24, v0, 6, v24
	v_and_b32_e32 v25, 63, v18
	v_add_u32_e32 v24, v24, v25
	v_mov_b32_e32 v25, 0
	v_mov_b32_e32 v19, v1
	v_lshl_add_u64 v[20:21], v[24:25], 0, v[20:21]
	s_ashr_i32 s7, s6, 31

.LBB0_498:
	v_lshlrev_b32_e32 v0, 2, v31
	v_add3_u32 v19, s29, v0, v33
	v_add3_u32 v0, s29, v33, v0
	ds_read2_b32 v[24:25], v19 offset1:130
	ds_read2_b32 v[34:35], v0 offset0:65 offset1:195
	v_add_u32_e32 v36, 0x400, v0
	ds_read2_b32 v[36:37], v36 offset0:69 offset1:199
	v_add_u32_e32 v38, 0x800, v0
	ds_read2_b32 v[38:39], v38 offset0:73 offset1:203
	s_waitcnt lgkmcnt(2)
	v_cvt_pk_bf16_f32 v34, v24, v34
	v_add_u32_e32 v24, 0x400, v19
	v_cvt_pk_bf16_f32 v35, v25, v35
	ds_read2_b32 v[24:25], v24 offset0:4 offset1:134
	v_add_u32_e32 v0, 0xc00, v0
	ds_read2_b32 v[40:41], v0 offset0:77 offset1:207
	v_add_u32_e32 v0, s21, v31
	s_ashr_i32 s21, s20, 31
	s_waitcnt lgkmcnt(1)
	v_cvt_pk_bf16_f32 v36, v24, v36
	v_add_u32_e32 v24, 0x800, v19
	v_cvt_pk_bf16_f32 v37, v25, v37
	ds_read2_b32 v[24:25], v24 offset0:8 offset1:138
	v_add_u32_e32 v19, 0xc00, v19
	s_add_i32 s93, s93, s71
	s_xor_b32 s92, s92, 1
	s_add_i32 s73, s73, s71
	s_waitcnt lgkmcnt(0)
	v_cvt_pk_bf16_f32 v38, v24, v38
	v_cvt_pk_bf16_f32 v39, v25, v39
	ds_read2_b32 v[24:25], v19 offset0:12 offset1:142
	v_ashrrev_i32_e32 v19, 31, v0
	s_add_i32 s81, s81, s82
	s_add_i32 s83, s83, s89
	s_add_i32 s90, s90, s18
	s_waitcnt lgkmcnt(0)
	v_cvt_pk_bf16_f32 v40, v24, v40
	v_cvt_pk_bf16_f32 v41, v25, v41
	v_readfirstlane_b32 s26, v20
	v_readlane_b32 s27, v244, 59
	s_nop 3
	s_cmp_eq_u32 s26, s27
	s_cbranch_scc1 .Lcvt_dn_2
	v_readlane_b32 s27, v244, 58
	s_nop 3
	s_cmp_eq_u32 s26, s27
	s_cbranch_scc1 .Lcvt_up_2
	v_readlane_b32 s27, v244, 62
	s_nop 3
	s_cmp_eq_u32 s26, s27
	s_cbranch_scc1 .Lcvt_in_2
	v_mad_u64_u32 v[24:25], s[26:27], v0, s72, 0
	v_mov_b32_e32 v0, v25
	v_mad_u64_u32 v[42:43], s[26:27], v19, s72, v[0:1]
	v_mov_b32_e32 v25, v42
	v_lshl_add_u64 v[20:21], v[24:25], 1, v[20:21]
	v_lshl_add_u64 v[20:21], s[20:21], 1, v[20:21]
	v_mov_b32_e32 v19, v1
	v_lshl_add_u64 v[20:21], v[20:21], 0, v[18:19]
	s_branch .Lcvt_st_2

.Lcvt_up_2:
	v_lshrrev_b32_e64 v24, 5, s20
	v_lshrrev_b32_e32 v25, 6, v18
	v_add_u32_e32 v24, v24, v25
	v_mul_u32_u24_e32 v24, 0x58000, v24
	v_lshl_add_u32 v24, v0, 6, v24
	v_and_b32_e32 v25, 63, v18
	v_add_u32_e32 v24, v24, v25
	v_mov_b32_e32 v25, 0
	v_mov_b32_e32 v19, v1
	v_lshl_add_u64 v[20:21], v[24:25], 0, v[20:21]
	s_branch .Lcvt_st_2
.Lcvt_in_2:
	v_lshrrev_b32_e64 v24, 5, s20
	v_lshrrev_b32_e32 v25, 6, v18
	v_add_u32_e32 v24, v24, v25
	v_mul_u32_u24_e32 v24, 0x3c000, v24
	v_lshl_add_u32 v24, v0, 6, v24
	v_and_b32_e32 v25, 63, v18
	v_add_u32_e32 v24, v24, v25
	v_mov_b32_e32 v25, 0
	v_mov_b32_e32 v19, v1
	v_lshl_add_u64 v[20:21], v[24:25], 0, v[20:21]

.Lpj_entry:
	s_waitcnt lgkmcnt(0)
	s_load_dwordx2 s[48:49], s[0:1], 0xc0
	s_load_dwordx2 s[50:51], s[0:1], 0x98
	s_mov_b32 s59, 32
	s_mov_b32 s72, 0x100000
	s_mov_b32 s73, 0x3c000
	s_movk_i32 s32, 0x780
	s_getpc_b64 s[82:83]
	s_add_u32 s82, s82, ROPE_HI@rel32@lo+4
	s_addc_u32 s83, s83, ROPE_HI@rel32@hi+12
	s_getpc_b64 s[92:93]
	s_add_u32 s92, s92, ROPE_LO@rel32@lo+4
	s_addc_u32 s93, s93, ROPE_LO@rel32@hi+12
	v_and_b32_e32 v0, 63, v154
	v_lshrrev_b32_e32 v131, 6, v154
	v_lshrrev_b32_e32 v243, 2, v0
	v_readfirstlane_b32 s41, v131
	v_and_b32_e32 v130, 3, v0
	v_mov_b32_e32 v134, 0x1320
	s_nop 1
	s_lshr_b32 s42, s41, 1
	s_and_b32 s43, s41, 1
	v_bfe_u32 v132, v0, 4, 2
	v_lshlrev_b32_e32 v132, 2, v132
	v_lshrrev_b32_e32 v132, v132, v134
	v_and_b32_e32 v132, 3, v132
	v_xor_b32_e32 v132, v132, v130
	v_lshlrev_b32_e32 v245, 4, v132
	v_bfe_u32 v132, v0, 2, 2
	v_lshlrev_b32_e32 v132, 2, v132
	v_lshrrev_b32_e32 v132, v132, v134
	v_and_b32_e32 v132, 3, v132
	v_lshrrev_b32_e32 v133, 4, v0
	v_xor_b32_e32 v132, v132, v133
	v_lshlrev_b32_e32 v132, 4, v132
	v_and_b32_e32 v131, 15, v0
	s_lshl_b32 s26, s42, 13
	v_lshl_add_u32 v238, v131, 6, v132
	v_add_u32_e32 v238, s26, v238
	s_lshl_b32 s62, s41, 12
	s_lshl_b32 s63, s41, 11
	s_add_i32 s63, s63, 0x4000
	s_lshl_b32 s26, s43, 12
	s_add_i32 s26, s26, 0x4000
	v_lshrrev_b32_e32 v134, 2, v131
	v_lshl_add_u32 v239, v134, 9, v132
	v_and_b32_e32 v134, 3, v131
	v_lshl_add_u32 v239, v134, 6, v239
	v_add_u32_e32 v239, s26, v239
	v_mov_b32_e32 v134, 0x1320
	v_lshrrev_b32_e32 v246, 3, v243
	v_and_b32_e32 v246, 3, v246
	v_lshlrev_b32_e32 v246, 2, v246
	v_lshrrev_b32_e32 v246, v246, v134
	v_and_b32_e32 v246, 3, v246
	v_xor_b32_e32 v246, v246, v130
	v_lshlrev_b32_e32 v246, 4, v246
	v_lshrrev_b32_e32 v247, 3, v243
	v_add_u32_e32 v247, 2, v247
	v_and_b32_e32 v247, 3, v247
	v_lshlrev_b32_e32 v247, 2, v247
	v_lshrrev_b32_e32 v247, v247, v134
	v_and_b32_e32 v247, 3, v247
	v_xor_b32_e32 v247, v247, v130
	v_lshlrev_b32_e32 v247, 4, v247
	s_lshl_b32 s26, s42, 7
	v_add_u32_e32 v227, s26, v131
	v_lshlrev_b32_e32 v228, 4, v133
	s_mov_b32 s34, s3
	s_cmp_lt_i32 s34, s32
	s_cbranch_scc0 .Lpj_done
	s_and_b32 s26, s34, 7
	s_lshr_b32 s27, s34, 3
	s_lshr_b32 s36, s27, 3
	s_and_b32 s27, s27, 7
	s_lshl_b32 s27, s27, 3
	s_add_i32 s35, s27, s26
	s_lshl_b32 s35, s35, 8
	s_lshl_b32 s36, s36, 7
	s_lshl_b32 s26, s41, 6
	s_add_i32 s26, s26, s35
	v_add_u32_e32 v0, s26, v243
	v_lshl_add_u32 v226, v0, 6, v245
	s_lshl_b32 s26, s41, 5
	s_add_i32 s26, s26, s36
	v_add_u32_e32 v0, s26, v243
	v_lshl_add_u32 v230, v0, 6, v246
	v_lshl_add_u32 v231, v0, 6, v247
	s_mov_b32 s60, 0
	s_mov_b32 s61, 0
	s_waitcnt lgkmcnt(0)
	s_mov_b64 s[54:55], s[48:49]
	s_mov_b64 s[56:57], s[50:51]
	s_add_i32 m0, s60, s62
	s_nop 0
	global_load_lds_dwordx4 v226, s[54:55]
	global_load_lds_dwordx4 v226, s[54:55] offset:1024
	global_load_lds_dwordx4 v226, s[54:55] offset:2048
	global_load_lds_dwordx4 v226, s[54:55] offset:3072
	s_add_i32 m0, s60, s63
	s_nop 0
	global_load_lds_dwordx4 v230, s[56:57]
	global_load_lds_dwordx4 v231, s[56:57] offset:1024
	s_add_i32 s60, s60, 0x6000
	s_cmp_eq_u32 s60, 0x12000
	s_cselect_b32 s60, 0, s60
	s_add_u32 s54, s54, s72
	s_addc_u32 s55, s55, 0
	s_add_u32 s56, s56, s73
	s_addc_u32 s57, s57, 0
	s_add_i32 m0, s60, s62
	s_nop 0
	global_load_lds_dwordx4 v226, s[54:55]
	global_load_lds_dwordx4 v226, s[54:55] offset:1024
	global_load_lds_dwordx4 v226, s[54:55] offset:2048
	global_load_lds_dwordx4 v226, s[54:55] offset:3072
	s_add_i32 m0, s60, s63
	s_nop 0
	global_load_lds_dwordx4 v230, s[56:57]
	global_load_lds_dwordx4 v231, s[56:57] offset:1024
	s_add_i32 s60, s60, 0x6000
	s_cmp_eq_u32 s60, 0x12000
	s_cselect_b32 s60, 0, s60
	s_add_u32 s54, s54, s72
	s_addc_u32 s55, s55, 0
	s_add_u32 s56, s56, s73
	s_addc_u32 s57, s57, 0
	s_add_i32 m0, s60, s62
	s_nop 0
	global_load_lds_dwordx4 v226, s[54:55]
	global_load_lds_dwordx4 v226, s[54:55] offset:1024
	global_load_lds_dwordx4 v226, s[54:55] offset:2048
	global_load_lds_dwordx4 v226, s[54:55] offset:3072
	s_add_i32 m0, s60, s63
	s_nop 0
	global_load_lds_dwordx4 v230, s[56:57]
	global_load_lds_dwordx4 v231, s[56:57] offset:1024
	s_add_i32 s60, s60, 0x6000
	s_cmp_eq_u32 s60, 0x12000
	s_cselect_b32 s60, 0, s60
	s_add_u32 s54, s54, s72
	s_addc_u32 s55, s55, 0
	s_add_u32 s56, s56, s73
	s_addc_u32 s57, s57, 0
	s_waitcnt vmcnt(12)
	s_barrier
	v_add_u32_e32 v240, s61, v238
	v_add_u32_e32 v241, s61, v239
	ds_read_b128 v[162:165], v241 offset:0
	ds_read_b128 v[166:169], v241 offset:256
	ds_read_b128 v[170:173], v241 offset:2048
	ds_read_b128 v[174:177], v241 offset:2304
	ds_read_b128 v[130:133], v240 offset:0
	ds_read_b128 v[134:137], v240 offset:1024
	ds_read_b128 v[138:141], v240 offset:2048
	ds_read_b128 v[142:145], v240 offset:3072
	ds_read_b128 v[146:149], v240 offset:4096
	ds_read_b128 v[150:153], v240 offset:5120
	ds_read_b128 v[154:157], v240 offset:6144
	ds_read_b128 v[158:161], v240 offset:7168
	s_add_i32 s61, s61, 0x6000
	s_cmp_eq_u32 s61, 0x12000
	s_cselect_b32 s61, 0, s61
	s_add_i32 s38, s34, s71
	s_cmp_lt_i32 s38, s32
	s_cselect_b32 s37, 1, 0
	s_cbranch_scc0 .Lpj_nn_a
	s_and_b32 s26, s38, 7
	s_lshr_b32 s27, s38, 3
	s_lshr_b32 s31, s27, 3
	s_and_b32 s27, s27, 7
	s_lshl_b32 s27, s27, 3
	s_add_i32 s30, s27, s26
	s_lshl_b32 s30, s30, 8
	s_lshl_b32 s31, s31, 7
	s_lshl_b32 s26, s41, 6
	s_add_i32 s26, s26, s30
	v_add_u32_e32 v0, s26, v243
	v_lshl_add_u32 v232, v0, 6, v245
	s_lshl_b32 s26, s41, 5
	s_add_i32 s26, s26, s31
	v_add_u32_e32 v0, s26, v243
	v_lshl_add_u32 v236, v0, 6, v246
	v_lshl_add_u32 v237, v0, 6, v247
.Lpj_nn_a:
	v_mov_b32_e32 v2, 0
	v_mov_b32_e32 v3, 0
	v_mov_b32_e32 v4, 0
	v_mov_b32_e32 v5, 0
	v_mov_b32_e32 v6, 0
	v_mov_b32_e32 v7, 0
	v_mov_b32_e32 v8, 0
	v_mov_b32_e32 v9, 0
	v_mov_b32_e32 v10, 0
	v_mov_b32_e32 v11, 0
	v_mov_b32_e32 v12, 0
	v_mov_b32_e32 v13, 0
	v_mov_b32_e32 v14, 0
	v_mov_b32_e32 v15, 0
	v_mov_b32_e32 v16, 0
	v_mov_b32_e32 v17, 0
	v_mov_b32_e32 v18, 0
	v_mov_b32_e32 v19, 0
	v_mov_b32_e32 v20, 0
	v_mov_b32_e32 v21, 0
	v_mov_b32_e32 v22, 0
	v_mov_b32_e32 v23, 0
	v_mov_b32_e32 v24, 0
	v_mov_b32_e32 v25, 0
	v_mov_b32_e32 v26, 0
	v_mov_b32_e32 v27, 0
	v_mov_b32_e32 v28, 0
	v_mov_b32_e32 v29, 0
	v_mov_b32_e32 v30, 0
	v_mov_b32_e32 v31, 0
	v_mov_b32_e32 v32, 0
	v_mov_b32_e32 v33, 0
	v_mov_b32_e32 v34, 0
	v_mov_b32_e32 v35, 0
	v_mov_b32_e32 v36, 0
	v_mov_b32_e32 v37, 0
	v_mov_b32_e32 v38, 0
	v_mov_b32_e32 v39, 0
	v_mov_b32_e32 v40, 0
	v_mov_b32_e32 v41, 0
	v_mov_b32_e32 v42, 0
	v_mov_b32_e32 v43, 0
	v_mov_b32_e32 v44, 0
	v_mov_b32_e32 v45, 0
	v_mov_b32_e32 v46, 0
	v_mov_b32_e32 v47, 0
	v_mov_b32_e32 v48, 0
	v_mov_b32_e32 v49, 0
	v_mov_b32_e32 v50, 0
	v_mov_b32_e32 v51, 0
	v_mov_b32_e32 v52, 0
	v_mov_b32_e32 v53, 0
	v_mov_b32_e32 v54, 0
	v_mov_b32_e32 v55, 0
	v_mov_b32_e32 v56, 0
	v_mov_b32_e32 v57, 0
	v_mov_b32_e32 v58, 0
	v_mov_b32_e32 v59, 0
	v_mov_b32_e32 v60, 0
	v_mov_b32_e32 v61, 0
	v_mov_b32_e32 v62, 0
	v_mov_b32_e32 v63, 0
	v_mov_b32_e32 v64, 0
	v_mov_b32_e32 v65, 0
	v_mov_b32_e32 v66, 0
	v_mov_b32_e32 v67, 0
	v_mov_b32_e32 v68, 0
	v_mov_b32_e32 v69, 0
	v_mov_b32_e32 v70, 0
	v_mov_b32_e32 v71, 0
	v_mov_b32_e32 v72, 0
	v_mov_b32_e32 v73, 0
	v_mov_b32_e32 v74, 0
	v_mov_b32_e32 v75, 0
	v_mov_b32_e32 v76, 0
	v_mov_b32_e32 v77, 0
	v_mov_b32_e32 v78, 0
	v_mov_b32_e32 v79, 0
	v_mov_b32_e32 v80, 0
	v_mov_b32_e32 v81, 0
	v_mov_b32_e32 v82, 0
	v_mov_b32_e32 v83, 0
	v_mov_b32_e32 v84, 0
	v_mov_b32_e32 v85, 0
	v_mov_b32_e32 v86, 0
	v_mov_b32_e32 v87, 0
	v_mov_b32_e32 v88, 0
	v_mov_b32_e32 v89, 0
	v_mov_b32_e32 v90, 0
	v_mov_b32_e32 v91, 0
	v_mov_b32_e32 v92, 0
	v_mov_b32_e32 v93, 0
	v_mov_b32_e32 v94, 0
	v_mov_b32_e32 v95, 0
	v_mov_b32_e32 v96, 0
	v_mov_b32_e32 v97, 0
	v_mov_b32_e32 v98, 0
	v_mov_b32_e32 v99, 0
	v_mov_b32_e32 v100, 0
	v_mov_b32_e32 v101, 0
	v_mov_b32_e32 v102, 0
	v_mov_b32_e32 v103, 0
	v_mov_b32_e32 v104, 0
	v_mov_b32_e32 v105, 0
	v_mov_b32_e32 v106, 0
	v_mov_b32_e32 v107, 0
	v_mov_b32_e32 v108, 0
	v_mov_b32_e32 v109, 0
	v_mov_b32_e32 v110, 0
	v_mov_b32_e32 v111, 0
	v_mov_b32_e32 v112, 0
	v_mov_b32_e32 v113, 0
	v_mov_b32_e32 v114, 0
	v_mov_b32_e32 v115, 0
	v_mov_b32_e32 v116, 0
	v_mov_b32_e32 v117, 0
	v_mov_b32_e32 v118, 0
	v_mov_b32_e32 v119, 0
	v_mov_b32_e32 v120, 0
	v_mov_b32_e32 v121, 0
	v_mov_b32_e32 v122, 0
	v_mov_b32_e32 v123, 0
	v_mov_b32_e32 v124, 0
	v_mov_b32_e32 v125, 0
	v_mov_b32_e32 v126, 0
	v_mov_b32_e32 v127, 0
	v_mov_b32_e32 v128, 0
	v_mov_b32_e32 v129, 0
	s_waitcnt vmcnt(6) lgkmcnt(0)
	s_barrier
	v_add_u32_e32 v240, s61, v238
	v_add_u32_e32 v241, s61, v239
	s_add_i32 m0, s60, s62
	v_mfma_f32_16x16x32_bf16 v[2:5], v[162:165], v[130:133], v[2:5]
	global_load_lds_dwordx4 v226, s[54:55]
	v_mfma_f32_16x16x32_bf16 v[6:9], v[166:169], v[130:133], v[6:9]
	global_load_lds_dwordx4 v226, s[54:55] offset:1024
	v_mfma_f32_16x16x32_bf16 v[10:13], v[170:173], v[130:133], v[10:13]
	global_load_lds_dwordx4 v226, s[54:55] offset:2048
	v_mfma_f32_16x16x32_bf16 v[14:17], v[174:177], v[130:133], v[14:17]
	global_load_lds_dwordx4 v226, s[54:55] offset:3072
	s_add_i32 m0, s60, s63
	v_mfma_f32_16x16x32_bf16 v[18:21], v[162:165], v[134:137], v[18:21]
	global_load_lds_dwordx4 v230, s[56:57]
	v_mfma_f32_16x16x32_bf16 v[22:25], v[166:169], v[134:137], v[22:25]
	global_load_lds_dwordx4 v231, s[56:57] offset:1024
	v_mfma_f32_16x16x32_bf16 v[26:29], v[170:173], v[134:137], v[26:29]
	v_mfma_f32_16x16x32_bf16 v[30:33], v[174:177], v[134:137], v[30:33]
	v_mfma_f32_16x16x32_bf16 v[34:37], v[162:165], v[138:141], v[34:37]
	ds_read_b128 v[210:213], v241 offset:0
	v_mfma_f32_16x16x32_bf16 v[38:41], v[166:169], v[138:141], v[38:41]
	ds_read_b128 v[214:217], v241 offset:256
	v_mfma_f32_16x16x32_bf16 v[42:45], v[170:173], v[138:141], v[42:45]
	ds_read_b128 v[218:221], v241 offset:2048
	v_mfma_f32_16x16x32_bf16 v[46:49], v[174:177], v[138:141], v[46:49]
	ds_read_b128 v[222:225], v241 offset:2304
	v_mfma_f32_16x16x32_bf16 v[50:53], v[162:165], v[142:145], v[50:53]
	ds_read_b128 v[178:181], v240 offset:0
	v_mfma_f32_16x16x32_bf16 v[54:57], v[166:169], v[142:145], v[54:57]
	ds_read_b128 v[182:185], v240 offset:1024
	v_mfma_f32_16x16x32_bf16 v[58:61], v[170:173], v[142:145], v[58:61]
	ds_read_b128 v[186:189], v240 offset:2048
	v_mfma_f32_16x16x32_bf16 v[62:65], v[174:177], v[142:145], v[62:65]
	ds_read_b128 v[190:193], v240 offset:3072
	v_mfma_f32_16x16x32_bf16 v[66:69], v[162:165], v[146:149], v[66:69]
	ds_read_b128 v[194:197], v240 offset:4096
	v_mfma_f32_16x16x32_bf16 v[70:73], v[166:169], v[146:149], v[70:73]
	ds_read_b128 v[198:201], v240 offset:5120
	v_mfma_f32_16x16x32_bf16 v[74:77], v[170:173], v[146:149], v[74:77]
	ds_read_b128 v[202:205], v240 offset:6144
	v_mfma_f32_16x16x32_bf16 v[78:81], v[174:177], v[146:149], v[78:81]
	ds_read_b128 v[206:209], v240 offset:7168
	v_mfma_f32_16x16x32_bf16 v[82:85], v[162:165], v[150:153], v[82:85]
	v_mfma_f32_16x16x32_bf16 v[86:89], v[166:169], v[150:153], v[86:89]
	v_mfma_f32_16x16x32_bf16 v[90:93], v[170:173], v[150:153], v[90:93]
	v_mfma_f32_16x16x32_bf16 v[94:97], v[174:177], v[150:153], v[94:97]
	v_mfma_f32_16x16x32_bf16 v[98:101], v[162:165], v[154:157], v[98:101]
	v_mfma_f32_16x16x32_bf16 v[102:105], v[166:169], v[154:157], v[102:105]
	v_mfma_f32_16x16x32_bf16 v[106:109], v[170:173], v[154:157], v[106:109]
	v_mfma_f32_16x16x32_bf16 v[110:113], v[174:177], v[154:157], v[110:113]
	v_mfma_f32_16x16x32_bf16 v[114:117], v[162:165], v[158:161], v[114:117]
	v_mfma_f32_16x16x32_bf16 v[118:121], v[166:169], v[158:161], v[118:121]
	v_mfma_f32_16x16x32_bf16 v[122:125], v[170:173], v[158:161], v[122:125]
	v_mfma_f32_16x16x32_bf16 v[126:129], v[174:177], v[158:161], v[126:129]
	s_add_i32 s60, s60, 0x6000
	s_cmp_eq_u32 s60, 0x12000
	s_cselect_b32 s60, 0, s60
	s_add_u32 s54, s54, s72
	s_addc_u32 s55, s55, 0
	s_add_u32 s56, s56, s73
	s_addc_u32 s57, s57, 0
	s_add_i32 s61, s61, 0x6000
	s_cmp_eq_u32 s61, 0x12000
	s_cselect_b32 s61, 0, s61
	s_waitcnt vmcnt(6) lgkmcnt(0)
	s_barrier
	v_add_u32_e32 v240, s61, v238
	v_add_u32_e32 v241, s61, v239
	s_add_i32 m0, s60, s62
	v_mfma_f32_16x16x32_bf16 v[2:5], v[210:213], v[178:181], v[2:5]
	global_load_lds_dwordx4 v226, s[54:55]
	v_mfma_f32_16x16x32_bf16 v[6:9], v[214:217], v[178:181], v[6:9]
	global_load_lds_dwordx4 v226, s[54:55] offset:1024
	v_mfma_f32_16x16x32_bf16 v[10:13], v[218:221], v[178:181], v[10:13]
	global_load_lds_dwordx4 v226, s[54:55] offset:2048
	v_mfma_f32_16x16x32_bf16 v[14:17], v[222:225], v[178:181], v[14:17]
	global_load_lds_dwordx4 v226, s[54:55] offset:3072
	s_add_i32 m0, s60, s63
	v_mfma_f32_16x16x32_bf16 v[18:21], v[210:213], v[182:185], v[18:21]
	global_load_lds_dwordx4 v230, s[56:57]
	v_mfma_f32_16x16x32_bf16 v[22:25], v[214:217], v[182:185], v[22:25]
	global_load_lds_dwordx4 v231, s[56:57] offset:1024
	v_mfma_f32_16x16x32_bf16 v[26:29], v[218:221], v[182:185], v[26:29]
	v_mfma_f32_16x16x32_bf16 v[30:33], v[222:225], v[182:185], v[30:33]
	v_mfma_f32_16x16x32_bf16 v[34:37], v[210:213], v[186:189], v[34:37]
	ds_read_b128 v[162:165], v241 offset:0
	v_mfma_f32_16x16x32_bf16 v[38:41], v[214:217], v[186:189], v[38:41]
	ds_read_b128 v[166:169], v241 offset:256
	v_mfma_f32_16x16x32_bf16 v[42:45], v[218:221], v[186:189], v[42:45]
	ds_read_b128 v[170:173], v241 offset:2048
	v_mfma_f32_16x16x32_bf16 v[46:49], v[222:225], v[186:189], v[46:49]
	ds_read_b128 v[174:177], v241 offset:2304
	v_mfma_f32_16x16x32_bf16 v[50:53], v[210:213], v[190:193], v[50:53]
	ds_read_b128 v[130:133], v240 offset:0
	v_mfma_f32_16x16x32_bf16 v[54:57], v[214:217], v[190:193], v[54:57]
	ds_read_b128 v[134:137], v240 offset:1024
	v_mfma_f32_16x16x32_bf16 v[58:61], v[218:221], v[190:193], v[58:61]
	ds_read_b128 v[138:141], v240 offset:2048
	v_mfma_f32_16x16x32_bf16 v[62:65], v[222:225], v[190:193], v[62:65]
	ds_read_b128 v[142:145], v240 offset:3072
	v_mfma_f32_16x16x32_bf16 v[66:69], v[210:213], v[194:197], v[66:69]
	ds_read_b128 v[146:149], v240 offset:4096
	v_mfma_f32_16x16x32_bf16 v[70:73], v[214:217], v[194:197], v[70:73]
	ds_read_b128 v[150:153], v240 offset:5120
	v_mfma_f32_16x16x32_bf16 v[74:77], v[218:221], v[194:197], v[74:77]
	ds_read_b128 v[154:157], v240 offset:6144
	v_mfma_f32_16x16x32_bf16 v[78:81], v[222:225], v[194:197], v[78:81]
	ds_read_b128 v[158:161], v240 offset:7168
	v_mfma_f32_16x16x32_bf16 v[82:85], v[210:213], v[198:201], v[82:85]
	v_mfma_f32_16x16x32_bf16 v[86:89], v[214:217], v[198:201], v[86:89]
	v_mfma_f32_16x16x32_bf16 v[90:93], v[218:221], v[198:201], v[90:93]
	v_mfma_f32_16x16x32_bf16 v[94:97], v[222:225], v[198:201], v[94:97]
	v_mfma_f32_16x16x32_bf16 v[98:101], v[210:213], v[202:205], v[98:101]
	v_mfma_f32_16x16x32_bf16 v[102:105], v[214:217], v[202:205], v[102:105]
	v_mfma_f32_16x16x32_bf16 v[106:109], v[218:221], v[202:205], v[106:109]
	v_mfma_f32_16x16x32_bf16 v[110:113], v[222:225], v[202:205], v[110:113]
	v_mfma_f32_16x16x32_bf16 v[114:117], v[210:213], v[206:209], v[114:117]
	v_mfma_f32_16x16x32_bf16 v[118:121], v[214:217], v[206:209], v[118:121]
	v_mfma_f32_16x16x32_bf16 v[122:125], v[218:221], v[206:209], v[122:125]
	v_mfma_f32_16x16x32_bf16 v[126:129], v[222:225], v[206:209], v[126:129]
	s_add_i32 s60, s60, 0x6000
	s_cmp_eq_u32 s60, 0x12000
	s_cselect_b32 s60, 0, s60
	s_add_u32 s54, s54, s72
	s_addc_u32 s55, s55, 0
	s_add_u32 s56, s56, s73
	s_addc_u32 s57, s57, 0
	s_add_i32 s61, s61, 0x6000
	s_cmp_eq_u32 s61, 0x12000
	s_cselect_b32 s61, 0, s61
	s_branch .Lpj_main
.Lpj_tile:
	s_add_i32 s38, s34, s71
	s_cmp_lt_i32 s38, s32
	s_cselect_b32 s37, 1, 0
	s_cbranch_scc0 .Lpj_nn_b
	s_and_b32 s26, s38, 7
	s_lshr_b32 s27, s38, 3
	s_lshr_b32 s31, s27, 3
	s_and_b32 s27, s27, 7
	s_lshl_b32 s27, s27, 3
	s_add_i32 s30, s27, s26
	s_lshl_b32 s30, s30, 8
	s_lshl_b32 s31, s31, 7
	s_lshl_b32 s26, s41, 6
	s_add_i32 s26, s26, s30
	v_add_u32_e32 v0, s26, v243
	v_lshl_add_u32 v232, v0, 6, v245
	s_lshl_b32 s26, s41, 5
	s_add_i32 s26, s26, s31
	v_add_u32_e32 v0, s26, v243
	v_lshl_add_u32 v236, v0, 6, v246
	v_lshl_add_u32 v237, v0, 6, v247
.Lpj_nn_b:
	v_mov_b32_e32 v2, 0
	v_mov_b32_e32 v3, 0
	v_mov_b32_e32 v4, 0
	v_mov_b32_e32 v5, 0
	v_mov_b32_e32 v6, 0
	v_mov_b32_e32 v7, 0
	v_mov_b32_e32 v8, 0
	v_mov_b32_e32 v9, 0
	v_mov_b32_e32 v10, 0
	v_mov_b32_e32 v11, 0
	v_mov_b32_e32 v12, 0
	v_mov_b32_e32 v13, 0
	v_mov_b32_e32 v14, 0
	v_mov_b32_e32 v15, 0
	v_mov_b32_e32 v16, 0
	v_mov_b32_e32 v17, 0
	v_mov_b32_e32 v18, 0
	v_mov_b32_e32 v19, 0
	v_mov_b32_e32 v20, 0
	v_mov_b32_e32 v21, 0
	v_mov_b32_e32 v22, 0
	v_mov_b32_e32 v23, 0
	v_mov_b32_e32 v24, 0
	v_mov_b32_e32 v25, 0
	v_mov_b32_e32 v26, 0
	v_mov_b32_e32 v27, 0
	v_mov_b32_e32 v28, 0
	v_mov_b32_e32 v29, 0
	v_mov_b32_e32 v30, 0
	v_mov_b32_e32 v31, 0
	v_mov_b32_e32 v32, 0
	v_mov_b32_e32 v33, 0
	v_mov_b32_e32 v34, 0
	v_mov_b32_e32 v35, 0
	v_mov_b32_e32 v36, 0
	v_mov_b32_e32 v37, 0
	v_mov_b32_e32 v38, 0
	v_mov_b32_e32 v39, 0
	v_mov_b32_e32 v40, 0
	v_mov_b32_e32 v41, 0
	v_mov_b32_e32 v42, 0
	v_mov_b32_e32 v43, 0
	v_mov_b32_e32 v44, 0
	v_mov_b32_e32 v45, 0
	v_mov_b32_e32 v46, 0
	v_mov_b32_e32 v47, 0
	v_mov_b32_e32 v48, 0
	v_mov_b32_e32 v49, 0
	v_mov_b32_e32 v50, 0
	v_mov_b32_e32 v51, 0
	v_mov_b32_e32 v52, 0
	v_mov_b32_e32 v53, 0
	v_mov_b32_e32 v54, 0
	v_mov_b32_e32 v55, 0
	v_mov_b32_e32 v56, 0
	v_mov_b32_e32 v57, 0
	v_mov_b32_e32 v58, 0
	v_mov_b32_e32 v59, 0
	v_mov_b32_e32 v60, 0
	v_mov_b32_e32 v61, 0
	v_mov_b32_e32 v62, 0
	v_mov_b32_e32 v63, 0
	v_mov_b32_e32 v64, 0
	v_mov_b32_e32 v65, 0
	v_mov_b32_e32 v66, 0
	v_mov_b32_e32 v67, 0
	v_mov_b32_e32 v68, 0
	v_mov_b32_e32 v69, 0
	v_mov_b32_e32 v70, 0
	v_mov_b32_e32 v71, 0
	v_mov_b32_e32 v72, 0
	v_mov_b32_e32 v73, 0
	v_mov_b32_e32 v74, 0
	v_mov_b32_e32 v75, 0
	v_mov_b32_e32 v76, 0
	v_mov_b32_e32 v77, 0
	v_mov_b32_e32 v78, 0
	v_mov_b32_e32 v79, 0
	v_mov_b32_e32 v80, 0
	v_mov_b32_e32 v81, 0
	v_mov_b32_e32 v82, 0
	v_mov_b32_e32 v83, 0
	v_mov_b32_e32 v84, 0
	v_mov_b32_e32 v85, 0
	v_mov_b32_e32 v86, 0
	v_mov_b32_e32 v87, 0
	v_mov_b32_e32 v88, 0
	v_mov_b32_e32 v89, 0
	v_mov_b32_e32 v90, 0
	v_mov_b32_e32 v91, 0
	v_mov_b32_e32 v92, 0
	v_mov_b32_e32 v93, 0
	v_mov_b32_e32 v94, 0
	v_mov_b32_e32 v95, 0
	v_mov_b32_e32 v96, 0
	v_mov_b32_e32 v97, 0
	v_mov_b32_e32 v98, 0
	v_mov_b32_e32 v99, 0
	v_mov_b32_e32 v100, 0
	v_mov_b32_e32 v101, 0
	v_mov_b32_e32 v102, 0
	v_mov_b32_e32 v103, 0
	v_mov_b32_e32 v104, 0
	v_mov_b32_e32 v105, 0
	v_mov_b32_e32 v106, 0
	v_mov_b32_e32 v107, 0
	v_mov_b32_e32 v108, 0
	v_mov_b32_e32 v109, 0
	v_mov_b32_e32 v110, 0
	v_mov_b32_e32 v111, 0
	v_mov_b32_e32 v112, 0
	v_mov_b32_e32 v113, 0
	v_mov_b32_e32 v114, 0
	v_mov_b32_e32 v115, 0
	v_mov_b32_e32 v116, 0
	v_mov_b32_e32 v117, 0
	v_mov_b32_e32 v118, 0
	v_mov_b32_e32 v119, 0
	v_mov_b32_e32 v120, 0
	v_mov_b32_e32 v121, 0
	v_mov_b32_e32 v122, 0
	v_mov_b32_e32 v123, 0
	v_mov_b32_e32 v124, 0
	v_mov_b32_e32 v125, 0
	v_mov_b32_e32 v126, 0
	v_mov_b32_e32 v127, 0
	v_mov_b32_e32 v128, 0
	v_mov_b32_e32 v129, 0
	s_waitcnt vmcnt(63) lgkmcnt(0)
	s_barrier
	v_add_u32_e32 v240, s61, v238
	v_add_u32_e32 v241, s61, v239
	s_add_i32 m0, s60, s62
	v_mfma_f32_16x16x32_bf16 v[2:5], v[162:165], v[130:133], v[2:5]
	global_load_lds_dwordx4 v226, s[54:55]
	v_mfma_f32_16x16x32_bf16 v[6:9], v[166:169], v[130:133], v[6:9]
	global_load_lds_dwordx4 v226, s[54:55] offset:1024
	v_mfma_f32_16x16x32_bf16 v[10:13], v[170:173], v[130:133], v[10:13]
	global_load_lds_dwordx4 v226, s[54:55] offset:2048
	v_mfma_f32_16x16x32_bf16 v[14:17], v[174:177], v[130:133], v[14:17]
	global_load_lds_dwordx4 v226, s[54:55] offset:3072
	s_add_i32 m0, s60, s63
	v_mfma_f32_16x16x32_bf16 v[18:21], v[162:165], v[134:137], v[18:21]
	global_load_lds_dwordx4 v230, s[56:57]
	v_mfma_f32_16x16x32_bf16 v[22:25], v[166:169], v[134:137], v[22:25]
	global_load_lds_dwordx4 v231, s[56:57] offset:1024
	v_mfma_f32_16x16x32_bf16 v[26:29], v[170:173], v[134:137], v[26:29]
	v_mfma_f32_16x16x32_bf16 v[30:33], v[174:177], v[134:137], v[30:33]
	v_mfma_f32_16x16x32_bf16 v[34:37], v[162:165], v[138:141], v[34:37]
	ds_read_b128 v[210:213], v241 offset:0
	v_mfma_f32_16x16x32_bf16 v[38:41], v[166:169], v[138:141], v[38:41]
	ds_read_b128 v[214:217], v241 offset:256
	v_mfma_f32_16x16x32_bf16 v[42:45], v[170:173], v[138:141], v[42:45]
	ds_read_b128 v[218:221], v241 offset:2048
	v_mfma_f32_16x16x32_bf16 v[46:49], v[174:177], v[138:141], v[46:49]
	ds_read_b128 v[222:225], v241 offset:2304
	v_mfma_f32_16x16x32_bf16 v[50:53], v[162:165], v[142:145], v[50:53]
	ds_read_b128 v[178:181], v240 offset:0
	v_mfma_f32_16x16x32_bf16 v[54:57], v[166:169], v[142:145], v[54:57]
	ds_read_b128 v[182:185], v240 offset:1024
	v_mfma_f32_16x16x32_bf16 v[58:61], v[170:173], v[142:145], v[58:61]
	ds_read_b128 v[186:189], v240 offset:2048
	v_mfma_f32_16x16x32_bf16 v[62:65], v[174:177], v[142:145], v[62:65]
	ds_read_b128 v[190:193], v240 offset:3072
	v_mfma_f32_16x16x32_bf16 v[66:69], v[162:165], v[146:149], v[66:69]
	ds_read_b128 v[194:197], v240 offset:4096
	v_mfma_f32_16x16x32_bf16 v[70:73], v[166:169], v[146:149], v[70:73]
	ds_read_b128 v[198:201], v240 offset:5120
	v_mfma_f32_16x16x32_bf16 v[74:77], v[170:173], v[146:149], v[74:77]
	ds_read_b128 v[202:205], v240 offset:6144
	v_mfma_f32_16x16x32_bf16 v[78:81], v[174:177], v[146:149], v[78:81]
	ds_read_b128 v[206:209], v240 offset:7168
	v_mfma_f32_16x16x32_bf16 v[82:85], v[162:165], v[150:153], v[82:85]
	v_mfma_f32_16x16x32_bf16 v[86:89], v[166:169], v[150:153], v[86:89]
	v_mfma_f32_16x16x32_bf16 v[90:93], v[170:173], v[150:153], v[90:93]
	v_mfma_f32_16x16x32_bf16 v[94:97], v[174:177], v[150:153], v[94:97]
	v_mfma_f32_16x16x32_bf16 v[98:101], v[162:165], v[154:157], v[98:101]
	v_mfma_f32_16x16x32_bf16 v[102:105], v[166:169], v[154:157], v[102:105]
	v_mfma_f32_16x16x32_bf16 v[106:109], v[170:173], v[154:157], v[106:109]
	v_mfma_f32_16x16x32_bf16 v[110:113], v[174:177], v[154:157], v[110:113]
	v_mfma_f32_16x16x32_bf16 v[114:117], v[162:165], v[158:161], v[114:117]
	v_mfma_f32_16x16x32_bf16 v[118:121], v[166:169], v[158:161], v[118:121]
	v_mfma_f32_16x16x32_bf16 v[122:125], v[170:173], v[158:161], v[122:125]
	v_mfma_f32_16x16x32_bf16 v[126:129], v[174:177], v[158:161], v[126:129]
	s_add_i32 s60, s60, 0x6000
	s_cmp_eq_u32 s60, 0x12000
	s_cselect_b32 s60, 0, s60
	s_add_u32 s54, s54, s72
	s_addc_u32 s55, s55, 0
	s_add_u32 s56, s56, s73
	s_addc_u32 s57, s57, 0
	s_add_i32 s61, s61, 0x6000
	s_cmp_eq_u32 s61, 0x12000
	s_cselect_b32 s61, 0, s61
	s_waitcnt vmcnt(63) lgkmcnt(0)
	s_barrier
	v_add_u32_e32 v240, s61, v238
	v_add_u32_e32 v241, s61, v239
	s_add_i32 m0, s60, s62
	v_mfma_f32_16x16x32_bf16 v[2:5], v[210:213], v[178:181], v[2:5]
	global_load_lds_dwordx4 v226, s[54:55]
	v_mfma_f32_16x16x32_bf16 v[6:9], v[214:217], v[178:181], v[6:9]
	global_load_lds_dwordx4 v226, s[54:55] offset:1024
	v_mfma_f32_16x16x32_bf16 v[10:13], v[218:221], v[178:181], v[10:13]
	global_load_lds_dwordx4 v226, s[54:55] offset:2048
	v_mfma_f32_16x16x32_bf16 v[14:17], v[222:225], v[178:181], v[14:17]
	global_load_lds_dwordx4 v226, s[54:55] offset:3072
	s_add_i32 m0, s60, s63
	v_mfma_f32_16x16x32_bf16 v[18:21], v[210:213], v[182:185], v[18:21]
	global_load_lds_dwordx4 v230, s[56:57]
	v_mfma_f32_16x16x32_bf16 v[22:25], v[214:217], v[182:185], v[22:25]
	global_load_lds_dwordx4 v231, s[56:57] offset:1024
	v_mfma_f32_16x16x32_bf16 v[26:29], v[218:221], v[182:185], v[26:29]
	v_mfma_f32_16x16x32_bf16 v[30:33], v[222:225], v[182:185], v[30:33]
	v_mfma_f32_16x16x32_bf16 v[34:37], v[210:213], v[186:189], v[34:37]
	ds_read_b128 v[162:165], v241 offset:0
	v_mfma_f32_16x16x32_bf16 v[38:41], v[214:217], v[186:189], v[38:41]
	ds_read_b128 v[166:169], v241 offset:256
	v_mfma_f32_16x16x32_bf16 v[42:45], v[218:221], v[186:189], v[42:45]
	ds_read_b128 v[170:173], v241 offset:2048
	v_mfma_f32_16x16x32_bf16 v[46:49], v[222:225], v[186:189], v[46:49]
	ds_read_b128 v[174:177], v241 offset:2304
	v_mfma_f32_16x16x32_bf16 v[50:53], v[210:213], v[190:193], v[50:53]
	ds_read_b128 v[130:133], v240 offset:0
	v_mfma_f32_16x16x32_bf16 v[54:57], v[214:217], v[190:193], v[54:57]
	ds_read_b128 v[134:137], v240 offset:1024
	v_mfma_f32_16x16x32_bf16 v[58:61], v[218:221], v[190:193], v[58:61]
	ds_read_b128 v[138:141], v240 offset:2048
	v_mfma_f32_16x16x32_bf16 v[62:65], v[222:225], v[190:193], v[62:65]
	ds_read_b128 v[142:145], v240 offset:3072
	v_mfma_f32_16x16x32_bf16 v[66:69], v[210:213], v[194:197], v[66:69]
	ds_read_b128 v[146:149], v240 offset:4096
	v_mfma_f32_16x16x32_bf16 v[70:73], v[214:217], v[194:197], v[70:73]
	ds_read_b128 v[150:153], v240 offset:5120
	v_mfma_f32_16x16x32_bf16 v[74:77], v[218:221], v[194:197], v[74:77]
	ds_read_b128 v[154:157], v240 offset:6144
	v_mfma_f32_16x16x32_bf16 v[78:81], v[222:225], v[194:197], v[78:81]
	ds_read_b128 v[158:161], v240 offset:7168
	v_mfma_f32_16x16x32_bf16 v[82:85], v[210:213], v[198:201], v[82:85]
	v_mfma_f32_16x16x32_bf16 v[86:89], v[214:217], v[198:201], v[86:89]
	v_mfma_f32_16x16x32_bf16 v[90:93], v[218:221], v[198:201], v[90:93]
	v_mfma_f32_16x16x32_bf16 v[94:97], v[222:225], v[198:201], v[94:97]
	v_mfma_f32_16x16x32_bf16 v[98:101], v[210:213], v[202:205], v[98:101]
	v_mfma_f32_16x16x32_bf16 v[102:105], v[214:217], v[202:205], v[102:105]
	v_mfma_f32_16x16x32_bf16 v[106:109], v[218:221], v[202:205], v[106:109]
	v_mfma_f32_16x16x32_bf16 v[110:113], v[222:225], v[202:205], v[110:113]
	v_mfma_f32_16x16x32_bf16 v[114:117], v[210:213], v[206:209], v[114:117]
	v_mfma_f32_16x16x32_bf16 v[118:121], v[214:217], v[206:209], v[118:121]
	v_mfma_f32_16x16x32_bf16 v[122:125], v[218:221], v[206:209], v[122:125]
	v_mfma_f32_16x16x32_bf16 v[126:129], v[222:225], v[206:209], v[126:129]
	s_add_i32 s60, s60, 0x6000
	s_cmp_eq_u32 s60, 0x12000
	s_cselect_b32 s60, 0, s60
	s_add_u32 s54, s54, s72
	s_addc_u32 s55, s55, 0
	s_add_u32 s56, s56, s73
	s_addc_u32 s57, s57, 0
	s_add_i32 s61, s61, 0x6000
	s_cmp_eq_u32 s61, 0x12000
	s_cselect_b32 s61, 0, s61

.Lpj_kloop:
	s_waitcnt vmcnt(6) lgkmcnt(0)
	s_barrier
	v_add_u32_e32 v240, s61, v238
	v_add_u32_e32 v241, s61, v239
	s_add_i32 m0, s60, s62
	v_mfma_f32_16x16x32_bf16 v[2:5], v[162:165], v[130:133], v[2:5]
	global_load_lds_dwordx4 v226, s[54:55]
	v_mfma_f32_16x16x32_bf16 v[6:9], v[166:169], v[130:133], v[6:9]
	global_load_lds_dwordx4 v226, s[54:55] offset:1024
	v_mfma_f32_16x16x32_bf16 v[10:13], v[170:173], v[130:133], v[10:13]
	global_load_lds_dwordx4 v226, s[54:55] offset:2048
	v_mfma_f32_16x16x32_bf16 v[14:17], v[174:177], v[130:133], v[14:17]
	global_load_lds_dwordx4 v226, s[54:55] offset:3072
	s_add_i32 m0, s60, s63
	v_mfma_f32_16x16x32_bf16 v[18:21], v[162:165], v[134:137], v[18:21]
	global_load_lds_dwordx4 v230, s[56:57]
	v_mfma_f32_16x16x32_bf16 v[22:25], v[166:169], v[134:137], v[22:25]
	global_load_lds_dwordx4 v231, s[56:57] offset:1024
	v_mfma_f32_16x16x32_bf16 v[26:29], v[170:173], v[134:137], v[26:29]
	v_mfma_f32_16x16x32_bf16 v[30:33], v[174:177], v[134:137], v[30:33]
	v_mfma_f32_16x16x32_bf16 v[34:37], v[162:165], v[138:141], v[34:37]
	ds_read_b128 v[210:213], v241 offset:0
	v_mfma_f32_16x16x32_bf16 v[38:41], v[166:169], v[138:141], v[38:41]
	ds_read_b128 v[214:217], v241 offset:256
	v_mfma_f32_16x16x32_bf16 v[42:45], v[170:173], v[138:141], v[42:45]
	ds_read_b128 v[218:221], v241 offset:2048
	v_mfma_f32_16x16x32_bf16 v[46:49], v[174:177], v[138:141], v[46:49]
	ds_read_b128 v[222:225], v241 offset:2304
	v_mfma_f32_16x16x32_bf16 v[50:53], v[162:165], v[142:145], v[50:53]
	ds_read_b128 v[178:181], v240 offset:0
	v_mfma_f32_16x16x32_bf16 v[54:57], v[166:169], v[142:145], v[54:57]
	ds_read_b128 v[182:185], v240 offset:1024
	v_mfma_f32_16x16x32_bf16 v[58:61], v[170:173], v[142:145], v[58:61]
	ds_read_b128 v[186:189], v240 offset:2048
	v_mfma_f32_16x16x32_bf16 v[62:65], v[174:177], v[142:145], v[62:65]
	ds_read_b128 v[190:193], v240 offset:3072
	v_mfma_f32_16x16x32_bf16 v[66:69], v[162:165], v[146:149], v[66:69]
	ds_read_b128 v[194:197], v240 offset:4096
	v_mfma_f32_16x16x32_bf16 v[70:73], v[166:169], v[146:149], v[70:73]
	ds_read_b128 v[198:201], v240 offset:5120
	v_mfma_f32_16x16x32_bf16 v[74:77], v[170:173], v[146:149], v[74:77]
	ds_read_b128 v[202:205], v240 offset:6144
	v_mfma_f32_16x16x32_bf16 v[78:81], v[174:177], v[146:149], v[78:81]
	ds_read_b128 v[206:209], v240 offset:7168
	v_mfma_f32_16x16x32_bf16 v[82:85], v[162:165], v[150:153], v[82:85]
	v_mfma_f32_16x16x32_bf16 v[86:89], v[166:169], v[150:153], v[86:89]
	v_mfma_f32_16x16x32_bf16 v[90:93], v[170:173], v[150:153], v[90:93]
	v_mfma_f32_16x16x32_bf16 v[94:97], v[174:177], v[150:153], v[94:97]
	v_mfma_f32_16x16x32_bf16 v[98:101], v[162:165], v[154:157], v[98:101]
	v_mfma_f32_16x16x32_bf16 v[102:105], v[166:169], v[154:157], v[102:105]
	v_mfma_f32_16x16x32_bf16 v[106:109], v[170:173], v[154:157], v[106:109]
	v_mfma_f32_16x16x32_bf16 v[110:113], v[174:177], v[154:157], v[110:113]
	v_mfma_f32_16x16x32_bf16 v[114:117], v[162:165], v[158:161], v[114:117]
	v_mfma_f32_16x16x32_bf16 v[118:121], v[166:169], v[158:161], v[118:121]
	v_mfma_f32_16x16x32_bf16 v[122:125], v[170:173], v[158:161], v[122:125]
	v_mfma_f32_16x16x32_bf16 v[126:129], v[174:177], v[158:161], v[126:129]
	s_add_i32 s60, s60, 0x6000
	s_cmp_eq_u32 s60, 0x12000
	s_cselect_b32 s60, 0, s60
	s_add_u32 s54, s54, s72
	s_addc_u32 s55, s55, 0
	s_add_u32 s56, s56, s73
	s_addc_u32 s57, s57, 0
	s_add_i32 s61, s61, 0x6000
	s_cmp_eq_u32 s61, 0x12000
	s_cselect_b32 s61, 0, s61
	s_waitcnt vmcnt(6) lgkmcnt(0)
	s_barrier
	v_add_u32_e32 v240, s61, v238
	v_add_u32_e32 v241, s61, v239
	s_add_i32 m0, s60, s62
	v_mfma_f32_16x16x32_bf16 v[2:5], v[210:213], v[178:181], v[2:5]
	global_load_lds_dwordx4 v226, s[54:55]
	v_mfma_f32_16x16x32_bf16 v[6:9], v[214:217], v[178:181], v[6:9]
	global_load_lds_dwordx4 v226, s[54:55] offset:1024
	v_mfma_f32_16x16x32_bf16 v[10:13], v[218:221], v[178:181], v[10:13]
	global_load_lds_dwordx4 v226, s[54:55] offset:2048
	v_mfma_f32_16x16x32_bf16 v[14:17], v[222:225], v[178:181], v[14:17]
	global_load_lds_dwordx4 v226, s[54:55] offset:3072
	s_add_i32 m0, s60, s63
	v_mfma_f32_16x16x32_bf16 v[18:21], v[210:213], v[182:185], v[18:21]
	global_load_lds_dwordx4 v230, s[56:57]
	v_mfma_f32_16x16x32_bf16 v[22:25], v[214:217], v[182:185], v[22:25]
	global_load_lds_dwordx4 v231, s[56:57] offset:1024
	v_mfma_f32_16x16x32_bf16 v[26:29], v[218:221], v[182:185], v[26:29]
	v_mfma_f32_16x16x32_bf16 v[30:33], v[222:225], v[182:185], v[30:33]
	v_mfma_f32_16x16x32_bf16 v[34:37], v[210:213], v[186:189], v[34:37]
	ds_read_b128 v[162:165], v241 offset:0
	v_mfma_f32_16x16x32_bf16 v[38:41], v[214:217], v[186:189], v[38:41]
	ds_read_b128 v[166:169], v241 offset:256
	v_mfma_f32_16x16x32_bf16 v[42:45], v[218:221], v[186:189], v[42:45]
	ds_read_b128 v[170:173], v241 offset:2048
	v_mfma_f32_16x16x32_bf16 v[46:49], v[222:225], v[186:189], v[46:49]
	ds_read_b128 v[174:177], v241 offset:2304
	v_mfma_f32_16x16x32_bf16 v[50:53], v[210:213], v[190:193], v[50:53]
	ds_read_b128 v[130:133], v240 offset:0
	v_mfma_f32_16x16x32_bf16 v[54:57], v[214:217], v[190:193], v[54:57]
	ds_read_b128 v[134:137], v240 offset:1024
	v_mfma_f32_16x16x32_bf16 v[58:61], v[218:221], v[190:193], v[58:61]
	ds_read_b128 v[138:141], v240 offset:2048
	v_mfma_f32_16x16x32_bf16 v[62:65], v[222:225], v[190:193], v[62:65]
	ds_read_b128 v[142:145], v240 offset:3072
	v_mfma_f32_16x16x32_bf16 v[66:69], v[210:213], v[194:197], v[66:69]
	ds_read_b128 v[146:149], v240 offset:4096
	v_mfma_f32_16x16x32_bf16 v[70:73], v[214:217], v[194:197], v[70:73]
	ds_read_b128 v[150:153], v240 offset:5120
	v_mfma_f32_16x16x32_bf16 v[74:77], v[218:221], v[194:197], v[74:77]
	ds_read_b128 v[154:157], v240 offset:6144
	v_mfma_f32_16x16x32_bf16 v[78:81], v[222:225], v[194:197], v[78:81]
	ds_read_b128 v[158:161], v240 offset:7168
	v_mfma_f32_16x16x32_bf16 v[82:85], v[210:213], v[198:201], v[82:85]
	v_mfma_f32_16x16x32_bf16 v[86:89], v[214:217], v[198:201], v[86:89]
	v_mfma_f32_16x16x32_bf16 v[90:93], v[218:221], v[198:201], v[90:93]
	v_mfma_f32_16x16x32_bf16 v[94:97], v[222:225], v[198:201], v[94:97]
	v_mfma_f32_16x16x32_bf16 v[98:101], v[210:213], v[202:205], v[98:101]
	v_mfma_f32_16x16x32_bf16 v[102:105], v[214:217], v[202:205], v[102:105]
	v_mfma_f32_16x16x32_bf16 v[106:109], v[218:221], v[202:205], v[106:109]
	v_mfma_f32_16x16x32_bf16 v[110:113], v[222:225], v[202:205], v[110:113]
	v_mfma_f32_16x16x32_bf16 v[114:117], v[210:213], v[206:209], v[114:117]
	v_mfma_f32_16x16x32_bf16 v[118:121], v[214:217], v[206:209], v[118:121]
	v_mfma_f32_16x16x32_bf16 v[122:125], v[218:221], v[206:209], v[122:125]
	v_mfma_f32_16x16x32_bf16 v[126:129], v[222:225], v[206:209], v[126:129]
	s_add_i32 s60, s60, 0x6000
	s_cmp_eq_u32 s60, 0x12000
	s_cselect_b32 s60, 0, s60
	s_add_u32 s54, s54, s72
	s_addc_u32 s55, s55, 0
	s_add_u32 s56, s56, s73
	s_addc_u32 s57, s57, 0
	s_add_i32 s61, s61, 0x6000
	s_cmp_eq_u32 s61, 0x12000
	s_cselect_b32 s61, 0, s61
	s_add_i32 s40, s40, -1
	s_cmp_lg_u32 s40, 0
	s_cbranch_scc1 .Lpj_kloop
	s_cmp_eq_u32 s37, 0
	s_cbranch_scc1 .Lpj_tail_last
	s_waitcnt vmcnt(6) lgkmcnt(0)
	s_barrier
	v_add_u32_e32 v240, s61, v238
	v_add_u32_e32 v241, s61, v239
	s_add_i32 m0, s60, s62
	v_mfma_f32_16x16x32_bf16 v[2:5], v[162:165], v[130:133], v[2:5]
	global_load_lds_dwordx4 v226, s[54:55]
	v_mfma_f32_16x16x32_bf16 v[6:9], v[166:169], v[130:133], v[6:9]
	global_load_lds_dwordx4 v226, s[54:55] offset:1024
	v_mfma_f32_16x16x32_bf16 v[10:13], v[170:173], v[130:133], v[10:13]
	global_load_lds_dwordx4 v226, s[54:55] offset:2048
	v_mfma_f32_16x16x32_bf16 v[14:17], v[174:177], v[130:133], v[14:17]
	global_load_lds_dwordx4 v226, s[54:55] offset:3072
	s_add_i32 m0, s60, s63
	v_mfma_f32_16x16x32_bf16 v[18:21], v[162:165], v[134:137], v[18:21]
	global_load_lds_dwordx4 v230, s[56:57]
	v_mfma_f32_16x16x32_bf16 v[22:25], v[166:169], v[134:137], v[22:25]
	global_load_lds_dwordx4 v231, s[56:57] offset:1024
	v_mfma_f32_16x16x32_bf16 v[26:29], v[170:173], v[134:137], v[26:29]
	v_mfma_f32_16x16x32_bf16 v[30:33], v[174:177], v[134:137], v[30:33]
	v_mfma_f32_16x16x32_bf16 v[34:37], v[162:165], v[138:141], v[34:37]
	ds_read_b128 v[210:213], v241 offset:0
	v_mfma_f32_16x16x32_bf16 v[38:41], v[166:169], v[138:141], v[38:41]
	ds_read_b128 v[214:217], v241 offset:256
	v_mfma_f32_16x16x32_bf16 v[42:45], v[170:173], v[138:141], v[42:45]
	ds_read_b128 v[218:221], v241 offset:2048
	v_mfma_f32_16x16x32_bf16 v[46:49], v[174:177], v[138:141], v[46:49]
	ds_read_b128 v[222:225], v241 offset:2304
	v_mfma_f32_16x16x32_bf16 v[50:53], v[162:165], v[142:145], v[50:53]
	ds_read_b128 v[178:181], v240 offset:0
	v_mfma_f32_16x16x32_bf16 v[54:57], v[166:169], v[142:145], v[54:57]
	ds_read_b128 v[182:185], v240 offset:1024
	v_mfma_f32_16x16x32_bf16 v[58:61], v[170:173], v[142:145], v[58:61]
	ds_read_b128 v[186:189], v240 offset:2048
	v_mfma_f32_16x16x32_bf16 v[62:65], v[174:177], v[142:145], v[62:65]
	ds_read_b128 v[190:193], v240 offset:3072
	v_mfma_f32_16x16x32_bf16 v[66:69], v[162:165], v[146:149], v[66:69]
	ds_read_b128 v[194:197], v240 offset:4096
	v_mfma_f32_16x16x32_bf16 v[70:73], v[166:169], v[146:149], v[70:73]
	ds_read_b128 v[198:201], v240 offset:5120
	v_mfma_f32_16x16x32_bf16 v[74:77], v[170:173], v[146:149], v[74:77]
	ds_read_b128 v[202:205], v240 offset:6144
	v_mfma_f32_16x16x32_bf16 v[78:81], v[174:177], v[146:149], v[78:81]
	ds_read_b128 v[206:209], v240 offset:7168
	v_mfma_f32_16x16x32_bf16 v[82:85], v[162:165], v[150:153], v[82:85]
	v_mfma_f32_16x16x32_bf16 v[86:89], v[166:169], v[150:153], v[86:89]
	v_mfma_f32_16x16x32_bf16 v[90:93], v[170:173], v[150:153], v[90:93]
	v_mfma_f32_16x16x32_bf16 v[94:97], v[174:177], v[150:153], v[94:97]
	v_mfma_f32_16x16x32_bf16 v[98:101], v[162:165], v[154:157], v[98:101]
	v_mfma_f32_16x16x32_bf16 v[102:105], v[166:169], v[154:157], v[102:105]
	v_mfma_f32_16x16x32_bf16 v[106:109], v[170:173], v[154:157], v[106:109]
	v_mfma_f32_16x16x32_bf16 v[110:113], v[174:177], v[154:157], v[110:113]
	v_mfma_f32_16x16x32_bf16 v[114:117], v[162:165], v[158:161], v[114:117]
	v_mfma_f32_16x16x32_bf16 v[118:121], v[166:169], v[158:161], v[118:121]
	v_mfma_f32_16x16x32_bf16 v[122:125], v[170:173], v[158:161], v[122:125]
	v_mfma_f32_16x16x32_bf16 v[126:129], v[174:177], v[158:161], v[126:129]
	s_add_i32 s60, s60, 0x6000
	s_cmp_eq_u32 s60, 0x12000
	s_cselect_b32 s60, 0, s60
	s_add_u32 s54, s54, s72
	s_addc_u32 s55, s55, 0
	s_add_u32 s56, s56, s73
	s_addc_u32 s57, s57, 0
	s_add_i32 s61, s61, 0x6000
	s_cmp_eq_u32 s61, 0x12000
	s_cselect_b32 s61, 0, s61
	v_mov_b32_e32 v226, v232
	v_mov_b32_e32 v230, v236
	v_mov_b32_e32 v231, v237
	s_mov_b64 s[54:55], s[48:49]
	s_mov_b64 s[56:57], s[50:51]
	s_waitcnt vmcnt(6) lgkmcnt(0)
	s_barrier
	v_add_u32_e32 v240, s61, v238
	v_add_u32_e32 v241, s61, v239
	s_add_i32 m0, s60, s62
	v_mfma_f32_16x16x32_bf16 v[2:5], v[210:213], v[178:181], v[2:5]
	global_load_lds_dwordx4 v226, s[54:55]
	v_mfma_f32_16x16x32_bf16 v[6:9], v[214:217], v[178:181], v[6:9]
	global_load_lds_dwordx4 v226, s[54:55] offset:1024
	v_mfma_f32_16x16x32_bf16 v[10:13], v[218:221], v[178:181], v[10:13]
	global_load_lds_dwordx4 v226, s[54:55] offset:2048
	v_mfma_f32_16x16x32_bf16 v[14:17], v[222:225], v[178:181], v[14:17]
	global_load_lds_dwordx4 v226, s[54:55] offset:3072
	s_add_i32 m0, s60, s63
	v_mfma_f32_16x16x32_bf16 v[18:21], v[210:213], v[182:185], v[18:21]
	global_load_lds_dwordx4 v230, s[56:57]
	v_mfma_f32_16x16x32_bf16 v[22:25], v[214:217], v[182:185], v[22:25]
	global_load_lds_dwordx4 v231, s[56:57] offset:1024
	v_mfma_f32_16x16x32_bf16 v[26:29], v[218:221], v[182:185], v[26:29]
	v_mfma_f32_16x16x32_bf16 v[30:33], v[222:225], v[182:185], v[30:33]
	v_mfma_f32_16x16x32_bf16 v[34:37], v[210:213], v[186:189], v[34:37]
	ds_read_b128 v[162:165], v241 offset:0
	v_mfma_f32_16x16x32_bf16 v[38:41], v[214:217], v[186:189], v[38:41]
	ds_read_b128 v[166:169], v241 offset:256
	v_mfma_f32_16x16x32_bf16 v[42:45], v[218:221], v[186:189], v[42:45]
	ds_read_b128 v[170:173], v241 offset:2048
	v_mfma_f32_16x16x32_bf16 v[46:49], v[222:225], v[186:189], v[46:49]
	ds_read_b128 v[174:177], v241 offset:2304
	v_mfma_f32_16x16x32_bf16 v[50:53], v[210:213], v[190:193], v[50:53]
	ds_read_b128 v[130:133], v240 offset:0
	v_mfma_f32_16x16x32_bf16 v[54:57], v[214:217], v[190:193], v[54:57]
	ds_read_b128 v[134:137], v240 offset:1024
	v_mfma_f32_16x16x32_bf16 v[58:61], v[218:221], v[190:193], v[58:61]
	ds_read_b128 v[138:141], v240 offset:2048
	v_mfma_f32_16x16x32_bf16 v[62:65], v[222:225], v[190:193], v[62:65]
	ds_read_b128 v[142:145], v240 offset:3072
	v_mfma_f32_16x16x32_bf16 v[66:69], v[210:213], v[194:197], v[66:69]
	ds_read_b128 v[146:149], v240 offset:4096
	v_mfma_f32_16x16x32_bf16 v[70:73], v[214:217], v[194:197], v[70:73]
	ds_read_b128 v[150:153], v240 offset:5120
	v_mfma_f32_16x16x32_bf16 v[74:77], v[218:221], v[194:197], v[74:77]
	ds_read_b128 v[154:157], v240 offset:6144
	v_mfma_f32_16x16x32_bf16 v[78:81], v[222:225], v[194:197], v[78:81]
	ds_read_b128 v[158:161], v240 offset:7168
	v_mfma_f32_16x16x32_bf16 v[82:85], v[210:213], v[198:201], v[82:85]
	v_mfma_f32_16x16x32_bf16 v[86:89], v[214:217], v[198:201], v[86:89]
	v_mfma_f32_16x16x32_bf16 v[90:93], v[218:221], v[198:201], v[90:93]
	v_mfma_f32_16x16x32_bf16 v[94:97], v[222:225], v[198:201], v[94:97]
	v_mfma_f32_16x16x32_bf16 v[98:101], v[210:213], v[202:205], v[98:101]
	v_mfma_f32_16x16x32_bf16 v[102:105], v[214:217], v[202:205], v[102:105]
	v_mfma_f32_16x16x32_bf16 v[106:109], v[218:221], v[202:205], v[106:109]
	v_mfma_f32_16x16x32_bf16 v[110:113], v[222:225], v[202:205], v[110:113]
	v_mfma_f32_16x16x32_bf16 v[114:117], v[210:213], v[206:209], v[114:117]
	v_mfma_f32_16x16x32_bf16 v[118:121], v[214:217], v[206:209], v[118:121]
	v_mfma_f32_16x16x32_bf16 v[122:125], v[218:221], v[206:209], v[122:125]
	v_mfma_f32_16x16x32_bf16 v[126:129], v[222:225], v[206:209], v[126:129]
	s_add_i32 s60, s60, 0x6000
	s_cmp_eq_u32 s60, 0x12000
	s_cselect_b32 s60, 0, s60
	s_add_u32 s54, s54, s72
	s_addc_u32 s55, s55, 0
	s_add_u32 s56, s56, s73
	s_addc_u32 s57, s57, 0
	s_add_i32 s61, s61, 0x6000
	s_cmp_eq_u32 s61, 0x12000
	s_cselect_b32 s61, 0, s61
	s_waitcnt vmcnt(6) lgkmcnt(0)
	s_barrier
	v_add_u32_e32 v240, s61, v238
	v_add_u32_e32 v241, s61, v239
	s_add_i32 m0, s60, s62
	v_mfma_f32_16x16x32_bf16 v[2:5], v[162:165], v[130:133], v[2:5]
	global_load_lds_dwordx4 v226, s[54:55]
	v_mfma_f32_16x16x32_bf16 v[6:9], v[166:169], v[130:133], v[6:9]
	global_load_lds_dwordx4 v226, s[54:55] offset:1024
	v_mfma_f32_16x16x32_bf16 v[10:13], v[170:173], v[130:133], v[10:13]
	global_load_lds_dwordx4 v226, s[54:55] offset:2048
	v_mfma_f32_16x16x32_bf16 v[14:17], v[174:177], v[130:133], v[14:17]
	global_load_lds_dwordx4 v226, s[54:55] offset:3072
	s_add_i32 m0, s60, s63
	v_mfma_f32_16x16x32_bf16 v[18:21], v[162:165], v[134:137], v[18:21]
	global_load_lds_dwordx4 v230, s[56:57]
	v_mfma_f32_16x16x32_bf16 v[22:25], v[166:169], v[134:137], v[22:25]
	global_load_lds_dwordx4 v231, s[56:57] offset:1024
	v_mfma_f32_16x16x32_bf16 v[26:29], v[170:173], v[134:137], v[26:29]
	v_mfma_f32_16x16x32_bf16 v[30:33], v[174:177], v[134:137], v[30:33]
	v_mfma_f32_16x16x32_bf16 v[34:37], v[162:165], v[138:141], v[34:37]
	ds_read_b128 v[210:213], v241 offset:0
	v_mfma_f32_16x16x32_bf16 v[38:41], v[166:169], v[138:141], v[38:41]
	ds_read_b128 v[214:217], v241 offset:256
	v_mfma_f32_16x16x32_bf16 v[42:45], v[170:173], v[138:141], v[42:45]
	ds_read_b128 v[218:221], v241 offset:2048
	v_mfma_f32_16x16x32_bf16 v[46:49], v[174:177], v[138:141], v[46:49]
	ds_read_b128 v[222:225], v241 offset:2304
	v_mfma_f32_16x16x32_bf16 v[50:53], v[162:165], v[142:145], v[50:53]
	ds_read_b128 v[178:181], v240 offset:0
	v_mfma_f32_16x16x32_bf16 v[54:57], v[166:169], v[142:145], v[54:57]
	ds_read_b128 v[182:185], v240 offset:1024
	v_mfma_f32_16x16x32_bf16 v[58:61], v[170:173], v[142:145], v[58:61]
	ds_read_b128 v[186:189], v240 offset:2048
	v_mfma_f32_16x16x32_bf16 v[62:65], v[174:177], v[142:145], v[62:65]
	ds_read_b128 v[190:193], v240 offset:3072
	v_mfma_f32_16x16x32_bf16 v[66:69], v[162:165], v[146:149], v[66:69]
	ds_read_b128 v[194:197], v240 offset:4096
	v_mfma_f32_16x16x32_bf16 v[70:73], v[166:169], v[146:149], v[70:73]
	ds_read_b128 v[198:201], v240 offset:5120
	v_mfma_f32_16x16x32_bf16 v[74:77], v[170:173], v[146:149], v[74:77]
	ds_read_b128 v[202:205], v240 offset:6144
	v_mfma_f32_16x16x32_bf16 v[78:81], v[174:177], v[146:149], v[78:81]
	ds_read_b128 v[206:209], v240 offset:7168
	v_mfma_f32_16x16x32_bf16 v[82:85], v[162:165], v[150:153], v[82:85]
	v_mfma_f32_16x16x32_bf16 v[86:89], v[166:169], v[150:153], v[86:89]
	v_mfma_f32_16x16x32_bf16 v[90:93], v[170:173], v[150:153], v[90:93]
	v_mfma_f32_16x16x32_bf16 v[94:97], v[174:177], v[150:153], v[94:97]
	v_mfma_f32_16x16x32_bf16 v[98:101], v[162:165], v[154:157], v[98:101]
	v_mfma_f32_16x16x32_bf16 v[102:105], v[166:169], v[154:157], v[102:105]
	v_mfma_f32_16x16x32_bf16 v[106:109], v[170:173], v[154:157], v[106:109]
	v_mfma_f32_16x16x32_bf16 v[110:113], v[174:177], v[154:157], v[110:113]
	v_mfma_f32_16x16x32_bf16 v[114:117], v[162:165], v[158:161], v[114:117]
	v_mfma_f32_16x16x32_bf16 v[118:121], v[166:169], v[158:161], v[118:121]
	v_mfma_f32_16x16x32_bf16 v[122:125], v[170:173], v[158:161], v[122:125]
	v_mfma_f32_16x16x32_bf16 v[126:129], v[174:177], v[158:161], v[126:129]
	s_add_i32 s60, s60, 0x6000
	s_cmp_eq_u32 s60, 0x12000
	s_cselect_b32 s60, 0, s60
	s_add_u32 s54, s54, s72
	s_addc_u32 s55, s55, 0
	s_add_u32 s56, s56, s73
	s_addc_u32 s57, s57, 0
	s_add_i32 s61, s61, 0x6000
	s_cmp_eq_u32 s61, 0x12000
	s_cselect_b32 s61, 0, s61
	s_waitcnt vmcnt(6) lgkmcnt(0)
	s_barrier
	v_add_u32_e32 v240, s61, v238
	v_add_u32_e32 v241, s61, v239
	s_add_i32 m0, s60, s62
	v_mfma_f32_16x16x32_bf16 v[2:5], v[210:213], v[178:181], v[2:5]
	global_load_lds_dwordx4 v226, s[54:55]
	v_mfma_f32_16x16x32_bf16 v[6:9], v[214:217], v[178:181], v[6:9]
	global_load_lds_dwordx4 v226, s[54:55] offset:1024
	v_mfma_f32_16x16x32_bf16 v[10:13], v[218:221], v[178:181], v[10:13]
	global_load_lds_dwordx4 v226, s[54:55] offset:2048
	v_mfma_f32_16x16x32_bf16 v[14:17], v[222:225], v[178:181], v[14:17]
	global_load_lds_dwordx4 v226, s[54:55] offset:3072
	s_add_i32 m0, s60, s63
	v_mfma_f32_16x16x32_bf16 v[18:21], v[210:213], v[182:185], v[18:21]
	global_load_lds_dwordx4 v230, s[56:57]
	v_mfma_f32_16x16x32_bf16 v[22:25], v[214:217], v[182:185], v[22:25]
	global_load_lds_dwordx4 v231, s[56:57] offset:1024
	v_mfma_f32_16x16x32_bf16 v[26:29], v[218:221], v[182:185], v[26:29]
	v_mfma_f32_16x16x32_bf16 v[30:33], v[222:225], v[182:185], v[30:33]
	v_mfma_f32_16x16x32_bf16 v[34:37], v[210:213], v[186:189], v[34:37]
	ds_read_b128 v[162:165], v241 offset:0
	v_mfma_f32_16x16x32_bf16 v[38:41], v[214:217], v[186:189], v[38:41]
	ds_read_b128 v[166:169], v241 offset:256
	v_mfma_f32_16x16x32_bf16 v[42:45], v[218:221], v[186:189], v[42:45]
	ds_read_b128 v[170:173], v241 offset:2048
	v_mfma_f32_16x16x32_bf16 v[46:49], v[222:225], v[186:189], v[46:49]
	ds_read_b128 v[174:177], v241 offset:2304
	v_mfma_f32_16x16x32_bf16 v[50:53], v[210:213], v[190:193], v[50:53]
	ds_read_b128 v[130:133], v240 offset:0
	v_mfma_f32_16x16x32_bf16 v[54:57], v[214:217], v[190:193], v[54:57]
	ds_read_b128 v[134:137], v240 offset:1024
	v_mfma_f32_16x16x32_bf16 v[58:61], v[218:221], v[190:193], v[58:61]
	ds_read_b128 v[138:141], v240 offset:2048
	v_mfma_f32_16x16x32_bf16 v[62:65], v[222:225], v[190:193], v[62:65]
	ds_read_b128 v[142:145], v240 offset:3072
	v_mfma_f32_16x16x32_bf16 v[66:69], v[210:213], v[194:197], v[66:69]
	ds_read_b128 v[146:149], v240 offset:4096
	v_mfma_f32_16x16x32_bf16 v[70:73], v[214:217], v[194:197], v[70:73]
	ds_read_b128 v[150:153], v240 offset:5120
	v_mfma_f32_16x16x32_bf16 v[74:77], v[218:221], v[194:197], v[74:77]
	ds_read_b128 v[154:157], v240 offset:6144
	v_mfma_f32_16x16x32_bf16 v[78:81], v[222:225], v[194:197], v[78:81]
	ds_read_b128 v[158:161], v240 offset:7168
	v_mfma_f32_16x16x32_bf16 v[82:85], v[210:213], v[198:201], v[82:85]
	v_mfma_f32_16x16x32_bf16 v[86:89], v[214:217], v[198:201], v[86:89]
	v_mfma_f32_16x16x32_bf16 v[90:93], v[218:221], v[198:201], v[90:93]
	v_mfma_f32_16x16x32_bf16 v[94:97], v[222:225], v[198:201], v[94:97]
	v_mfma_f32_16x16x32_bf16 v[98:101], v[210:213], v[202:205], v[98:101]
	v_mfma_f32_16x16x32_bf16 v[102:105], v[214:217], v[202:205], v[102:105]
	v_mfma_f32_16x16x32_bf16 v[106:109], v[218:221], v[202:205], v[106:109]
	v_mfma_f32_16x16x32_bf16 v[110:113], v[222:225], v[202:205], v[110:113]
	v_mfma_f32_16x16x32_bf16 v[114:117], v[210:213], v[206:209], v[114:117]
	v_mfma_f32_16x16x32_bf16 v[118:121], v[214:217], v[206:209], v[118:121]
	v_mfma_f32_16x16x32_bf16 v[122:125], v[218:221], v[206:209], v[122:125]
	v_mfma_f32_16x16x32_bf16 v[126:129], v[222:225], v[206:209], v[126:129]
	s_add_i32 s60, s60, 0x6000
	s_cmp_eq_u32 s60, 0x12000
	s_cselect_b32 s60, 0, s60
	s_add_u32 s54, s54, s72
	s_addc_u32 s55, s55, 0
	s_add_u32 s56, s56, s73
	s_addc_u32 s57, s57, 0
	s_add_i32 s61, s61, 0x6000
	s_cmp_eq_u32 s61, 0x12000
	s_cselect_b32 s61, 0, s61
	s_branch .Lpj_epi
.Lpj_ret_n:
	s_mov_b32 s34, s38
	s_mov_b32 s35, s30
	s_mov_b32 s36, s31
	s_branch .Lpj_tile

.Lpj_epi:
	s_nop 7
	s_nop 1
	s_lshr_b32 s20, s36, 7
	s_cmp_lt_u32 s20, 3
	s_cbranch_scc1 .Lpj_case0
	s_cmp_lt_u32 s20, 6
	s_cbranch_scc1 .Lpj_case1
	s_cmp_lt_u32 s20, 9
	s_cbranch_scc1 .Lpj_case2
	s_cmp_lt_u32 s20, 12
	s_cbranch_scc1 .Lpj_case3
	s_cmp_lt_u32 s20, 15
	s_cbranch_scc1 .Lpj_case4
	s_cmp_lt_u32 s20, 18
	s_cbranch_scc1 .Lpj_case5
	s_cmp_lt_u32 s20, 21
	s_cbranch_scc1 .Lpj_case6
	s_cmp_lt_u32 s20, 23
	s_cbranch_scc1 .Lpj_case7
	s_cmp_lt_u32 s20, 25
	s_cbranch_scc1 .Lpj_case8
	s_cmp_lt_u32 s20, 27
	s_cbranch_scc1 .Lpj_case9
	s_cmp_lt_u32 s20, 29
	s_cbranch_scc1 .Lpj_case10
	s_branch .Lpj_glr
.Lpj_case0:
	s_movk_i32 s25, 0xc8
	s_load_dwordx2 s[18:19], s[0:1], s25
	s_sub_i32 s26, s20, 0
	s_lshl_b32 s26, s26, 7
	s_add_i32 s66, s26, 0
	s_movk_i32 s39, 1280
	s_mov_b32 s21, 0x3e000000
	s_branch .Lpj_rot
.Lpj_case1:
	s_movk_i32 s25, 0xd0
	s_load_dwordx2 s[18:19], s[0:1], s25
	s_sub_i32 s26, s20, 3
	s_lshl_b32 s26, s26, 7
	s_add_i32 s66, s26, 0
	s_movk_i32 s39, 1280
	s_mov_b32 s21, 0x3f800000
	s_branch .Lpj_rot
.Lpj_case2:
	s_movk_i32 s25, 0xd8
	s_load_dwordx2 s[18:19], s[0:1], s25
	s_sub_i32 s26, s20, 6
	s_lshl_b32 s26, s26, 1
	s_add_i32 s89, s26, 0
	s_add_i32 s89, s89, s43
	s_movk_i32 s90, 10
	s_branch .Lpj_vt
.Lpj_case3:
	s_movk_i32 s25, 0xe0
	s_load_dwordx2 s[18:19], s[0:1], s25
	s_sub_i32 s26, s20, 9
	s_lshl_b32 s26, s26, 7
	s_add_i32 s66, s26, 0
	s_movk_i32 s39, 1280
	s_branch .Lpj_silu
.Lpj_case4:
	s_movk_i32 s25, 0xe8
	s_load_dwordx2 s[18:19], s[0:1], s25
	s_sub_i32 s26, s20, 12
	s_lshl_b32 s26, s26, 7
	s_add_i32 s66, s26, 0
	s_movk_i32 s39, 768
	s_mov_b32 s21, 0x3e38aa3b
	s_branch .Lpj_row
.Lpj_case5:
	s_movk_i32 s25, 0xf0
	s_load_dwordx2 s[18:19], s[0:1], s25
	s_sub_i32 s26, s20, 15
	s_lshl_b32 s26, s26, 7
	s_add_i32 s66, s26, 0
	s_movk_i32 s39, 768
	s_mov_b32 s21, 0x3f800000
	s_branch .Lpj_row
.Lpj_case6:
	s_movk_i32 s25, 0xf8
	s_load_dwordx2 s[18:19], s[0:1], s25
	s_sub_i32 s26, s20, 18
	s_lshl_b32 s26, s26, 1
	s_add_i32 s89, s26, 0
	s_add_i32 s89, s89, s43
	s_movk_i32 s90, 6
	s_branch .Lpj_vt
.Lpj_case7:
	s_movk_i32 s25, 0xc8
	s_load_dwordx2 s[18:19], s[0:1], s25
	s_sub_i32 s26, s20, 21
	s_lshl_b32 s26, s26, 7
	s_add_i32 s66, s26, 384
	s_movk_i32 s39, 1280
	s_mov_b32 s21, 0x3e000000
	s_branch .Lpj_row
.Lpj_case8:
	s_movk_i32 s25, 0xd0
	s_load_dwordx2 s[18:19], s[0:1], s25
	s_sub_i32 s26, s20, 23
	s_lshl_b32 s26, s26, 7
	s_add_i32 s66, s26, 384
	s_movk_i32 s39, 1280
	s_mov_b32 s21, 0x3f800000
	s_branch .Lpj_row
.Lpj_case9:
	s_movk_i32 s25, 0xd8
	s_load_dwordx2 s[18:19], s[0:1], s25
	s_sub_i32 s26, s20, 25
	s_lshl_b32 s26, s26, 1
	s_add_i32 s89, s26, 6
	s_add_i32 s89, s89, s43
	s_movk_i32 s90, 10
	s_branch .Lpj_vt
.Lpj_case10:
	s_movk_i32 s25, 0xe0
	s_load_dwordx2 s[18:19], s[0:1], s25
	s_sub_i32 s26, s20, 27
	s_lshl_b32 s26, s26, 7
	s_add_i32 s66, s26, 384
	s_movk_i32 s39, 1280
	s_branch .Lpj_silu
.Lpj_rot:
	v_lshlrev_b32_e32 v196, 1, v228
	global_load_dwordx4 v[180:183], v196, s[82:83]
	global_load_dwordx4 v[184:187], v196, s[82:83] offset:16
	global_load_dwordx4 v[188:191], v196, s[92:93]
	global_load_dwordx4 v[192:195], v196, s[92:93] offset:16
	s_and_b32 s26, s35, 0xfff
	s_waitcnt vmcnt(0)
	v_add_u32_e32 v178, 0, v227
	v_add_u32_e32 v178, s26, v178
	v_and_b32_e32 v178, 0xfff, v178
	v_cvt_f32_u32_e32 v178, v178
	v_mul_f32_e32 v196, v180, v178
	v_fma_f32 v197, v178, v180, -v196
	v_floor_f32_e32 v198, v196
	v_fma_f32 v199, v180, v178, -v198
	v_fmac_f32_e32 v197, v188, v178
	v_add_f32_e32 v199, v199, v197
	v_sin_f32_e32 v200, v199
	v_cos_f32_e32 v201, v199
	s_nop 0
	v_mul_f32_e32 v202, v10, v200
	v_mul_f32_e32 v203, v10, v201
	v_fma_f32 v10, v2, v200, v203
	v_fma_f32 v2, v2, v201, -v202
	v_mul_f32_e32 v196, v181, v178
	v_fma_f32 v197, v178, v181, -v196
	v_floor_f32_e32 v198, v196
	v_fma_f32 v199, v181, v178, -v198
	v_fmac_f32_e32 v197, v189, v178
	v_add_f32_e32 v199, v199, v197
	v_sin_f32_e32 v200, v199
	v_cos_f32_e32 v201, v199
	s_nop 0
	v_mul_f32_e32 v202, v11, v200
	v_mul_f32_e32 v203, v11, v201
	v_fma_f32 v11, v3, v200, v203
	v_fma_f32 v3, v3, v201, -v202
	v_mul_f32_e32 v196, v182, v178
	v_fma_f32 v197, v178, v182, -v196
	v_floor_f32_e32 v198, v196
	v_fma_f32 v199, v182, v178, -v198
	v_fmac_f32_e32 v197, v190, v178
	v_add_f32_e32 v199, v199, v197
	v_sin_f32_e32 v200, v199
	v_cos_f32_e32 v201, v199
	s_nop 0
	v_mul_f32_e32 v202, v12, v200
	v_mul_f32_e32 v203, v12, v201
	v_fma_f32 v12, v4, v200, v203
	v_fma_f32 v4, v4, v201, -v202
	v_mul_f32_e32 v196, v183, v178
	v_fma_f32 v197, v178, v183, -v196
	v_floor_f32_e32 v198, v196
	v_fma_f32 v199, v183, v178, -v198
	v_fmac_f32_e32 v197, v191, v178
	v_add_f32_e32 v199, v199, v197
	v_sin_f32_e32 v200, v199
	v_cos_f32_e32 v201, v199
	s_nop 0
	v_mul_f32_e32 v202, v13, v200
	v_mul_f32_e32 v203, v13, v201
	v_fma_f32 v13, v5, v200, v203
	v_fma_f32 v5, v5, v201, -v202
	v_mul_f32_e32 v196, v184, v178
	v_fma_f32 v197, v178, v184, -v196
	v_floor_f32_e32 v198, v196
	v_fma_f32 v199, v184, v178, -v198
	v_fmac_f32_e32 v197, v192, v178
	v_add_f32_e32 v199, v199, v197
	v_sin_f32_e32 v200, v199
	v_cos_f32_e32 v201, v199
	s_nop 0
	v_mul_f32_e32 v202, v14, v200
	v_mul_f32_e32 v203, v14, v201
	v_fma_f32 v14, v6, v200, v203
	v_fma_f32 v6, v6, v201, -v202
	v_mul_f32_e32 v196, v185, v178
	v_fma_f32 v197, v178, v185, -v196
	v_floor_f32_e32 v198, v196
	v_fma_f32 v199, v185, v178, -v198
	v_fmac_f32_e32 v197, v193, v178
	v_add_f32_e32 v199, v199, v197
	v_sin_f32_e32 v200, v199
	v_cos_f32_e32 v201, v199
	s_nop 0
	v_mul_f32_e32 v202, v15, v200
	v_mul_f32_e32 v203, v15, v201
	v_fma_f32 v15, v7, v200, v203
	v_fma_f32 v7, v7, v201, -v202
	v_mul_f32_e32 v196, v186, v178
	v_fma_f32 v197, v178, v186, -v196
	v_floor_f32_e32 v198, v196
	v_fma_f32 v199, v186, v178, -v198
	v_fmac_f32_e32 v197, v194, v178
	v_add_f32_e32 v199, v199, v197
	v_sin_f32_e32 v200, v199
	v_cos_f32_e32 v201, v199
	s_nop 0
	v_mul_f32_e32 v202, v16, v200
	v_mul_f32_e32 v203, v16, v201
	v_fma_f32 v16, v8, v200, v203
	v_fma_f32 v8, v8, v201, -v202
	v_mul_f32_e32 v196, v187, v178
	v_fma_f32 v197, v178, v187, -v196
	v_floor_f32_e32 v198, v196
	v_fma_f32 v199, v187, v178, -v198
	v_fmac_f32_e32 v197, v195, v178
	v_add_f32_e32 v199, v199, v197
	v_sin_f32_e32 v200, v199
	v_cos_f32_e32 v201, v199
	s_nop 0
	v_mul_f32_e32 v202, v17, v200
	v_mul_f32_e32 v203, v17, v201
	v_fma_f32 v17, v9, v200, v203
	v_fma_f32 v9, v9, v201, -v202
	v_add_u32_e32 v178, 16, v227
	v_add_u32_e32 v178, s26, v178
	v_and_b32_e32 v178, 0xfff, v178
	v_cvt_f32_u32_e32 v178, v178
	v_mul_f32_e32 v196, v180, v178
	v_fma_f32 v197, v178, v180, -v196
	v_floor_f32_e32 v198, v196
	v_fma_f32 v199, v180, v178, -v198
	v_fmac_f32_e32 v197, v188, v178
	v_add_f32_e32 v199, v199, v197
	v_sin_f32_e32 v200, v199
	v_cos_f32_e32 v201, v199
	s_nop 0
	v_mul_f32_e32 v202, v26, v200
	v_mul_f32_e32 v203, v26, v201
	v_fma_f32 v26, v18, v200, v203
	v_fma_f32 v18, v18, v201, -v202
	v_mul_f32_e32 v196, v181, v178
	v_fma_f32 v197, v178, v181, -v196
	v_floor_f32_e32 v198, v196
	v_fma_f32 v199, v181, v178, -v198
	v_fmac_f32_e32 v197, v189, v178
	v_add_f32_e32 v199, v199, v197
	v_sin_f32_e32 v200, v199
	v_cos_f32_e32 v201, v199
	s_nop 0
	v_mul_f32_e32 v202, v27, v200
	v_mul_f32_e32 v203, v27, v201
	v_fma_f32 v27, v19, v200, v203
	v_fma_f32 v19, v19, v201, -v202
	v_mul_f32_e32 v196, v182, v178
	v_fma_f32 v197, v178, v182, -v196
	v_floor_f32_e32 v198, v196
	v_fma_f32 v199, v182, v178, -v198
	v_fmac_f32_e32 v197, v190, v178
	v_add_f32_e32 v199, v199, v197
	v_sin_f32_e32 v200, v199
	v_cos_f32_e32 v201, v199
	s_nop 0
	v_mul_f32_e32 v202, v28, v200
	v_mul_f32_e32 v203, v28, v201
	v_fma_f32 v28, v20, v200, v203
	v_fma_f32 v20, v20, v201, -v202
	v_mul_f32_e32 v196, v183, v178
	v_fma_f32 v197, v178, v183, -v196
	v_floor_f32_e32 v198, v196
	v_fma_f32 v199, v183, v178, -v198
	v_fmac_f32_e32 v197, v191, v178
	v_add_f32_e32 v199, v199, v197
	v_sin_f32_e32 v200, v199
	v_cos_f32_e32 v201, v199
	s_nop 0
	v_mul_f32_e32 v202, v29, v200
	v_mul_f32_e32 v203, v29, v201
	v_fma_f32 v29, v21, v200, v203
	v_fma_f32 v21, v21, v201, -v202
	v_mul_f32_e32 v196, v184, v178
	v_fma_f32 v197, v178, v184, -v196
	v_floor_f32_e32 v198, v196
	v_fma_f32 v199, v184, v178, -v198
	v_fmac_f32_e32 v197, v192, v178
	v_add_f32_e32 v199, v199, v197
	v_sin_f32_e32 v200, v199
	v_cos_f32_e32 v201, v199
	s_nop 0
	v_mul_f32_e32 v202, v30, v200
	v_mul_f32_e32 v203, v30, v201
	v_fma_f32 v30, v22, v200, v203
	v_fma_f32 v22, v22, v201, -v202
	v_mul_f32_e32 v196, v185, v178
	v_fma_f32 v197, v178, v185, -v196
	v_floor_f32_e32 v198, v196
	v_fma_f32 v199, v185, v178, -v198
	v_fmac_f32_e32 v197, v193, v178
	v_add_f32_e32 v199, v199, v197
	v_sin_f32_e32 v200, v199
	v_cos_f32_e32 v201, v199
	s_nop 0
	v_mul_f32_e32 v202, v31, v200
	v_mul_f32_e32 v203, v31, v201
	v_fma_f32 v31, v23, v200, v203
	v_fma_f32 v23, v23, v201, -v202
	v_mul_f32_e32 v196, v186, v178
	v_fma_f32 v197, v178, v186, -v196
	v_floor_f32_e32 v198, v196
	v_fma_f32 v199, v186, v178, -v198
	v_fmac_f32_e32 v197, v194, v178
	v_add_f32_e32 v199, v199, v197
	v_sin_f32_e32 v200, v199
	v_cos_f32_e32 v201, v199
	s_nop 0
	v_mul_f32_e32 v202, v32, v200
	v_mul_f32_e32 v203, v32, v201
	v_fma_f32 v32, v24, v200, v203
	v_fma_f32 v24, v24, v201, -v202
	v_mul_f32_e32 v196, v187, v178
	v_fma_f32 v197, v178, v187, -v196
	v_floor_f32_e32 v198, v196
	v_fma_f32 v199, v187, v178, -v198
	v_fmac_f32_e32 v197, v195, v178
	v_add_f32_e32 v199, v199, v197
	v_sin_f32_e32 v200, v199
	v_cos_f32_e32 v201, v199
	s_nop 0
	v_mul_f32_e32 v202, v33, v200
	v_mul_f32_e32 v203, v33, v201
	v_fma_f32 v33, v25, v200, v203
	v_fma_f32 v25, v25, v201, -v202
	v_add_u32_e32 v178, 32, v227
	v_add_u32_e32 v178, s26, v178
	v_and_b32_e32 v178, 0xfff, v178
	v_cvt_f32_u32_e32 v178, v178
	v_mul_f32_e32 v196, v180, v178
	v_fma_f32 v197, v178, v180, -v196
	v_floor_f32_e32 v198, v196
	v_fma_f32 v199, v180, v178, -v198
	v_fmac_f32_e32 v197, v188, v178
	v_add_f32_e32 v199, v199, v197
	v_sin_f32_e32 v200, v199
	v_cos_f32_e32 v201, v199
	s_nop 0
	v_mul_f32_e32 v202, v42, v200
	v_mul_f32_e32 v203, v42, v201
	v_fma_f32 v42, v34, v200, v203
	v_fma_f32 v34, v34, v201, -v202
	v_mul_f32_e32 v196, v181, v178
	v_fma_f32 v197, v178, v181, -v196
	v_floor_f32_e32 v198, v196
	v_fma_f32 v199, v181, v178, -v198
	v_fmac_f32_e32 v197, v189, v178
	v_add_f32_e32 v199, v199, v197
	v_sin_f32_e32 v200, v199
	v_cos_f32_e32 v201, v199
	s_nop 0
	v_mul_f32_e32 v202, v43, v200
	v_mul_f32_e32 v203, v43, v201
	v_fma_f32 v43, v35, v200, v203
	v_fma_f32 v35, v35, v201, -v202
	v_mul_f32_e32 v196, v182, v178
	v_fma_f32 v197, v178, v182, -v196
	v_floor_f32_e32 v198, v196
	v_fma_f32 v199, v182, v178, -v198
	v_fmac_f32_e32 v197, v190, v178
	v_add_f32_e32 v199, v199, v197
	v_sin_f32_e32 v200, v199
	v_cos_f32_e32 v201, v199
	s_nop 0
	v_mul_f32_e32 v202, v44, v200
	v_mul_f32_e32 v203, v44, v201
	v_fma_f32 v44, v36, v200, v203
	v_fma_f32 v36, v36, v201, -v202
	v_mul_f32_e32 v196, v183, v178
	v_fma_f32 v197, v178, v183, -v196
	v_floor_f32_e32 v198, v196
	v_fma_f32 v199, v183, v178, -v198
	v_fmac_f32_e32 v197, v191, v178
	v_add_f32_e32 v199, v199, v197
	v_sin_f32_e32 v200, v199
	v_cos_f32_e32 v201, v199
	s_nop 0
	v_mul_f32_e32 v202, v45, v200
	v_mul_f32_e32 v203, v45, v201
	v_fma_f32 v45, v37, v200, v203
	v_fma_f32 v37, v37, v201, -v202
	v_mul_f32_e32 v196, v184, v178
	v_fma_f32 v197, v178, v184, -v196
	v_floor_f32_e32 v198, v196
	v_fma_f32 v199, v184, v178, -v198
	v_fmac_f32_e32 v197, v192, v178
	v_add_f32_e32 v199, v199, v197
	v_sin_f32_e32 v200, v199
	v_cos_f32_e32 v201, v199
	s_nop 0
	v_mul_f32_e32 v202, v46, v200
	v_mul_f32_e32 v203, v46, v201
	v_fma_f32 v46, v38, v200, v203
	v_fma_f32 v38, v38, v201, -v202
	v_mul_f32_e32 v196, v185, v178
	v_fma_f32 v197, v178, v185, -v196
	v_floor_f32_e32 v198, v196
	v_fma_f32 v199, v185, v178, -v198
	v_fmac_f32_e32 v197, v193, v178
	v_add_f32_e32 v199, v199, v197
	v_sin_f32_e32 v200, v199
	v_cos_f32_e32 v201, v199
	s_nop 0
	v_mul_f32_e32 v202, v47, v200
	v_mul_f32_e32 v203, v47, v201
	v_fma_f32 v47, v39, v200, v203
	v_fma_f32 v39, v39, v201, -v202
	v_mul_f32_e32 v196, v186, v178
	v_fma_f32 v197, v178, v186, -v196
	v_floor_f32_e32 v198, v196
	v_fma_f32 v199, v186, v178, -v198
	v_fmac_f32_e32 v197, v194, v178
	v_add_f32_e32 v199, v199, v197
	v_sin_f32_e32 v200, v199
	v_cos_f32_e32 v201, v199
	s_nop 0
	v_mul_f32_e32 v202, v48, v200
	v_mul_f32_e32 v203, v48, v201
	v_fma_f32 v48, v40, v200, v203
	v_fma_f32 v40, v40, v201, -v202
	v_mul_f32_e32 v196, v187, v178
	v_fma_f32 v197, v178, v187, -v196
	v_floor_f32_e32 v198, v196
	v_fma_f32 v199, v187, v178, -v198
	v_fmac_f32_e32 v197, v195, v178
	v_add_f32_e32 v199, v199, v197
	v_sin_f32_e32 v200, v199
	v_cos_f32_e32 v201, v199
	s_nop 0
	v_mul_f32_e32 v202, v49, v200
	v_mul_f32_e32 v203, v49, v201
	v_fma_f32 v49, v41, v200, v203
	v_fma_f32 v41, v41, v201, -v202
	v_add_u32_e32 v178, 48, v227
	v_add_u32_e32 v178, s26, v178
	v_and_b32_e32 v178, 0xfff, v178
	v_cvt_f32_u32_e32 v178, v178
	v_mul_f32_e32 v196, v180, v178
	v_fma_f32 v197, v178, v180, -v196
	v_floor_f32_e32 v198, v196
	v_fma_f32 v199, v180, v178, -v198
	v_fmac_f32_e32 v197, v188, v178
	v_add_f32_e32 v199, v199, v197
	v_sin_f32_e32 v200, v199
	v_cos_f32_e32 v201, v199
	s_nop 0
	v_mul_f32_e32 v202, v58, v200
	v_mul_f32_e32 v203, v58, v201
	v_fma_f32 v58, v50, v200, v203
	v_fma_f32 v50, v50, v201, -v202
	v_mul_f32_e32 v196, v181, v178
	v_fma_f32 v197, v178, v181, -v196
	v_floor_f32_e32 v198, v196
	v_fma_f32 v199, v181, v178, -v198
	v_fmac_f32_e32 v197, v189, v178
	v_add_f32_e32 v199, v199, v197
	v_sin_f32_e32 v200, v199
	v_cos_f32_e32 v201, v199
	s_nop 0
	v_mul_f32_e32 v202, v59, v200
	v_mul_f32_e32 v203, v59, v201
	v_fma_f32 v59, v51, v200, v203
	v_fma_f32 v51, v51, v201, -v202
	v_mul_f32_e32 v196, v182, v178
	v_fma_f32 v197, v178, v182, -v196
	v_floor_f32_e32 v198, v196
	v_fma_f32 v199, v182, v178, -v198
	v_fmac_f32_e32 v197, v190, v178
	v_add_f32_e32 v199, v199, v197
	v_sin_f32_e32 v200, v199
	v_cos_f32_e32 v201, v199
	s_nop 0
	v_mul_f32_e32 v202, v60, v200
	v_mul_f32_e32 v203, v60, v201
	v_fma_f32 v60, v52, v200, v203
	v_fma_f32 v52, v52, v201, -v202
	v_mul_f32_e32 v196, v183, v178
	v_fma_f32 v197, v178, v183, -v196
	v_floor_f32_e32 v198, v196
	v_fma_f32 v199, v183, v178, -v198
	v_fmac_f32_e32 v197, v191, v178
	v_add_f32_e32 v199, v199, v197
	v_sin_f32_e32 v200, v199
	v_cos_f32_e32 v201, v199
	s_nop 0
	v_mul_f32_e32 v202, v61, v200
	v_mul_f32_e32 v203, v61, v201
	v_fma_f32 v61, v53, v200, v203
	v_fma_f32 v53, v53, v201, -v202
	v_mul_f32_e32 v196, v184, v178
	v_fma_f32 v197, v178, v184, -v196
	v_floor_f32_e32 v198, v196
	v_fma_f32 v199, v184, v178, -v198
	v_fmac_f32_e32 v197, v192, v178
	v_add_f32_e32 v199, v199, v197
	v_sin_f32_e32 v200, v199
	v_cos_f32_e32 v201, v199
	s_nop 0
	v_mul_f32_e32 v202, v62, v200
	v_mul_f32_e32 v203, v62, v201
	v_fma_f32 v62, v54, v200, v203
	v_fma_f32 v54, v54, v201, -v202
	v_mul_f32_e32 v196, v185, v178
	v_fma_f32 v197, v178, v185, -v196
	v_floor_f32_e32 v198, v196
	v_fma_f32 v199, v185, v178, -v198
	v_fmac_f32_e32 v197, v193, v178
	v_add_f32_e32 v199, v199, v197
	v_sin_f32_e32 v200, v199
	v_cos_f32_e32 v201, v199
	s_nop 0
	v_mul_f32_e32 v202, v63, v200
	v_mul_f32_e32 v203, v63, v201
	v_fma_f32 v63, v55, v200, v203
	v_fma_f32 v55, v55, v201, -v202
	v_mul_f32_e32 v196, v186, v178
	v_fma_f32 v197, v178, v186, -v196
	v_floor_f32_e32 v198, v196
	v_fma_f32 v199, v186, v178, -v198
	v_fmac_f32_e32 v197, v194, v178
	v_add_f32_e32 v199, v199, v197
	v_sin_f32_e32 v200, v199
	v_cos_f32_e32 v201, v199
	s_nop 0
	v_mul_f32_e32 v202, v64, v200
	v_mul_f32_e32 v203, v64, v201
	v_fma_f32 v64, v56, v200, v203
	v_fma_f32 v56, v56, v201, -v202
	v_mul_f32_e32 v196, v187, v178
	v_fma_f32 v197, v178, v187, -v196
	v_floor_f32_e32 v198, v196
	v_fma_f32 v199, v187, v178, -v198
	v_fmac_f32_e32 v197, v195, v178
	v_add_f32_e32 v199, v199, v197
	v_sin_f32_e32 v200, v199
	v_cos_f32_e32 v201, v199
	s_nop 0
	v_mul_f32_e32 v202, v65, v200
	v_mul_f32_e32 v203, v65, v201
	v_fma_f32 v65, v57, v200, v203
	v_fma_f32 v57, v57, v201, -v202
	v_add_u32_e32 v178, 64, v227
	v_add_u32_e32 v178, s26, v178
	v_and_b32_e32 v178, 0xfff, v178
	v_cvt_f32_u32_e32 v178, v178
	v_mul_f32_e32 v196, v180, v178
	v_fma_f32 v197, v178, v180, -v196
	v_floor_f32_e32 v198, v196
	v_fma_f32 v199, v180, v178, -v198
	v_fmac_f32_e32 v197, v188, v178
	v_add_f32_e32 v199, v199, v197
	v_sin_f32_e32 v200, v199
	v_cos_f32_e32 v201, v199
	s_nop 0
	v_mul_f32_e32 v202, v74, v200
	v_mul_f32_e32 v203, v74, v201
	v_fma_f32 v74, v66, v200, v203
	v_fma_f32 v66, v66, v201, -v202
	v_mul_f32_e32 v196, v181, v178
	v_fma_f32 v197, v178, v181, -v196
	v_floor_f32_e32 v198, v196
	v_fma_f32 v199, v181, v178, -v198
	v_fmac_f32_e32 v197, v189, v178
	v_add_f32_e32 v199, v199, v197
	v_sin_f32_e32 v200, v199
	v_cos_f32_e32 v201, v199
	s_nop 0
	v_mul_f32_e32 v202, v75, v200
	v_mul_f32_e32 v203, v75, v201
	v_fma_f32 v75, v67, v200, v203
	v_fma_f32 v67, v67, v201, -v202
	v_mul_f32_e32 v196, v182, v178
	v_fma_f32 v197, v178, v182, -v196
	v_floor_f32_e32 v198, v196
	v_fma_f32 v199, v182, v178, -v198
	v_fmac_f32_e32 v197, v190, v178
	v_add_f32_e32 v199, v199, v197
	v_sin_f32_e32 v200, v199
	v_cos_f32_e32 v201, v199
	s_nop 0
	v_mul_f32_e32 v202, v76, v200
	v_mul_f32_e32 v203, v76, v201
	v_fma_f32 v76, v68, v200, v203
	v_fma_f32 v68, v68, v201, -v202
	v_mul_f32_e32 v196, v183, v178
	v_fma_f32 v197, v178, v183, -v196
	v_floor_f32_e32 v198, v196
	v_fma_f32 v199, v183, v178, -v198
	v_fmac_f32_e32 v197, v191, v178
	v_add_f32_e32 v199, v199, v197
	v_sin_f32_e32 v200, v199
	v_cos_f32_e32 v201, v199
	s_nop 0
	v_mul_f32_e32 v202, v77, v200
	v_mul_f32_e32 v203, v77, v201
	v_fma_f32 v77, v69, v200, v203
	v_fma_f32 v69, v69, v201, -v202
	v_mul_f32_e32 v196, v184, v178
	v_fma_f32 v197, v178, v184, -v196
	v_floor_f32_e32 v198, v196
	v_fma_f32 v199, v184, v178, -v198
	v_fmac_f32_e32 v197, v192, v178
	v_add_f32_e32 v199, v199, v197
	v_sin_f32_e32 v200, v199
	v_cos_f32_e32 v201, v199
	s_nop 0
	v_mul_f32_e32 v202, v78, v200
	v_mul_f32_e32 v203, v78, v201
	v_fma_f32 v78, v70, v200, v203
	v_fma_f32 v70, v70, v201, -v202
	v_mul_f32_e32 v196, v185, v178
	v_fma_f32 v197, v178, v185, -v196
	v_floor_f32_e32 v198, v196
	v_fma_f32 v199, v185, v178, -v198
	v_fmac_f32_e32 v197, v193, v178
	v_add_f32_e32 v199, v199, v197
	v_sin_f32_e32 v200, v199
	v_cos_f32_e32 v201, v199
	s_nop 0
	v_mul_f32_e32 v202, v79, v200
	v_mul_f32_e32 v203, v79, v201
	v_fma_f32 v79, v71, v200, v203
	v_fma_f32 v71, v71, v201, -v202
	v_mul_f32_e32 v196, v186, v178
	v_fma_f32 v197, v178, v186, -v196
	v_floor_f32_e32 v198, v196
	v_fma_f32 v199, v186, v178, -v198
	v_fmac_f32_e32 v197, v194, v178
	v_add_f32_e32 v199, v199, v197
	v_sin_f32_e32 v200, v199
	v_cos_f32_e32 v201, v199
	s_nop 0
	v_mul_f32_e32 v202, v80, v200
	v_mul_f32_e32 v203, v80, v201
	v_fma_f32 v80, v72, v200, v203
	v_fma_f32 v72, v72, v201, -v202
	v_mul_f32_e32 v196, v187, v178
	v_fma_f32 v197, v178, v187, -v196
	v_floor_f32_e32 v198, v196
	v_fma_f32 v199, v187, v178, -v198
	v_fmac_f32_e32 v197, v195, v178
	v_add_f32_e32 v199, v199, v197
	v_sin_f32_e32 v200, v199
	v_cos_f32_e32 v201, v199
	s_nop 0
	v_mul_f32_e32 v202, v81, v200
	v_mul_f32_e32 v203, v81, v201
	v_fma_f32 v81, v73, v200, v203
	v_fma_f32 v73, v73, v201, -v202
	v_add_u32_e32 v178, 80, v227
	v_add_u32_e32 v178, s26, v178
	v_and_b32_e32 v178, 0xfff, v178
	v_cvt_f32_u32_e32 v178, v178
	v_mul_f32_e32 v196, v180, v178
	v_fma_f32 v197, v178, v180, -v196
	v_floor_f32_e32 v198, v196
	v_fma_f32 v199, v180, v178, -v198
	v_fmac_f32_e32 v197, v188, v178
	v_add_f32_e32 v199, v199, v197
	v_sin_f32_e32 v200, v199
	v_cos_f32_e32 v201, v199
	s_nop 0
	v_mul_f32_e32 v202, v90, v200
	v_mul_f32_e32 v203, v90, v201
	v_fma_f32 v90, v82, v200, v203
	v_fma_f32 v82, v82, v201, -v202
	v_mul_f32_e32 v196, v181, v178
	v_fma_f32 v197, v178, v181, -v196
	v_floor_f32_e32 v198, v196
	v_fma_f32 v199, v181, v178, -v198
	v_fmac_f32_e32 v197, v189, v178
	v_add_f32_e32 v199, v199, v197
	v_sin_f32_e32 v200, v199
	v_cos_f32_e32 v201, v199
	s_nop 0
	v_mul_f32_e32 v202, v91, v200
	v_mul_f32_e32 v203, v91, v201
	v_fma_f32 v91, v83, v200, v203
	v_fma_f32 v83, v83, v201, -v202
	v_mul_f32_e32 v196, v182, v178
	v_fma_f32 v197, v178, v182, -v196
	v_floor_f32_e32 v198, v196
	v_fma_f32 v199, v182, v178, -v198
	v_fmac_f32_e32 v197, v190, v178
	v_add_f32_e32 v199, v199, v197
	v_sin_f32_e32 v200, v199
	v_cos_f32_e32 v201, v199
	s_nop 0
	v_mul_f32_e32 v202, v92, v200
	v_mul_f32_e32 v203, v92, v201
	v_fma_f32 v92, v84, v200, v203
	v_fma_f32 v84, v84, v201, -v202
	v_mul_f32_e32 v196, v183, v178
	v_fma_f32 v197, v178, v183, -v196
	v_floor_f32_e32 v198, v196
	v_fma_f32 v199, v183, v178, -v198
	v_fmac_f32_e32 v197, v191, v178
	v_add_f32_e32 v199, v199, v197
	v_sin_f32_e32 v200, v199
	v_cos_f32_e32 v201, v199
	s_nop 0
	v_mul_f32_e32 v202, v93, v200
	v_mul_f32_e32 v203, v93, v201
	v_fma_f32 v93, v85, v200, v203
	v_fma_f32 v85, v85, v201, -v202
	v_mul_f32_e32 v196, v184, v178
	v_fma_f32 v197, v178, v184, -v196
	v_floor_f32_e32 v198, v196
	v_fma_f32 v199, v184, v178, -v198
	v_fmac_f32_e32 v197, v192, v178
	v_add_f32_e32 v199, v199, v197
	v_sin_f32_e32 v200, v199
	v_cos_f32_e32 v201, v199
	s_nop 0
	v_mul_f32_e32 v202, v94, v200
	v_mul_f32_e32 v203, v94, v201
	v_fma_f32 v94, v86, v200, v203
	v_fma_f32 v86, v86, v201, -v202
	v_mul_f32_e32 v196, v185, v178
	v_fma_f32 v197, v178, v185, -v196
	v_floor_f32_e32 v198, v196
	v_fma_f32 v199, v185, v178, -v198
	v_fmac_f32_e32 v197, v193, v178
	v_add_f32_e32 v199, v199, v197
	v_sin_f32_e32 v200, v199
	v_cos_f32_e32 v201, v199
	s_nop 0
	v_mul_f32_e32 v202, v95, v200
	v_mul_f32_e32 v203, v95, v201
	v_fma_f32 v95, v87, v200, v203
	v_fma_f32 v87, v87, v201, -v202
	v_mul_f32_e32 v196, v186, v178
	v_fma_f32 v197, v178, v186, -v196
	v_floor_f32_e32 v198, v196
	v_fma_f32 v199, v186, v178, -v198
	v_fmac_f32_e32 v197, v194, v178
	v_add_f32_e32 v199, v199, v197
	v_sin_f32_e32 v200, v199
	v_cos_f32_e32 v201, v199
	s_nop 0
	v_mul_f32_e32 v202, v96, v200
	v_mul_f32_e32 v203, v96, v201
	v_fma_f32 v96, v88, v200, v203
	v_fma_f32 v88, v88, v201, -v202
	v_mul_f32_e32 v196, v187, v178
	v_fma_f32 v197, v178, v187, -v196
	v_floor_f32_e32 v198, v196
	v_fma_f32 v199, v187, v178, -v198
	v_fmac_f32_e32 v197, v195, v178
	v_add_f32_e32 v199, v199, v197
	v_sin_f32_e32 v200, v199
	v_cos_f32_e32 v201, v199
	s_nop 0
	v_mul_f32_e32 v202, v97, v200
	v_mul_f32_e32 v203, v97, v201
	v_fma_f32 v97, v89, v200, v203
	v_fma_f32 v89, v89, v201, -v202
	v_add_u32_e32 v178, 96, v227
	v_add_u32_e32 v178, s26, v178
	v_and_b32_e32 v178, 0xfff, v178
	v_cvt_f32_u32_e32 v178, v178
	v_mul_f32_e32 v196, v180, v178
	v_fma_f32 v197, v178, v180, -v196
	v_floor_f32_e32 v198, v196
	v_fma_f32 v199, v180, v178, -v198
	v_fmac_f32_e32 v197, v188, v178
	v_add_f32_e32 v199, v199, v197
	v_sin_f32_e32 v200, v199
	v_cos_f32_e32 v201, v199
	s_nop 0
	v_mul_f32_e32 v202, v106, v200
	v_mul_f32_e32 v203, v106, v201
	v_fma_f32 v106, v98, v200, v203
	v_fma_f32 v98, v98, v201, -v202
	v_mul_f32_e32 v196, v181, v178
	v_fma_f32 v197, v178, v181, -v196
	v_floor_f32_e32 v198, v196
	v_fma_f32 v199, v181, v178, -v198
	v_fmac_f32_e32 v197, v189, v178
	v_add_f32_e32 v199, v199, v197
	v_sin_f32_e32 v200, v199
	v_cos_f32_e32 v201, v199
	s_nop 0
	v_mul_f32_e32 v202, v107, v200
	v_mul_f32_e32 v203, v107, v201
	v_fma_f32 v107, v99, v200, v203
	v_fma_f32 v99, v99, v201, -v202
	v_mul_f32_e32 v196, v182, v178
	v_fma_f32 v197, v178, v182, -v196
	v_floor_f32_e32 v198, v196
	v_fma_f32 v199, v182, v178, -v198
	v_fmac_f32_e32 v197, v190, v178
	v_add_f32_e32 v199, v199, v197
	v_sin_f32_e32 v200, v199
	v_cos_f32_e32 v201, v199
	s_nop 0
	v_mul_f32_e32 v202, v108, v200
	v_mul_f32_e32 v203, v108, v201
	v_fma_f32 v108, v100, v200, v203
	v_fma_f32 v100, v100, v201, -v202
	v_mul_f32_e32 v196, v183, v178
	v_fma_f32 v197, v178, v183, -v196
	v_floor_f32_e32 v198, v196
	v_fma_f32 v199, v183, v178, -v198
	v_fmac_f32_e32 v197, v191, v178
	v_add_f32_e32 v199, v199, v197
	v_sin_f32_e32 v200, v199
	v_cos_f32_e32 v201, v199
	s_nop 0
	v_mul_f32_e32 v202, v109, v200
	v_mul_f32_e32 v203, v109, v201
	v_fma_f32 v109, v101, v200, v203
	v_fma_f32 v101, v101, v201, -v202
	v_mul_f32_e32 v196, v184, v178
	v_fma_f32 v197, v178, v184, -v196
	v_floor_f32_e32 v198, v196
	v_fma_f32 v199, v184, v178, -v198
	v_fmac_f32_e32 v197, v192, v178
	v_add_f32_e32 v199, v199, v197
	v_sin_f32_e32 v200, v199
	v_cos_f32_e32 v201, v199
	s_nop 0
	v_mul_f32_e32 v202, v110, v200
	v_mul_f32_e32 v203, v110, v201
	v_fma_f32 v110, v102, v200, v203
	v_fma_f32 v102, v102, v201, -v202
	v_mul_f32_e32 v196, v185, v178
	v_fma_f32 v197, v178, v185, -v196
	v_floor_f32_e32 v198, v196
	v_fma_f32 v199, v185, v178, -v198
	v_fmac_f32_e32 v197, v193, v178
	v_add_f32_e32 v199, v199, v197
	v_sin_f32_e32 v200, v199
	v_cos_f32_e32 v201, v199
	s_nop 0
	v_mul_f32_e32 v202, v111, v200
	v_mul_f32_e32 v203, v111, v201
	v_fma_f32 v111, v103, v200, v203
	v_fma_f32 v103, v103, v201, -v202
	v_mul_f32_e32 v196, v186, v178
	v_fma_f32 v197, v178, v186, -v196
	v_floor_f32_e32 v198, v196
	v_fma_f32 v199, v186, v178, -v198
	v_fmac_f32_e32 v197, v194, v178
	v_add_f32_e32 v199, v199, v197
	v_sin_f32_e32 v200, v199
	v_cos_f32_e32 v201, v199
	s_nop 0
	v_mul_f32_e32 v202, v112, v200
	v_mul_f32_e32 v203, v112, v201
	v_fma_f32 v112, v104, v200, v203
	v_fma_f32 v104, v104, v201, -v202
	v_mul_f32_e32 v196, v187, v178
	v_fma_f32 v197, v178, v187, -v196
	v_floor_f32_e32 v198, v196
	v_fma_f32 v199, v187, v178, -v198
	v_fmac_f32_e32 v197, v195, v178
	v_add_f32_e32 v199, v199, v197
	v_sin_f32_e32 v200, v199
	v_cos_f32_e32 v201, v199
	s_nop 0
	v_mul_f32_e32 v202, v113, v200
	v_mul_f32_e32 v203, v113, v201
	v_fma_f32 v113, v105, v200, v203
	v_fma_f32 v105, v105, v201, -v202
	v_add_u32_e32 v178, 112, v227
	v_add_u32_e32 v178, s26, v178
	v_and_b32_e32 v178, 0xfff, v178
	v_cvt_f32_u32_e32 v178, v178
	v_mul_f32_e32 v196, v180, v178
	v_fma_f32 v197, v178, v180, -v196
	v_floor_f32_e32 v198, v196
	v_fma_f32 v199, v180, v178, -v198
	v_fmac_f32_e32 v197, v188, v178
	v_add_f32_e32 v199, v199, v197
	v_sin_f32_e32 v200, v199
	v_cos_f32_e32 v201, v199
	s_nop 0
	v_mul_f32_e32 v202, v122, v200
	v_mul_f32_e32 v203, v122, v201
	v_fma_f32 v122, v114, v200, v203
	v_fma_f32 v114, v114, v201, -v202
	v_mul_f32_e32 v196, v181, v178
	v_fma_f32 v197, v178, v181, -v196
	v_floor_f32_e32 v198, v196
	v_fma_f32 v199, v181, v178, -v198
	v_fmac_f32_e32 v197, v189, v178
	v_add_f32_e32 v199, v199, v197
	v_sin_f32_e32 v200, v199
	v_cos_f32_e32 v201, v199
	s_nop 0
	v_mul_f32_e32 v202, v123, v200
	v_mul_f32_e32 v203, v123, v201
	v_fma_f32 v123, v115, v200, v203
	v_fma_f32 v115, v115, v201, -v202
	v_mul_f32_e32 v196, v182, v178
	v_fma_f32 v197, v178, v182, -v196
	v_floor_f32_e32 v198, v196
	v_fma_f32 v199, v182, v178, -v198
	v_fmac_f32_e32 v197, v190, v178
	v_add_f32_e32 v199, v199, v197
	v_sin_f32_e32 v200, v199
	v_cos_f32_e32 v201, v199
	s_nop 0
	v_mul_f32_e32 v202, v124, v200
	v_mul_f32_e32 v203, v124, v201
	v_fma_f32 v124, v116, v200, v203
	v_fma_f32 v116, v116, v201, -v202
	v_mul_f32_e32 v196, v183, v178
	v_fma_f32 v197, v178, v183, -v196
	v_floor_f32_e32 v198, v196
	v_fma_f32 v199, v183, v178, -v198
	v_fmac_f32_e32 v197, v191, v178
	v_add_f32_e32 v199, v199, v197
	v_sin_f32_e32 v200, v199
	v_cos_f32_e32 v201, v199
	s_nop 0
	v_mul_f32_e32 v202, v125, v200
	v_mul_f32_e32 v203, v125, v201
	v_fma_f32 v125, v117, v200, v203
	v_fma_f32 v117, v117, v201, -v202
	v_mul_f32_e32 v196, v184, v178
	v_fma_f32 v197, v178, v184, -v196
	v_floor_f32_e32 v198, v196
	v_fma_f32 v199, v184, v178, -v198
	v_fmac_f32_e32 v197, v192, v178
	v_add_f32_e32 v199, v199, v197
	v_sin_f32_e32 v200, v199
	v_cos_f32_e32 v201, v199
	s_nop 0
	v_mul_f32_e32 v202, v126, v200
	v_mul_f32_e32 v203, v126, v201
	v_fma_f32 v126, v118, v200, v203
	v_fma_f32 v118, v118, v201, -v202
	v_mul_f32_e32 v196, v185, v178
	v_fma_f32 v197, v178, v185, -v196
	v_floor_f32_e32 v198, v196
	v_fma_f32 v199, v185, v178, -v198
	v_fmac_f32_e32 v197, v193, v178
	v_add_f32_e32 v199, v199, v197
	v_sin_f32_e32 v200, v199
	v_cos_f32_e32 v201, v199
	s_nop 0
	v_mul_f32_e32 v202, v127, v200
	v_mul_f32_e32 v203, v127, v201
	v_fma_f32 v127, v119, v200, v203
	v_fma_f32 v119, v119, v201, -v202
	v_mul_f32_e32 v196, v186, v178
	v_fma_f32 v197, v178, v186, -v196
	v_floor_f32_e32 v198, v196
	v_fma_f32 v199, v186, v178, -v198
	v_fmac_f32_e32 v197, v194, v178
	v_add_f32_e32 v199, v199, v197
	v_sin_f32_e32 v200, v199
	v_cos_f32_e32 v201, v199
	s_nop 0
	v_mul_f32_e32 v202, v128, v200
	v_mul_f32_e32 v203, v128, v201
	v_fma_f32 v128, v120, v200, v203
	v_fma_f32 v120, v120, v201, -v202
	v_mul_f32_e32 v196, v187, v178
	v_fma_f32 v197, v178, v187, -v196
	v_floor_f32_e32 v198, v196
	v_fma_f32 v199, v187, v178, -v198
	v_fmac_f32_e32 v197, v195, v178
	v_add_f32_e32 v199, v199, v197
	v_sin_f32_e32 v200, v199
	v_cos_f32_e32 v201, v199
	s_nop 0
	v_mul_f32_e32 v202, v129, v200
	v_mul_f32_e32 v203, v129, v201
	v_fma_f32 v129, v121, v200, v203
	v_fma_f32 v121, v121, v201, -v202
	s_branch .Lpj_row
.Lpj_silu:
	v_mul_f32_e32 v196, 0xbfb8aa3b, v2
	v_exp_f32_e32 v196, v196
	s_nop 0
	v_add_f32_e32 v196, 1.0, v196
	v_rcp_f32_e32 v196, v196
	s_nop 0
	v_mul_f32_e32 v2, v2, v196
	v_mul_f32_e32 v196, 0xbfb8aa3b, v3
	v_exp_f32_e32 v196, v196
	s_nop 0
	v_add_f32_e32 v196, 1.0, v196
	v_rcp_f32_e32 v196, v196
	s_nop 0
	v_mul_f32_e32 v3, v3, v196
	v_mul_f32_e32 v196, 0xbfb8aa3b, v4
	v_exp_f32_e32 v196, v196
	s_nop 0
	v_add_f32_e32 v196, 1.0, v196
	v_rcp_f32_e32 v196, v196
	s_nop 0
	v_mul_f32_e32 v4, v4, v196
	v_mul_f32_e32 v196, 0xbfb8aa3b, v5
	v_exp_f32_e32 v196, v196
	s_nop 0
	v_add_f32_e32 v196, 1.0, v196
	v_rcp_f32_e32 v196, v196
	s_nop 0
	v_mul_f32_e32 v5, v5, v196
	v_mul_f32_e32 v196, 0xbfb8aa3b, v6
	v_exp_f32_e32 v196, v196
	s_nop 0
	v_add_f32_e32 v196, 1.0, v196
	v_rcp_f32_e32 v196, v196
	s_nop 0
	v_mul_f32_e32 v6, v6, v196
	v_mul_f32_e32 v196, 0xbfb8aa3b, v7
	v_exp_f32_e32 v196, v196
	s_nop 0
	v_add_f32_e32 v196, 1.0, v196
	v_rcp_f32_e32 v196, v196
	s_nop 0
	v_mul_f32_e32 v7, v7, v196
	v_mul_f32_e32 v196, 0xbfb8aa3b, v8
	v_exp_f32_e32 v196, v196
	s_nop 0
	v_add_f32_e32 v196, 1.0, v196
	v_rcp_f32_e32 v196, v196
	s_nop 0
	v_mul_f32_e32 v8, v8, v196
	v_mul_f32_e32 v196, 0xbfb8aa3b, v9
	v_exp_f32_e32 v196, v196
	s_nop 0
	v_add_f32_e32 v196, 1.0, v196
	v_rcp_f32_e32 v196, v196
	s_nop 0
	v_mul_f32_e32 v9, v9, v196
	v_mul_f32_e32 v196, 0xbfb8aa3b, v10
	v_exp_f32_e32 v196, v196
	s_nop 0
	v_add_f32_e32 v196, 1.0, v196
	v_rcp_f32_e32 v196, v196
	s_nop 0
	v_mul_f32_e32 v10, v10, v196
	v_mul_f32_e32 v196, 0xbfb8aa3b, v11
	v_exp_f32_e32 v196, v196
	s_nop 0
	v_add_f32_e32 v196, 1.0, v196
	v_rcp_f32_e32 v196, v196
	s_nop 0
	v_mul_f32_e32 v11, v11, v196
	v_mul_f32_e32 v196, 0xbfb8aa3b, v12
	v_exp_f32_e32 v196, v196
	s_nop 0
	v_add_f32_e32 v196, 1.0, v196
	v_rcp_f32_e32 v196, v196
	s_nop 0
	v_mul_f32_e32 v12, v12, v196
	v_mul_f32_e32 v196, 0xbfb8aa3b, v13
	v_exp_f32_e32 v196, v196
	s_nop 0
	v_add_f32_e32 v196, 1.0, v196
	v_rcp_f32_e32 v196, v196
	s_nop 0
	v_mul_f32_e32 v13, v13, v196
	v_mul_f32_e32 v196, 0xbfb8aa3b, v14
	v_exp_f32_e32 v196, v196
	s_nop 0
	v_add_f32_e32 v196, 1.0, v196
	v_rcp_f32_e32 v196, v196
	s_nop 0
	v_mul_f32_e32 v14, v14, v196
	v_mul_f32_e32 v196, 0xbfb8aa3b, v15
	v_exp_f32_e32 v196, v196
	s_nop 0
	v_add_f32_e32 v196, 1.0, v196
	v_rcp_f32_e32 v196, v196
	s_nop 0
	v_mul_f32_e32 v15, v15, v196
	v_mul_f32_e32 v196, 0xbfb8aa3b, v16
	v_exp_f32_e32 v196, v196
	s_nop 0
	v_add_f32_e32 v196, 1.0, v196
	v_rcp_f32_e32 v196, v196
	s_nop 0
	v_mul_f32_e32 v16, v16, v196
	v_mul_f32_e32 v196, 0xbfb8aa3b, v17
	v_exp_f32_e32 v196, v196
	s_nop 0
	v_add_f32_e32 v196, 1.0, v196
	v_rcp_f32_e32 v196, v196
	s_nop 0
	v_mul_f32_e32 v17, v17, v196
	v_mul_f32_e32 v196, 0xbfb8aa3b, v18
	v_exp_f32_e32 v196, v196
	s_nop 0
	v_add_f32_e32 v196, 1.0, v196
	v_rcp_f32_e32 v196, v196
	s_nop 0
	v_mul_f32_e32 v18, v18, v196
	v_mul_f32_e32 v196, 0xbfb8aa3b, v19
	v_exp_f32_e32 v196, v196
	s_nop 0
	v_add_f32_e32 v196, 1.0, v196
	v_rcp_f32_e32 v196, v196
	s_nop 0
	v_mul_f32_e32 v19, v19, v196
	v_mul_f32_e32 v196, 0xbfb8aa3b, v20
	v_exp_f32_e32 v196, v196
	s_nop 0
	v_add_f32_e32 v196, 1.0, v196
	v_rcp_f32_e32 v196, v196
	s_nop 0
	v_mul_f32_e32 v20, v20, v196
	v_mul_f32_e32 v196, 0xbfb8aa3b, v21
	v_exp_f32_e32 v196, v196
	s_nop 0
	v_add_f32_e32 v196, 1.0, v196
	v_rcp_f32_e32 v196, v196
	s_nop 0
	v_mul_f32_e32 v21, v21, v196
	v_mul_f32_e32 v196, 0xbfb8aa3b, v22
	v_exp_f32_e32 v196, v196
	s_nop 0
	v_add_f32_e32 v196, 1.0, v196
	v_rcp_f32_e32 v196, v196
	s_nop 0
	v_mul_f32_e32 v22, v22, v196
	v_mul_f32_e32 v196, 0xbfb8aa3b, v23
	v_exp_f32_e32 v196, v196
	s_nop 0
	v_add_f32_e32 v196, 1.0, v196
	v_rcp_f32_e32 v196, v196
	s_nop 0
	v_mul_f32_e32 v23, v23, v196
	v_mul_f32_e32 v196, 0xbfb8aa3b, v24
	v_exp_f32_e32 v196, v196
	s_nop 0
	v_add_f32_e32 v196, 1.0, v196
	v_rcp_f32_e32 v196, v196
	s_nop 0
	v_mul_f32_e32 v24, v24, v196
	v_mul_f32_e32 v196, 0xbfb8aa3b, v25
	v_exp_f32_e32 v196, v196
	s_nop 0
	v_add_f32_e32 v196, 1.0, v196
	v_rcp_f32_e32 v196, v196
	s_nop 0
	v_mul_f32_e32 v25, v25, v196
	v_mul_f32_e32 v196, 0xbfb8aa3b, v26
	v_exp_f32_e32 v196, v196
	s_nop 0
	v_add_f32_e32 v196, 1.0, v196
	v_rcp_f32_e32 v196, v196
	s_nop 0
	v_mul_f32_e32 v26, v26, v196
	v_mul_f32_e32 v196, 0xbfb8aa3b, v27
	v_exp_f32_e32 v196, v196
	s_nop 0
	v_add_f32_e32 v196, 1.0, v196
	v_rcp_f32_e32 v196, v196
	s_nop 0
	v_mul_f32_e32 v27, v27, v196
	v_mul_f32_e32 v196, 0xbfb8aa3b, v28
	v_exp_f32_e32 v196, v196
	s_nop 0
	v_add_f32_e32 v196, 1.0, v196
	v_rcp_f32_e32 v196, v196
	s_nop 0
	v_mul_f32_e32 v28, v28, v196
	v_mul_f32_e32 v196, 0xbfb8aa3b, v29
	v_exp_f32_e32 v196, v196
	s_nop 0
	v_add_f32_e32 v196, 1.0, v196
	v_rcp_f32_e32 v196, v196
	s_nop 0
	v_mul_f32_e32 v29, v29, v196
	v_mul_f32_e32 v196, 0xbfb8aa3b, v30
	v_exp_f32_e32 v196, v196
	s_nop 0
	v_add_f32_e32 v196, 1.0, v196
	v_rcp_f32_e32 v196, v196
	s_nop 0
	v_mul_f32_e32 v30, v30, v196
	v_mul_f32_e32 v196, 0xbfb8aa3b, v31
	v_exp_f32_e32 v196, v196
	s_nop 0
	v_add_f32_e32 v196, 1.0, v196
	v_rcp_f32_e32 v196, v196
	s_nop 0
	v_mul_f32_e32 v31, v31, v196
	v_mul_f32_e32 v196, 0xbfb8aa3b, v32
	v_exp_f32_e32 v196, v196
	s_nop 0
	v_add_f32_e32 v196, 1.0, v196
	v_rcp_f32_e32 v196, v196
	s_nop 0
	v_mul_f32_e32 v32, v32, v196
	v_mul_f32_e32 v196, 0xbfb8aa3b, v33
	v_exp_f32_e32 v196, v196
	s_nop 0
	v_add_f32_e32 v196, 1.0, v196
	v_rcp_f32_e32 v196, v196
	s_nop 0
	v_mul_f32_e32 v33, v33, v196
	v_mul_f32_e32 v196, 0xbfb8aa3b, v34
	v_exp_f32_e32 v196, v196
	s_nop 0
	v_add_f32_e32 v196, 1.0, v196
	v_rcp_f32_e32 v196, v196
	s_nop 0
	v_mul_f32_e32 v34, v34, v196
	v_mul_f32_e32 v196, 0xbfb8aa3b, v35
	v_exp_f32_e32 v196, v196
	s_nop 0
	v_add_f32_e32 v196, 1.0, v196
	v_rcp_f32_e32 v196, v196
	s_nop 0
	v_mul_f32_e32 v35, v35, v196
	v_mul_f32_e32 v196, 0xbfb8aa3b, v36
	v_exp_f32_e32 v196, v196
	s_nop 0
	v_add_f32_e32 v196, 1.0, v196
	v_rcp_f32_e32 v196, v196
	s_nop 0
	v_mul_f32_e32 v36, v36, v196
	v_mul_f32_e32 v196, 0xbfb8aa3b, v37
	v_exp_f32_e32 v196, v196
	s_nop 0
	v_add_f32_e32 v196, 1.0, v196
	v_rcp_f32_e32 v196, v196
	s_nop 0
	v_mul_f32_e32 v37, v37, v196
	v_mul_f32_e32 v196, 0xbfb8aa3b, v38
	v_exp_f32_e32 v196, v196
	s_nop 0
	v_add_f32_e32 v196, 1.0, v196
	v_rcp_f32_e32 v196, v196
	s_nop 0
	v_mul_f32_e32 v38, v38, v196
	v_mul_f32_e32 v196, 0xbfb8aa3b, v39
	v_exp_f32_e32 v196, v196
	s_nop 0
	v_add_f32_e32 v196, 1.0, v196
	v_rcp_f32_e32 v196, v196
	s_nop 0
	v_mul_f32_e32 v39, v39, v196
	v_mul_f32_e32 v196, 0xbfb8aa3b, v40
	v_exp_f32_e32 v196, v196
	s_nop 0
	v_add_f32_e32 v196, 1.0, v196
	v_rcp_f32_e32 v196, v196
	s_nop 0
	v_mul_f32_e32 v40, v40, v196
	v_mul_f32_e32 v196, 0xbfb8aa3b, v41
	v_exp_f32_e32 v196, v196
	s_nop 0
	v_add_f32_e32 v196, 1.0, v196
	v_rcp_f32_e32 v196, v196
	s_nop 0
	v_mul_f32_e32 v41, v41, v196
	v_mul_f32_e32 v196, 0xbfb8aa3b, v42
	v_exp_f32_e32 v196, v196
	s_nop 0
	v_add_f32_e32 v196, 1.0, v196
	v_rcp_f32_e32 v196, v196
	s_nop 0
	v_mul_f32_e32 v42, v42, v196
	v_mul_f32_e32 v196, 0xbfb8aa3b, v43
	v_exp_f32_e32 v196, v196
	s_nop 0
	v_add_f32_e32 v196, 1.0, v196
	v_rcp_f32_e32 v196, v196
	s_nop 0
	v_mul_f32_e32 v43, v43, v196
	v_mul_f32_e32 v196, 0xbfb8aa3b, v44
	v_exp_f32_e32 v196, v196
	s_nop 0
	v_add_f32_e32 v196, 1.0, v196
	v_rcp_f32_e32 v196, v196
	s_nop 0
	v_mul_f32_e32 v44, v44, v196
	v_mul_f32_e32 v196, 0xbfb8aa3b, v45
	v_exp_f32_e32 v196, v196
	s_nop 0
	v_add_f32_e32 v196, 1.0, v196
	v_rcp_f32_e32 v196, v196
	s_nop 0
	v_mul_f32_e32 v45, v45, v196
	v_mul_f32_e32 v196, 0xbfb8aa3b, v46
	v_exp_f32_e32 v196, v196
	s_nop 0
	v_add_f32_e32 v196, 1.0, v196
	v_rcp_f32_e32 v196, v196
	s_nop 0
	v_mul_f32_e32 v46, v46, v196
	v_mul_f32_e32 v196, 0xbfb8aa3b, v47
	v_exp_f32_e32 v196, v196
	s_nop 0
	v_add_f32_e32 v196, 1.0, v196
	v_rcp_f32_e32 v196, v196
	s_nop 0
	v_mul_f32_e32 v47, v47, v196
	v_mul_f32_e32 v196, 0xbfb8aa3b, v48
	v_exp_f32_e32 v196, v196
	s_nop 0
	v_add_f32_e32 v196, 1.0, v196
	v_rcp_f32_e32 v196, v196
	s_nop 0
	v_mul_f32_e32 v48, v48, v196
	v_mul_f32_e32 v196, 0xbfb8aa3b, v49
	v_exp_f32_e32 v196, v196
	s_nop 0
	v_add_f32_e32 v196, 1.0, v196
	v_rcp_f32_e32 v196, v196
	s_nop 0
	v_mul_f32_e32 v49, v49, v196
	v_mul_f32_e32 v196, 0xbfb8aa3b, v50
	v_exp_f32_e32 v196, v196
	s_nop 0
	v_add_f32_e32 v196, 1.0, v196
	v_rcp_f32_e32 v196, v196
	s_nop 0
	v_mul_f32_e32 v50, v50, v196
	v_mul_f32_e32 v196, 0xbfb8aa3b, v51
	v_exp_f32_e32 v196, v196
	s_nop 0
	v_add_f32_e32 v196, 1.0, v196
	v_rcp_f32_e32 v196, v196
	s_nop 0
	v_mul_f32_e32 v51, v51, v196
	v_mul_f32_e32 v196, 0xbfb8aa3b, v52
	v_exp_f32_e32 v196, v196
	s_nop 0
	v_add_f32_e32 v196, 1.0, v196
	v_rcp_f32_e32 v196, v196
	s_nop 0
	v_mul_f32_e32 v52, v52, v196
	v_mul_f32_e32 v196, 0xbfb8aa3b, v53
	v_exp_f32_e32 v196, v196
	s_nop 0
	v_add_f32_e32 v196, 1.0, v196
	v_rcp_f32_e32 v196, v196
	s_nop 0
	v_mul_f32_e32 v53, v53, v196
	v_mul_f32_e32 v196, 0xbfb8aa3b, v54
	v_exp_f32_e32 v196, v196
	s_nop 0
	v_add_f32_e32 v196, 1.0, v196
	v_rcp_f32_e32 v196, v196
	s_nop 0
	v_mul_f32_e32 v54, v54, v196
	v_mul_f32_e32 v196, 0xbfb8aa3b, v55
	v_exp_f32_e32 v196, v196
	s_nop 0
	v_add_f32_e32 v196, 1.0, v196
	v_rcp_f32_e32 v196, v196
	s_nop 0
	v_mul_f32_e32 v55, v55, v196
	v_mul_f32_e32 v196, 0xbfb8aa3b, v56
	v_exp_f32_e32 v196, v196
	s_nop 0
	v_add_f32_e32 v196, 1.0, v196
	v_rcp_f32_e32 v196, v196
	s_nop 0
	v_mul_f32_e32 v56, v56, v196
	v_mul_f32_e32 v196, 0xbfb8aa3b, v57
	v_exp_f32_e32 v196, v196
	s_nop 0
	v_add_f32_e32 v196, 1.0, v196
	v_rcp_f32_e32 v196, v196
	s_nop 0
	v_mul_f32_e32 v57, v57, v196
	v_mul_f32_e32 v196, 0xbfb8aa3b, v58
	v_exp_f32_e32 v196, v196
	s_nop 0
	v_add_f32_e32 v196, 1.0, v196
	v_rcp_f32_e32 v196, v196
	s_nop 0
	v_mul_f32_e32 v58, v58, v196
	v_mul_f32_e32 v196, 0xbfb8aa3b, v59
	v_exp_f32_e32 v196, v196
	s_nop 0
	v_add_f32_e32 v196, 1.0, v196
	v_rcp_f32_e32 v196, v196
	s_nop 0
	v_mul_f32_e32 v59, v59, v196
	v_mul_f32_e32 v196, 0xbfb8aa3b, v60
	v_exp_f32_e32 v196, v196
	s_nop 0
	v_add_f32_e32 v196, 1.0, v196
	v_rcp_f32_e32 v196, v196
	s_nop 0
	v_mul_f32_e32 v60, v60, v196
	v_mul_f32_e32 v196, 0xbfb8aa3b, v61
	v_exp_f32_e32 v196, v196
	s_nop 0
	v_add_f32_e32 v196, 1.0, v196
	v_rcp_f32_e32 v196, v196
	s_nop 0
	v_mul_f32_e32 v61, v61, v196
	v_mul_f32_e32 v196, 0xbfb8aa3b, v62
	v_exp_f32_e32 v196, v196
	s_nop 0
	v_add_f32_e32 v196, 1.0, v196
	v_rcp_f32_e32 v196, v196
	s_nop 0
	v_mul_f32_e32 v62, v62, v196
	v_mul_f32_e32 v196, 0xbfb8aa3b, v63
	v_exp_f32_e32 v196, v196
	s_nop 0
	v_add_f32_e32 v196, 1.0, v196
	v_rcp_f32_e32 v196, v196
	s_nop 0
	v_mul_f32_e32 v63, v63, v196
	v_mul_f32_e32 v196, 0xbfb8aa3b, v64
	v_exp_f32_e32 v196, v196
	s_nop 0
	v_add_f32_e32 v196, 1.0, v196
	v_rcp_f32_e32 v196, v196
	s_nop 0
	v_mul_f32_e32 v64, v64, v196
	v_mul_f32_e32 v196, 0xbfb8aa3b, v65
	v_exp_f32_e32 v196, v196
	s_nop 0
	v_add_f32_e32 v196, 1.0, v196
	v_rcp_f32_e32 v196, v196
	s_nop 0
	v_mul_f32_e32 v65, v65, v196
	v_mul_f32_e32 v196, 0xbfb8aa3b, v66
	v_exp_f32_e32 v196, v196
	s_nop 0
	v_add_f32_e32 v196, 1.0, v196
	v_rcp_f32_e32 v196, v196
	s_nop 0
	v_mul_f32_e32 v66, v66, v196
	v_mul_f32_e32 v196, 0xbfb8aa3b, v67
	v_exp_f32_e32 v196, v196
	s_nop 0
	v_add_f32_e32 v196, 1.0, v196
	v_rcp_f32_e32 v196, v196
	s_nop 0
	v_mul_f32_e32 v67, v67, v196
	v_mul_f32_e32 v196, 0xbfb8aa3b, v68
	v_exp_f32_e32 v196, v196
	s_nop 0
	v_add_f32_e32 v196, 1.0, v196
	v_rcp_f32_e32 v196, v196
	s_nop 0
	v_mul_f32_e32 v68, v68, v196
	v_mul_f32_e32 v196, 0xbfb8aa3b, v69
	v_exp_f32_e32 v196, v196
	s_nop 0
	v_add_f32_e32 v196, 1.0, v196
	v_rcp_f32_e32 v196, v196
	s_nop 0
	v_mul_f32_e32 v69, v69, v196
	v_mul_f32_e32 v196, 0xbfb8aa3b, v70
	v_exp_f32_e32 v196, v196
	s_nop 0
	v_add_f32_e32 v196, 1.0, v196
	v_rcp_f32_e32 v196, v196
	s_nop 0
	v_mul_f32_e32 v70, v70, v196
	v_mul_f32_e32 v196, 0xbfb8aa3b, v71
	v_exp_f32_e32 v196, v196
	s_nop 0
	v_add_f32_e32 v196, 1.0, v196
	v_rcp_f32_e32 v196, v196
	s_nop 0
	v_mul_f32_e32 v71, v71, v196
	v_mul_f32_e32 v196, 0xbfb8aa3b, v72
	v_exp_f32_e32 v196, v196
	s_nop 0
	v_add_f32_e32 v196, 1.0, v196
	v_rcp_f32_e32 v196, v196
	s_nop 0
	v_mul_f32_e32 v72, v72, v196
	v_mul_f32_e32 v196, 0xbfb8aa3b, v73
	v_exp_f32_e32 v196, v196
	s_nop 0
	v_add_f32_e32 v196, 1.0, v196
	v_rcp_f32_e32 v196, v196
	s_nop 0
	v_mul_f32_e32 v73, v73, v196
	v_mul_f32_e32 v196, 0xbfb8aa3b, v74
	v_exp_f32_e32 v196, v196
	s_nop 0
	v_add_f32_e32 v196, 1.0, v196
	v_rcp_f32_e32 v196, v196
	s_nop 0
	v_mul_f32_e32 v74, v74, v196
	v_mul_f32_e32 v196, 0xbfb8aa3b, v75
	v_exp_f32_e32 v196, v196
	s_nop 0
	v_add_f32_e32 v196, 1.0, v196
	v_rcp_f32_e32 v196, v196
	s_nop 0
	v_mul_f32_e32 v75, v75, v196
	v_mul_f32_e32 v196, 0xbfb8aa3b, v76
	v_exp_f32_e32 v196, v196
	s_nop 0
	v_add_f32_e32 v196, 1.0, v196
	v_rcp_f32_e32 v196, v196
	s_nop 0
	v_mul_f32_e32 v76, v76, v196
	v_mul_f32_e32 v196, 0xbfb8aa3b, v77
	v_exp_f32_e32 v196, v196
	s_nop 0
	v_add_f32_e32 v196, 1.0, v196
	v_rcp_f32_e32 v196, v196
	s_nop 0
	v_mul_f32_e32 v77, v77, v196
	v_mul_f32_e32 v196, 0xbfb8aa3b, v78
	v_exp_f32_e32 v196, v196
	s_nop 0
	v_add_f32_e32 v196, 1.0, v196
	v_rcp_f32_e32 v196, v196
	s_nop 0
	v_mul_f32_e32 v78, v78, v196
	v_mul_f32_e32 v196, 0xbfb8aa3b, v79
	v_exp_f32_e32 v196, v196
	s_nop 0
	v_add_f32_e32 v196, 1.0, v196
	v_rcp_f32_e32 v196, v196
	s_nop 0
	v_mul_f32_e32 v79, v79, v196
	v_mul_f32_e32 v196, 0xbfb8aa3b, v80
	v_exp_f32_e32 v196, v196
	s_nop 0
	v_add_f32_e32 v196, 1.0, v196
	v_rcp_f32_e32 v196, v196
	s_nop 0
	v_mul_f32_e32 v80, v80, v196
	v_mul_f32_e32 v196, 0xbfb8aa3b, v81
	v_exp_f32_e32 v196, v196
	s_nop 0
	v_add_f32_e32 v196, 1.0, v196
	v_rcp_f32_e32 v196, v196
	s_nop 0
	v_mul_f32_e32 v81, v81, v196
	v_mul_f32_e32 v196, 0xbfb8aa3b, v82
	v_exp_f32_e32 v196, v196
	s_nop 0
	v_add_f32_e32 v196, 1.0, v196
	v_rcp_f32_e32 v196, v196
	s_nop 0
	v_mul_f32_e32 v82, v82, v196
	v_mul_f32_e32 v196, 0xbfb8aa3b, v83
	v_exp_f32_e32 v196, v196
	s_nop 0
	v_add_f32_e32 v196, 1.0, v196
	v_rcp_f32_e32 v196, v196
	s_nop 0
	v_mul_f32_e32 v83, v83, v196
	v_mul_f32_e32 v196, 0xbfb8aa3b, v84
	v_exp_f32_e32 v196, v196
	s_nop 0
	v_add_f32_e32 v196, 1.0, v196
	v_rcp_f32_e32 v196, v196
	s_nop 0
	v_mul_f32_e32 v84, v84, v196
	v_mul_f32_e32 v196, 0xbfb8aa3b, v85
	v_exp_f32_e32 v196, v196
	s_nop 0
	v_add_f32_e32 v196, 1.0, v196
	v_rcp_f32_e32 v196, v196
	s_nop 0
	v_mul_f32_e32 v85, v85, v196
	v_mul_f32_e32 v196, 0xbfb8aa3b, v86
	v_exp_f32_e32 v196, v196
	s_nop 0
	v_add_f32_e32 v196, 1.0, v196
	v_rcp_f32_e32 v196, v196
	s_nop 0
	v_mul_f32_e32 v86, v86, v196
	v_mul_f32_e32 v196, 0xbfb8aa3b, v87
	v_exp_f32_e32 v196, v196
	s_nop 0
	v_add_f32_e32 v196, 1.0, v196
	v_rcp_f32_e32 v196, v196
	s_nop 0
	v_mul_f32_e32 v87, v87, v196
	v_mul_f32_e32 v196, 0xbfb8aa3b, v88
	v_exp_f32_e32 v196, v196
	s_nop 0
	v_add_f32_e32 v196, 1.0, v196
	v_rcp_f32_e32 v196, v196
	s_nop 0
	v_mul_f32_e32 v88, v88, v196
	v_mul_f32_e32 v196, 0xbfb8aa3b, v89
	v_exp_f32_e32 v196, v196
	s_nop 0
	v_add_f32_e32 v196, 1.0, v196
	v_rcp_f32_e32 v196, v196
	s_nop 0
	v_mul_f32_e32 v89, v89, v196
	v_mul_f32_e32 v196, 0xbfb8aa3b, v90
	v_exp_f32_e32 v196, v196
	s_nop 0
	v_add_f32_e32 v196, 1.0, v196
	v_rcp_f32_e32 v196, v196
	s_nop 0
	v_mul_f32_e32 v90, v90, v196
	v_mul_f32_e32 v196, 0xbfb8aa3b, v91
	v_exp_f32_e32 v196, v196
	s_nop 0
	v_add_f32_e32 v196, 1.0, v196
	v_rcp_f32_e32 v196, v196
	s_nop 0
	v_mul_f32_e32 v91, v91, v196
	v_mul_f32_e32 v196, 0xbfb8aa3b, v92
	v_exp_f32_e32 v196, v196
	s_nop 0
	v_add_f32_e32 v196, 1.0, v196
	v_rcp_f32_e32 v196, v196
	s_nop 0
	v_mul_f32_e32 v92, v92, v196
	v_mul_f32_e32 v196, 0xbfb8aa3b, v93
	v_exp_f32_e32 v196, v196
	s_nop 0
	v_add_f32_e32 v196, 1.0, v196
	v_rcp_f32_e32 v196, v196
	s_nop 0
	v_mul_f32_e32 v93, v93, v196
	v_mul_f32_e32 v196, 0xbfb8aa3b, v94
	v_exp_f32_e32 v196, v196
	s_nop 0
	v_add_f32_e32 v196, 1.0, v196
	v_rcp_f32_e32 v196, v196
	s_nop 0
	v_mul_f32_e32 v94, v94, v196
	v_mul_f32_e32 v196, 0xbfb8aa3b, v95
	v_exp_f32_e32 v196, v196
	s_nop 0
	v_add_f32_e32 v196, 1.0, v196
	v_rcp_f32_e32 v196, v196
	s_nop 0
	v_mul_f32_e32 v95, v95, v196
	v_mul_f32_e32 v196, 0xbfb8aa3b, v96
	v_exp_f32_e32 v196, v196
	s_nop 0
	v_add_f32_e32 v196, 1.0, v196
	v_rcp_f32_e32 v196, v196
	s_nop 0
	v_mul_f32_e32 v96, v96, v196
	v_mul_f32_e32 v196, 0xbfb8aa3b, v97
	v_exp_f32_e32 v196, v196
	s_nop 0
	v_add_f32_e32 v196, 1.0, v196
	v_rcp_f32_e32 v196, v196
	s_nop 0
	v_mul_f32_e32 v97, v97, v196
	v_mul_f32_e32 v196, 0xbfb8aa3b, v98
	v_exp_f32_e32 v196, v196
	s_nop 0
	v_add_f32_e32 v196, 1.0, v196
	v_rcp_f32_e32 v196, v196
	s_nop 0
	v_mul_f32_e32 v98, v98, v196
	v_mul_f32_e32 v196, 0xbfb8aa3b, v99
	v_exp_f32_e32 v196, v196
	s_nop 0
	v_add_f32_e32 v196, 1.0, v196
	v_rcp_f32_e32 v196, v196
	s_nop 0
	v_mul_f32_e32 v99, v99, v196
	v_mul_f32_e32 v196, 0xbfb8aa3b, v100
	v_exp_f32_e32 v196, v196
	s_nop 0
	v_add_f32_e32 v196, 1.0, v196
	v_rcp_f32_e32 v196, v196
	s_nop 0
	v_mul_f32_e32 v100, v100, v196
	v_mul_f32_e32 v196, 0xbfb8aa3b, v101
	v_exp_f32_e32 v196, v196
	s_nop 0
	v_add_f32_e32 v196, 1.0, v196
	v_rcp_f32_e32 v196, v196
	s_nop 0
	v_mul_f32_e32 v101, v101, v196
	v_mul_f32_e32 v196, 0xbfb8aa3b, v102
	v_exp_f32_e32 v196, v196
	s_nop 0
	v_add_f32_e32 v196, 1.0, v196
	v_rcp_f32_e32 v196, v196
	s_nop 0
	v_mul_f32_e32 v102, v102, v196
	v_mul_f32_e32 v196, 0xbfb8aa3b, v103
	v_exp_f32_e32 v196, v196
	s_nop 0
	v_add_f32_e32 v196, 1.0, v196
	v_rcp_f32_e32 v196, v196
	s_nop 0
	v_mul_f32_e32 v103, v103, v196
	v_mul_f32_e32 v196, 0xbfb8aa3b, v104
	v_exp_f32_e32 v196, v196
	s_nop 0
	v_add_f32_e32 v196, 1.0, v196
	v_rcp_f32_e32 v196, v196
	s_nop 0
	v_mul_f32_e32 v104, v104, v196
	v_mul_f32_e32 v196, 0xbfb8aa3b, v105
	v_exp_f32_e32 v196, v196
	s_nop 0
	v_add_f32_e32 v196, 1.0, v196
	v_rcp_f32_e32 v196, v196
	s_nop 0
	v_mul_f32_e32 v105, v105, v196
	v_mul_f32_e32 v196, 0xbfb8aa3b, v106
	v_exp_f32_e32 v196, v196
	s_nop 0
	v_add_f32_e32 v196, 1.0, v196
	v_rcp_f32_e32 v196, v196
	s_nop 0
	v_mul_f32_e32 v106, v106, v196
	v_mul_f32_e32 v196, 0xbfb8aa3b, v107
	v_exp_f32_e32 v196, v196
	s_nop 0
	v_add_f32_e32 v196, 1.0, v196
	v_rcp_f32_e32 v196, v196
	s_nop 0
	v_mul_f32_e32 v107, v107, v196
	v_mul_f32_e32 v196, 0xbfb8aa3b, v108
	v_exp_f32_e32 v196, v196
	s_nop 0
	v_add_f32_e32 v196, 1.0, v196
	v_rcp_f32_e32 v196, v196
	s_nop 0
	v_mul_f32_e32 v108, v108, v196
	v_mul_f32_e32 v196, 0xbfb8aa3b, v109
	v_exp_f32_e32 v196, v196
	s_nop 0
	v_add_f32_e32 v196, 1.0, v196
	v_rcp_f32_e32 v196, v196
	s_nop 0
	v_mul_f32_e32 v109, v109, v196
	v_mul_f32_e32 v196, 0xbfb8aa3b, v110
	v_exp_f32_e32 v196, v196
	s_nop 0
	v_add_f32_e32 v196, 1.0, v196
	v_rcp_f32_e32 v196, v196
	s_nop 0
	v_mul_f32_e32 v110, v110, v196
	v_mul_f32_e32 v196, 0xbfb8aa3b, v111
	v_exp_f32_e32 v196, v196
	s_nop 0
	v_add_f32_e32 v196, 1.0, v196
	v_rcp_f32_e32 v196, v196
	s_nop 0
	v_mul_f32_e32 v111, v111, v196
	v_mul_f32_e32 v196, 0xbfb8aa3b, v112
	v_exp_f32_e32 v196, v196
	s_nop 0
	v_add_f32_e32 v196, 1.0, v196
	v_rcp_f32_e32 v196, v196
	s_nop 0
	v_mul_f32_e32 v112, v112, v196
	v_mul_f32_e32 v196, 0xbfb8aa3b, v113
	v_exp_f32_e32 v196, v196
	s_nop 0
	v_add_f32_e32 v196, 1.0, v196
	v_rcp_f32_e32 v196, v196
	s_nop 0
	v_mul_f32_e32 v113, v113, v196
	v_mul_f32_e32 v196, 0xbfb8aa3b, v114
	v_exp_f32_e32 v196, v196
	s_nop 0
	v_add_f32_e32 v196, 1.0, v196
	v_rcp_f32_e32 v196, v196
	s_nop 0
	v_mul_f32_e32 v114, v114, v196
	v_mul_f32_e32 v196, 0xbfb8aa3b, v115
	v_exp_f32_e32 v196, v196
	s_nop 0
	v_add_f32_e32 v196, 1.0, v196
	v_rcp_f32_e32 v196, v196
	s_nop 0
	v_mul_f32_e32 v115, v115, v196
	v_mul_f32_e32 v196, 0xbfb8aa3b, v116
	v_exp_f32_e32 v196, v196
	s_nop 0
	v_add_f32_e32 v196, 1.0, v196
	v_rcp_f32_e32 v196, v196
	s_nop 0
	v_mul_f32_e32 v116, v116, v196
	v_mul_f32_e32 v196, 0xbfb8aa3b, v117
	v_exp_f32_e32 v196, v196
	s_nop 0
	v_add_f32_e32 v196, 1.0, v196
	v_rcp_f32_e32 v196, v196
	s_nop 0
	v_mul_f32_e32 v117, v117, v196
	v_mul_f32_e32 v196, 0xbfb8aa3b, v118
	v_exp_f32_e32 v196, v196
	s_nop 0
	v_add_f32_e32 v196, 1.0, v196
	v_rcp_f32_e32 v196, v196
	s_nop 0
	v_mul_f32_e32 v118, v118, v196
	v_mul_f32_e32 v196, 0xbfb8aa3b, v119
	v_exp_f32_e32 v196, v196
	s_nop 0
	v_add_f32_e32 v196, 1.0, v196
	v_rcp_f32_e32 v196, v196
	s_nop 0
	v_mul_f32_e32 v119, v119, v196
	v_mul_f32_e32 v196, 0xbfb8aa3b, v120
	v_exp_f32_e32 v196, v196
	s_nop 0
	v_add_f32_e32 v196, 1.0, v196
	v_rcp_f32_e32 v196, v196
	s_nop 0
	v_mul_f32_e32 v120, v120, v196
	v_mul_f32_e32 v196, 0xbfb8aa3b, v121
	v_exp_f32_e32 v196, v196
	s_nop 0
	v_add_f32_e32 v196, 1.0, v196
	v_rcp_f32_e32 v196, v196
	s_nop 0
	v_mul_f32_e32 v121, v121, v196
	v_mul_f32_e32 v196, 0xbfb8aa3b, v122
	v_exp_f32_e32 v196, v196
	s_nop 0
	v_add_f32_e32 v196, 1.0, v196
	v_rcp_f32_e32 v196, v196
	s_nop 0
	v_mul_f32_e32 v122, v122, v196
	v_mul_f32_e32 v196, 0xbfb8aa3b, v123
	v_exp_f32_e32 v196, v196
	s_nop 0
	v_add_f32_e32 v196, 1.0, v196
	v_rcp_f32_e32 v196, v196
	s_nop 0
	v_mul_f32_e32 v123, v123, v196
	v_mul_f32_e32 v196, 0xbfb8aa3b, v124
	v_exp_f32_e32 v196, v196
	s_nop 0
	v_add_f32_e32 v196, 1.0, v196
	v_rcp_f32_e32 v196, v196
	s_nop 0
	v_mul_f32_e32 v124, v124, v196
	v_mul_f32_e32 v196, 0xbfb8aa3b, v125
	v_exp_f32_e32 v196, v196
	s_nop 0
	v_add_f32_e32 v196, 1.0, v196
	v_rcp_f32_e32 v196, v196
	s_nop 0
	v_mul_f32_e32 v125, v125, v196
	v_mul_f32_e32 v196, 0xbfb8aa3b, v126
	v_exp_f32_e32 v196, v196
	s_nop 0
	v_add_f32_e32 v196, 1.0, v196
	v_rcp_f32_e32 v196, v196
	s_nop 0
	v_mul_f32_e32 v126, v126, v196
	v_mul_f32_e32 v196, 0xbfb8aa3b, v127
	v_exp_f32_e32 v196, v196
	s_nop 0
	v_add_f32_e32 v196, 1.0, v196
	v_rcp_f32_e32 v196, v196
	s_nop 0
	v_mul_f32_e32 v127, v127, v196
	v_mul_f32_e32 v196, 0xbfb8aa3b, v128
	v_exp_f32_e32 v196, v196
	s_nop 0
	v_add_f32_e32 v196, 1.0, v196
	v_rcp_f32_e32 v196, v196
	s_nop 0
	v_mul_f32_e32 v128, v128, v196
	v_mul_f32_e32 v196, 0xbfb8aa3b, v129
	v_exp_f32_e32 v196, v196
	s_nop 0
	v_add_f32_e32 v196, 1.0, v196
	v_rcp_f32_e32 v196, v196
	s_nop 0
	v_mul_f32_e32 v129, v129, v196
	s_mov_b32 s21, 0x3f800000
.Lpj_row:
	s_lshl_b32 s26, s43, 6
	s_add_i32 s66, s66, s26
	v_mul_lo_u32 v179, v227, s39
	v_add_u32_e32 v179, v179, v228
	s_mul_i32 s26, s35, s39
	s_lshl_b32 s27, s66, 1
	s_add_i32 s26, s26, s27
	s_lshl_b32 s27, s39, 4
	s_waitcnt vmcnt(0) lgkmcnt(0)
	s_add_u32 s6, s18, s26
	s_addc_u32 s7, s19, 0
	v_mul_f32_e32 v2, s21, v2
	v_mul_f32_e32 v3, s21, v3
	v_mul_f32_e32 v4, s21, v4
	v_mul_f32_e32 v5, s21, v5
	v_mul_f32_e32 v6, s21, v6
	v_mul_f32_e32 v7, s21, v7
	v_mul_f32_e32 v8, s21, v8
	v_mul_f32_e32 v9, s21, v9
	v_cvt_pk_bf16_f32 v2, v2, v3
	v_cvt_pk_bf16_f32 v3, v4, v5
	v_cvt_pk_bf16_f32 v4, v6, v7
	v_cvt_pk_bf16_f32 v5, v8, v9
	global_store_dwordx4 v179, v[2:5], s[6:7]
	v_mul_f32_e32 v10, s21, v10
	v_mul_f32_e32 v11, s21, v11
	v_mul_f32_e32 v12, s21, v12
	v_mul_f32_e32 v13, s21, v13
	v_mul_f32_e32 v14, s21, v14
	v_mul_f32_e32 v15, s21, v15
	v_mul_f32_e32 v16, s21, v16
	v_mul_f32_e32 v17, s21, v17
	v_cvt_pk_bf16_f32 v10, v10, v11
	v_cvt_pk_bf16_f32 v11, v12, v13
	v_cvt_pk_bf16_f32 v12, v14, v15
	v_cvt_pk_bf16_f32 v13, v16, v17
	global_store_dwordx4 v179, v[10:13], s[6:7] offset:64
	s_add_u32 s6, s6, s27
	s_addc_u32 s7, s7, 0
	v_mul_f32_e32 v18, s21, v18
	v_mul_f32_e32 v19, s21, v19
	v_mul_f32_e32 v20, s21, v20
	v_mul_f32_e32 v21, s21, v21
	v_mul_f32_e32 v22, s21, v22
	v_mul_f32_e32 v23, s21, v23
	v_mul_f32_e32 v24, s21, v24
	v_mul_f32_e32 v25, s21, v25
	v_cvt_pk_bf16_f32 v18, v18, v19
	v_cvt_pk_bf16_f32 v19, v20, v21
	v_cvt_pk_bf16_f32 v20, v22, v23
	v_cvt_pk_bf16_f32 v21, v24, v25
	global_store_dwordx4 v179, v[18:21], s[6:7]
	v_mul_f32_e32 v26, s21, v26
	v_mul_f32_e32 v27, s21, v27
	v_mul_f32_e32 v28, s21, v28
	v_mul_f32_e32 v29, s21, v29
	v_mul_f32_e32 v30, s21, v30
	v_mul_f32_e32 v31, s21, v31
	v_mul_f32_e32 v32, s21, v32
	v_mul_f32_e32 v33, s21, v33
	v_cvt_pk_bf16_f32 v26, v26, v27
	v_cvt_pk_bf16_f32 v27, v28, v29
	v_cvt_pk_bf16_f32 v28, v30, v31
	v_cvt_pk_bf16_f32 v29, v32, v33
	global_store_dwordx4 v179, v[26:29], s[6:7] offset:64
	s_add_u32 s6, s6, s27
	s_addc_u32 s7, s7, 0
	v_mul_f32_e32 v34, s21, v34
	v_mul_f32_e32 v35, s21, v35
	v_mul_f32_e32 v36, s21, v36
	v_mul_f32_e32 v37, s21, v37
	v_mul_f32_e32 v38, s21, v38
	v_mul_f32_e32 v39, s21, v39
	v_mul_f32_e32 v40, s21, v40
	v_mul_f32_e32 v41, s21, v41
	v_cvt_pk_bf16_f32 v34, v34, v35
	v_cvt_pk_bf16_f32 v35, v36, v37
	v_cvt_pk_bf16_f32 v36, v38, v39
	v_cvt_pk_bf16_f32 v37, v40, v41
	global_store_dwordx4 v179, v[34:37], s[6:7]
	v_mul_f32_e32 v42, s21, v42
	v_mul_f32_e32 v43, s21, v43
	v_mul_f32_e32 v44, s21, v44
	v_mul_f32_e32 v45, s21, v45
	v_mul_f32_e32 v46, s21, v46
	v_mul_f32_e32 v47, s21, v47
	v_mul_f32_e32 v48, s21, v48
	v_mul_f32_e32 v49, s21, v49
	v_cvt_pk_bf16_f32 v42, v42, v43
	v_cvt_pk_bf16_f32 v43, v44, v45
	v_cvt_pk_bf16_f32 v44, v46, v47
	v_cvt_pk_bf16_f32 v45, v48, v49
	global_store_dwordx4 v179, v[42:45], s[6:7] offset:64
	s_add_u32 s6, s6, s27
	s_addc_u32 s7, s7, 0
	v_mul_f32_e32 v50, s21, v50
	v_mul_f32_e32 v51, s21, v51
	v_mul_f32_e32 v52, s21, v52
	v_mul_f32_e32 v53, s21, v53
	v_mul_f32_e32 v54, s21, v54
	v_mul_f32_e32 v55, s21, v55
	v_mul_f32_e32 v56, s21, v56
	v_mul_f32_e32 v57, s21, v57
	v_cvt_pk_bf16_f32 v50, v50, v51
	v_cvt_pk_bf16_f32 v51, v52, v53
	v_cvt_pk_bf16_f32 v52, v54, v55
	v_cvt_pk_bf16_f32 v53, v56, v57
	global_store_dwordx4 v179, v[50:53], s[6:7]
	v_mul_f32_e32 v58, s21, v58
	v_mul_f32_e32 v59, s21, v59
	v_mul_f32_e32 v60, s21, v60
	v_mul_f32_e32 v61, s21, v61
	v_mul_f32_e32 v62, s21, v62
	v_mul_f32_e32 v63, s21, v63
	v_mul_f32_e32 v64, s21, v64
	v_mul_f32_e32 v65, s21, v65
	v_cvt_pk_bf16_f32 v58, v58, v59
	v_cvt_pk_bf16_f32 v59, v60, v61
	v_cvt_pk_bf16_f32 v60, v62, v63
	v_cvt_pk_bf16_f32 v61, v64, v65
	global_store_dwordx4 v179, v[58:61], s[6:7] offset:64
	s_add_u32 s6, s6, s27
	s_addc_u32 s7, s7, 0
	v_mul_f32_e32 v66, s21, v66
	v_mul_f32_e32 v67, s21, v67
	v_mul_f32_e32 v68, s21, v68
	v_mul_f32_e32 v69, s21, v69
	v_mul_f32_e32 v70, s21, v70
	v_mul_f32_e32 v71, s21, v71
	v_mul_f32_e32 v72, s21, v72
	v_mul_f32_e32 v73, s21, v73
	v_cvt_pk_bf16_f32 v66, v66, v67
	v_cvt_pk_bf16_f32 v67, v68, v69
	v_cvt_pk_bf16_f32 v68, v70, v71
	v_cvt_pk_bf16_f32 v69, v72, v73
	global_store_dwordx4 v179, v[66:69], s[6:7]
	v_mul_f32_e32 v74, s21, v74
	v_mul_f32_e32 v75, s21, v75
	v_mul_f32_e32 v76, s21, v76
	v_mul_f32_e32 v77, s21, v77
	v_mul_f32_e32 v78, s21, v78
	v_mul_f32_e32 v79, s21, v79
	v_mul_f32_e32 v80, s21, v80
	v_mul_f32_e32 v81, s21, v81
	v_cvt_pk_bf16_f32 v74, v74, v75
	v_cvt_pk_bf16_f32 v75, v76, v77
	v_cvt_pk_bf16_f32 v76, v78, v79
	v_cvt_pk_bf16_f32 v77, v80, v81
	global_store_dwordx4 v179, v[74:77], s[6:7] offset:64
	s_add_u32 s6, s6, s27
	s_addc_u32 s7, s7, 0
	v_mul_f32_e32 v82, s21, v82
	v_mul_f32_e32 v83, s21, v83
	v_mul_f32_e32 v84, s21, v84
	v_mul_f32_e32 v85, s21, v85
	v_mul_f32_e32 v86, s21, v86
	v_mul_f32_e32 v87, s21, v87
	v_mul_f32_e32 v88, s21, v88
	v_mul_f32_e32 v89, s21, v89
	v_cvt_pk_bf16_f32 v82, v82, v83
	v_cvt_pk_bf16_f32 v83, v84, v85
	v_cvt_pk_bf16_f32 v84, v86, v87
	v_cvt_pk_bf16_f32 v85, v88, v89
	global_store_dwordx4 v179, v[82:85], s[6:7]
	v_mul_f32_e32 v90, s21, v90
	v_mul_f32_e32 v91, s21, v91
	v_mul_f32_e32 v92, s21, v92
	v_mul_f32_e32 v93, s21, v93
	v_mul_f32_e32 v94, s21, v94
	v_mul_f32_e32 v95, s21, v95
	v_mul_f32_e32 v96, s21, v96
	v_mul_f32_e32 v97, s21, v97
	v_cvt_pk_bf16_f32 v90, v90, v91
	v_cvt_pk_bf16_f32 v91, v92, v93
	v_cvt_pk_bf16_f32 v92, v94, v95
	v_cvt_pk_bf16_f32 v93, v96, v97
	global_store_dwordx4 v179, v[90:93], s[6:7] offset:64
	s_add_u32 s6, s6, s27
	s_addc_u32 s7, s7, 0
	v_mul_f32_e32 v98, s21, v98
	v_mul_f32_e32 v99, s21, v99
	v_mul_f32_e32 v100, s21, v100
	v_mul_f32_e32 v101, s21, v101
	v_mul_f32_e32 v102, s21, v102
	v_mul_f32_e32 v103, s21, v103
	v_mul_f32_e32 v104, s21, v104
	v_mul_f32_e32 v105, s21, v105
	v_cvt_pk_bf16_f32 v98, v98, v99
	v_cvt_pk_bf16_f32 v99, v100, v101
	v_cvt_pk_bf16_f32 v100, v102, v103
	v_cvt_pk_bf16_f32 v101, v104, v105
	global_store_dwordx4 v179, v[98:101], s[6:7]
	v_mul_f32_e32 v106, s21, v106
	v_mul_f32_e32 v107, s21, v107
	v_mul_f32_e32 v108, s21, v108
	v_mul_f32_e32 v109, s21, v109
	v_mul_f32_e32 v110, s21, v110
	v_mul_f32_e32 v111, s21, v111
	v_mul_f32_e32 v112, s21, v112
	v_mul_f32_e32 v113, s21, v113
	v_cvt_pk_bf16_f32 v106, v106, v107
	v_cvt_pk_bf16_f32 v107, v108, v109
	v_cvt_pk_bf16_f32 v108, v110, v111
	v_cvt_pk_bf16_f32 v109, v112, v113
	global_store_dwordx4 v179, v[106:109], s[6:7] offset:64
	s_add_u32 s6, s6, s27
	s_addc_u32 s7, s7, 0
	v_mul_f32_e32 v114, s21, v114
	v_mul_f32_e32 v115, s21, v115
	v_mul_f32_e32 v116, s21, v116
	v_mul_f32_e32 v117, s21, v117
	v_mul_f32_e32 v118, s21, v118
	v_mul_f32_e32 v119, s21, v119
	v_mul_f32_e32 v120, s21, v120
	v_mul_f32_e32 v121, s21, v121
	v_cvt_pk_bf16_f32 v114, v114, v115
	v_cvt_pk_bf16_f32 v115, v116, v117
	v_cvt_pk_bf16_f32 v116, v118, v119
	v_cvt_pk_bf16_f32 v117, v120, v121
	global_store_dwordx4 v179, v[114:117], s[6:7]
	v_mul_f32_e32 v122, s21, v122
	v_mul_f32_e32 v123, s21, v123
	v_mul_f32_e32 v124, s21, v124
	v_mul_f32_e32 v125, s21, v125
	v_mul_f32_e32 v126, s21, v126
	v_mul_f32_e32 v127, s21, v127
	v_mul_f32_e32 v128, s21, v128
	v_mul_f32_e32 v129, s21, v129
	v_cvt_pk_bf16_f32 v122, v122, v123
	v_cvt_pk_bf16_f32 v123, v124, v125
	v_cvt_pk_bf16_f32 v124, v126, v127
	v_cvt_pk_bf16_f32 v125, v128, v129
	global_store_dwordx4 v179, v[122:125], s[6:7] offset:64
	s_branch .Lpj_epi_end
.Lpj_vt:
	s_lshr_b32 s26, s35, 12
	s_mul_i32 s26, s26, s90
	s_add_i32 s26, s26, s89
	s_lshl_b32 s26, s26, 18
	s_and_b32 s27, s35, 0xfff
	s_add_i32 s26, s26, s27
	s_lshl_b32 s26, s26, 1
	v_lshlrev_b32_e32 v179, 12, v228
	v_lshl_add_u32 v179, v227, 1, v179
	s_waitcnt vmcnt(0) lgkmcnt(0)
	s_add_u32 s6, s18, s26
	s_addc_u32 s7, s19, 0
	v_cvt_pk_bf16_f32 v2, v2, v2
	v_cvt_pk_bf16_f32 v18, v18, v18
	v_cvt_pk_bf16_f32 v34, v34, v34
	v_cvt_pk_bf16_f32 v50, v50, v50
	v_cvt_pk_bf16_f32 v66, v66, v66
	v_cvt_pk_bf16_f32 v82, v82, v82
	v_cvt_pk_bf16_f32 v98, v98, v98
	v_cvt_pk_bf16_f32 v114, v114, v114
	global_store_short v179, v2, s[6:7]
	global_store_short v179, v18, s[6:7] offset:32
	global_store_short v179, v34, s[6:7] offset:64
	global_store_short v179, v50, s[6:7] offset:96
	global_store_short v179, v66, s[6:7] offset:128
	global_store_short v179, v82, s[6:7] offset:160
	global_store_short v179, v98, s[6:7] offset:192
	global_store_short v179, v114, s[6:7] offset:224
	s_add_u32 s6, s6, 0x2000
	s_addc_u32 s7, s7, 0
	v_cvt_pk_bf16_f32 v3, v3, v3
	v_cvt_pk_bf16_f32 v19, v19, v19
	v_cvt_pk_bf16_f32 v35, v35, v35
	v_cvt_pk_bf16_f32 v51, v51, v51
	v_cvt_pk_bf16_f32 v67, v67, v67
	v_cvt_pk_bf16_f32 v83, v83, v83
	v_cvt_pk_bf16_f32 v99, v99, v99
	v_cvt_pk_bf16_f32 v115, v115, v115
	global_store_short v179, v3, s[6:7]
	global_store_short v179, v19, s[6:7] offset:32
	global_store_short v179, v35, s[6:7] offset:64
	global_store_short v179, v51, s[6:7] offset:96
	global_store_short v179, v67, s[6:7] offset:128
	global_store_short v179, v83, s[6:7] offset:160
	global_store_short v179, v99, s[6:7] offset:192
	global_store_short v179, v115, s[6:7] offset:224
	s_add_u32 s6, s6, 0x2000
	s_addc_u32 s7, s7, 0
	v_cvt_pk_bf16_f32 v4, v4, v4
	v_cvt_pk_bf16_f32 v20, v20, v20
	v_cvt_pk_bf16_f32 v36, v36, v36
	v_cvt_pk_bf16_f32 v52, v52, v52
	v_cvt_pk_bf16_f32 v68, v68, v68
	v_cvt_pk_bf16_f32 v84, v84, v84
	v_cvt_pk_bf16_f32 v100, v100, v100
	v_cvt_pk_bf16_f32 v116, v116, v116
	global_store_short v179, v4, s[6:7]
	global_store_short v179, v20, s[6:7] offset:32
	global_store_short v179, v36, s[6:7] offset:64
	global_store_short v179, v52, s[6:7] offset:96
	global_store_short v179, v68, s[6:7] offset:128
	global_store_short v179, v84, s[6:7] offset:160
	global_store_short v179, v100, s[6:7] offset:192
	global_store_short v179, v116, s[6:7] offset:224
	s_add_u32 s6, s6, 0x2000
	s_addc_u32 s7, s7, 0
	v_cvt_pk_bf16_f32 v5, v5, v5
	v_cvt_pk_bf16_f32 v21, v21, v21
	v_cvt_pk_bf16_f32 v37, v37, v37
	v_cvt_pk_bf16_f32 v53, v53, v53
	v_cvt_pk_bf16_f32 v69, v69, v69
	v_cvt_pk_bf16_f32 v85, v85, v85
	v_cvt_pk_bf16_f32 v101, v101, v101
	v_cvt_pk_bf16_f32 v117, v117, v117
	global_store_short v179, v5, s[6:7]
	global_store_short v179, v21, s[6:7] offset:32
	global_store_short v179, v37, s[6:7] offset:64
	global_store_short v179, v53, s[6:7] offset:96
	global_store_short v179, v69, s[6:7] offset:128
	global_store_short v179, v85, s[6:7] offset:160
	global_store_short v179, v101, s[6:7] offset:192
	global_store_short v179, v117, s[6:7] offset:224
	s_add_u32 s6, s6, 0x2000
	s_addc_u32 s7, s7, 0
	v_cvt_pk_bf16_f32 v6, v6, v6
	v_cvt_pk_bf16_f32 v22, v22, v22
	v_cvt_pk_bf16_f32 v38, v38, v38
	v_cvt_pk_bf16_f32 v54, v54, v54
	v_cvt_pk_bf16_f32 v70, v70, v70
	v_cvt_pk_bf16_f32 v86, v86, v86
	v_cvt_pk_bf16_f32 v102, v102, v102
	v_cvt_pk_bf16_f32 v118, v118, v118
	global_store_short v179, v6, s[6:7]
	global_store_short v179, v22, s[6:7] offset:32
	global_store_short v179, v38, s[6:7] offset:64
	global_store_short v179, v54, s[6:7] offset:96
	global_store_short v179, v70, s[6:7] offset:128
	global_store_short v179, v86, s[6:7] offset:160
	global_store_short v179, v102, s[6:7] offset:192
	global_store_short v179, v118, s[6:7] offset:224
	s_add_u32 s6, s6, 0x2000
	s_addc_u32 s7, s7, 0
	v_cvt_pk_bf16_f32 v7, v7, v7
	v_cvt_pk_bf16_f32 v23, v23, v23
	v_cvt_pk_bf16_f32 v39, v39, v39
	v_cvt_pk_bf16_f32 v55, v55, v55
	v_cvt_pk_bf16_f32 v71, v71, v71
	v_cvt_pk_bf16_f32 v87, v87, v87
	v_cvt_pk_bf16_f32 v103, v103, v103
	v_cvt_pk_bf16_f32 v119, v119, v119
	global_store_short v179, v7, s[6:7]
	global_store_short v179, v23, s[6:7] offset:32
	global_store_short v179, v39, s[6:7] offset:64
	global_store_short v179, v55, s[6:7] offset:96
	global_store_short v179, v71, s[6:7] offset:128
	global_store_short v179, v87, s[6:7] offset:160
	global_store_short v179, v103, s[6:7] offset:192
	global_store_short v179, v119, s[6:7] offset:224
	s_add_u32 s6, s6, 0x2000
	s_addc_u32 s7, s7, 0
	v_cvt_pk_bf16_f32 v8, v8, v8
	v_cvt_pk_bf16_f32 v24, v24, v24
	v_cvt_pk_bf16_f32 v40, v40, v40
	v_cvt_pk_bf16_f32 v56, v56, v56
	v_cvt_pk_bf16_f32 v72, v72, v72
	v_cvt_pk_bf16_f32 v88, v88, v88
	v_cvt_pk_bf16_f32 v104, v104, v104
	v_cvt_pk_bf16_f32 v120, v120, v120
	global_store_short v179, v8, s[6:7]
	global_store_short v179, v24, s[6:7] offset:32
	global_store_short v179, v40, s[6:7] offset:64
	global_store_short v179, v56, s[6:7] offset:96
	global_store_short v179, v72, s[6:7] offset:128
	global_store_short v179, v88, s[6:7] offset:160
	global_store_short v179, v104, s[6:7] offset:192
	global_store_short v179, v120, s[6:7] offset:224
	s_add_u32 s6, s6, 0x2000
	s_addc_u32 s7, s7, 0
	v_cvt_pk_bf16_f32 v9, v9, v9
	v_cvt_pk_bf16_f32 v25, v25, v25
	v_cvt_pk_bf16_f32 v41, v41, v41
	v_cvt_pk_bf16_f32 v57, v57, v57
	v_cvt_pk_bf16_f32 v73, v73, v73
	v_cvt_pk_bf16_f32 v89, v89, v89
	v_cvt_pk_bf16_f32 v105, v105, v105
	v_cvt_pk_bf16_f32 v121, v121, v121
	global_store_short v179, v9, s[6:7]
	global_store_short v179, v25, s[6:7] offset:32
	global_store_short v179, v41, s[6:7] offset:64
	global_store_short v179, v57, s[6:7] offset:96
	global_store_short v179, v73, s[6:7] offset:128
	global_store_short v179, v89, s[6:7] offset:160
	global_store_short v179, v105, s[6:7] offset:192
	global_store_short v179, v121, s[6:7] offset:224
	s_add_u32 s6, s6, 0x32000
	s_addc_u32 s7, s7, 0
	v_cvt_pk_bf16_f32 v10, v10, v10
	v_cvt_pk_bf16_f32 v26, v26, v26
	v_cvt_pk_bf16_f32 v42, v42, v42
	v_cvt_pk_bf16_f32 v58, v58, v58
	v_cvt_pk_bf16_f32 v74, v74, v74
	v_cvt_pk_bf16_f32 v90, v90, v90
	v_cvt_pk_bf16_f32 v106, v106, v106
	v_cvt_pk_bf16_f32 v122, v122, v122
	global_store_short v179, v10, s[6:7]
	global_store_short v179, v26, s[6:7] offset:32
	global_store_short v179, v42, s[6:7] offset:64
	global_store_short v179, v58, s[6:7] offset:96
	global_store_short v179, v74, s[6:7] offset:128
	global_store_short v179, v90, s[6:7] offset:160
	global_store_short v179, v106, s[6:7] offset:192
	global_store_short v179, v122, s[6:7] offset:224
	s_add_u32 s6, s6, 0x2000
	s_addc_u32 s7, s7, 0
	v_cvt_pk_bf16_f32 v11, v11, v11
	v_cvt_pk_bf16_f32 v27, v27, v27
	v_cvt_pk_bf16_f32 v43, v43, v43
	v_cvt_pk_bf16_f32 v59, v59, v59
	v_cvt_pk_bf16_f32 v75, v75, v75
	v_cvt_pk_bf16_f32 v91, v91, v91
	v_cvt_pk_bf16_f32 v107, v107, v107
	v_cvt_pk_bf16_f32 v123, v123, v123
	global_store_short v179, v11, s[6:7]
	global_store_short v179, v27, s[6:7] offset:32
	global_store_short v179, v43, s[6:7] offset:64
	global_store_short v179, v59, s[6:7] offset:96
	global_store_short v179, v75, s[6:7] offset:128
	global_store_short v179, v91, s[6:7] offset:160
	global_store_short v179, v107, s[6:7] offset:192
	global_store_short v179, v123, s[6:7] offset:224
	s_add_u32 s6, s6, 0x2000
	s_addc_u32 s7, s7, 0
	v_cvt_pk_bf16_f32 v12, v12, v12
	v_cvt_pk_bf16_f32 v28, v28, v28
	v_cvt_pk_bf16_f32 v44, v44, v44
	v_cvt_pk_bf16_f32 v60, v60, v60
	v_cvt_pk_bf16_f32 v76, v76, v76
	v_cvt_pk_bf16_f32 v92, v92, v92
	v_cvt_pk_bf16_f32 v108, v108, v108
	v_cvt_pk_bf16_f32 v124, v124, v124
	global_store_short v179, v12, s[6:7]
	global_store_short v179, v28, s[6:7] offset:32
	global_store_short v179, v44, s[6:7] offset:64
	global_store_short v179, v60, s[6:7] offset:96
	global_store_short v179, v76, s[6:7] offset:128
	global_store_short v179, v92, s[6:7] offset:160
	global_store_short v179, v108, s[6:7] offset:192
	global_store_short v179, v124, s[6:7] offset:224
	s_add_u32 s6, s6, 0x2000
	s_addc_u32 s7, s7, 0
	v_cvt_pk_bf16_f32 v13, v13, v13
	v_cvt_pk_bf16_f32 v29, v29, v29
	v_cvt_pk_bf16_f32 v45, v45, v45
	v_cvt_pk_bf16_f32 v61, v61, v61
	v_cvt_pk_bf16_f32 v77, v77, v77
	v_cvt_pk_bf16_f32 v93, v93, v93
	v_cvt_pk_bf16_f32 v109, v109, v109
	v_cvt_pk_bf16_f32 v125, v125, v125
	global_store_short v179, v13, s[6:7]
	global_store_short v179, v29, s[6:7] offset:32
	global_store_short v179, v45, s[6:7] offset:64
	global_store_short v179, v61, s[6:7] offset:96
	global_store_short v179, v77, s[6:7] offset:128
	global_store_short v179, v93, s[6:7] offset:160
	global_store_short v179, v109, s[6:7] offset:192
	global_store_short v179, v125, s[6:7] offset:224
	s_add_u32 s6, s6, 0x2000
	s_addc_u32 s7, s7, 0
	v_cvt_pk_bf16_f32 v14, v14, v14
	v_cvt_pk_bf16_f32 v30, v30, v30
	v_cvt_pk_bf16_f32 v46, v46, v46
	v_cvt_pk_bf16_f32 v62, v62, v62
	v_cvt_pk_bf16_f32 v78, v78, v78
	v_cvt_pk_bf16_f32 v94, v94, v94
	v_cvt_pk_bf16_f32 v110, v110, v110
	v_cvt_pk_bf16_f32 v126, v126, v126
	global_store_short v179, v14, s[6:7]
	global_store_short v179, v30, s[6:7] offset:32
	global_store_short v179, v46, s[6:7] offset:64
	global_store_short v179, v62, s[6:7] offset:96
	global_store_short v179, v78, s[6:7] offset:128
	global_store_short v179, v94, s[6:7] offset:160
	global_store_short v179, v110, s[6:7] offset:192
	global_store_short v179, v126, s[6:7] offset:224
	s_add_u32 s6, s6, 0x2000
	s_addc_u32 s7, s7, 0
	v_cvt_pk_bf16_f32 v15, v15, v15
	v_cvt_pk_bf16_f32 v31, v31, v31
	v_cvt_pk_bf16_f32 v47, v47, v47
	v_cvt_pk_bf16_f32 v63, v63, v63
	v_cvt_pk_bf16_f32 v79, v79, v79
	v_cvt_pk_bf16_f32 v95, v95, v95
	v_cvt_pk_bf16_f32 v111, v111, v111
	v_cvt_pk_bf16_f32 v127, v127, v127
	global_store_short v179, v15, s[6:7]
	global_store_short v179, v31, s[6:7] offset:32
	global_store_short v179, v47, s[6:7] offset:64
	global_store_short v179, v63, s[6:7] offset:96
	global_store_short v179, v79, s[6:7] offset:128
	global_store_short v179, v95, s[6:7] offset:160
	global_store_short v179, v111, s[6:7] offset:192
	global_store_short v179, v127, s[6:7] offset:224
	s_add_u32 s6, s6, 0x2000
	s_addc_u32 s7, s7, 0
	v_cvt_pk_bf16_f32 v16, v16, v16
	v_cvt_pk_bf16_f32 v32, v32, v32
	v_cvt_pk_bf16_f32 v48, v48, v48
	v_cvt_pk_bf16_f32 v64, v64, v64
	v_cvt_pk_bf16_f32 v80, v80, v80
	v_cvt_pk_bf16_f32 v96, v96, v96
	v_cvt_pk_bf16_f32 v112, v112, v112
	v_cvt_pk_bf16_f32 v128, v128, v128
	global_store_short v179, v16, s[6:7]
	global_store_short v179, v32, s[6:7] offset:32
	global_store_short v179, v48, s[6:7] offset:64
	global_store_short v179, v64, s[6:7] offset:96
	global_store_short v179, v80, s[6:7] offset:128
	global_store_short v179, v96, s[6:7] offset:160
	global_store_short v179, v112, s[6:7] offset:192
	global_store_short v179, v128, s[6:7] offset:224
	s_add_u32 s6, s6, 0x2000
	s_addc_u32 s7, s7, 0
	v_cvt_pk_bf16_f32 v17, v17, v17
	v_cvt_pk_bf16_f32 v33, v33, v33
	v_cvt_pk_bf16_f32 v49, v49, v49
	v_cvt_pk_bf16_f32 v65, v65, v65
	v_cvt_pk_bf16_f32 v81, v81, v81
	v_cvt_pk_bf16_f32 v97, v97, v97
	v_cvt_pk_bf16_f32 v113, v113, v113
	v_cvt_pk_bf16_f32 v129, v129, v129
	global_store_short v179, v17, s[6:7]
	global_store_short v179, v33, s[6:7] offset:32
	global_store_short v179, v49, s[6:7] offset:64
	global_store_short v179, v65, s[6:7] offset:96
	global_store_short v179, v81, s[6:7] offset:128
	global_store_short v179, v97, s[6:7] offset:160
	global_store_short v179, v113, s[6:7] offset:192
	global_store_short v179, v129, s[6:7] offset:224
	s_branch .Lpj_epi_end
.Lpj_glr:
	s_load_dwordx2 s[18:19], s[0:1], 0x100
	s_lshl_b32 s26, s35, 6
	v_lshlrev_b32_e32 v179, 1, v228
	v_lshl_add_u32 v179, v227, 6, v179
	s_waitcnt vmcnt(0) lgkmcnt(0)
	s_cmp_eq_u32 s43, 0
	s_cbranch_scc0 .Lpj_epi_end
	s_add_u32 s6, s18, s26
	s_addc_u32 s7, s19, 0
	s_mov_b32 exec_lo, -1
	s_mov_b32 exec_hi, 0
	global_store_dwordx4 v179, v[2:5], s[6:7]
	global_store_dwordx4 v179, v[6:9], s[6:7] offset:16
	s_add_u32 s6, s6, 0x400
	s_addc_u32 s7, s7, 0
	global_store_dwordx4 v179, v[18:21], s[6:7]
	global_store_dwordx4 v179, v[22:25], s[6:7] offset:16
	s_add_u32 s6, s6, 0x400
	s_addc_u32 s7, s7, 0
	global_store_dwordx4 v179, v[34:37], s[6:7]
	global_store_dwordx4 v179, v[38:41], s[6:7] offset:16
	s_add_u32 s6, s6, 0x400
	s_addc_u32 s7, s7, 0
	global_store_dwordx4 v179, v[50:53], s[6:7]
	global_store_dwordx4 v179, v[54:57], s[6:7] offset:16
	s_add_u32 s6, s6, 0x400
	s_addc_u32 s7, s7, 0
	global_store_dwordx4 v179, v[66:69], s[6:7]
	global_store_dwordx4 v179, v[70:73], s[6:7] offset:16
	s_add_u32 s6, s6, 0x400
	s_addc_u32 s7, s7, 0
	global_store_dwordx4 v179, v[82:85], s[6:7]
	global_store_dwordx4 v179, v[86:89], s[6:7] offset:16
	s_add_u32 s6, s6, 0x400
	s_addc_u32 s7, s7, 0
	global_store_dwordx4 v179, v[98:101], s[6:7]
	global_store_dwordx4 v179, v[102:105], s[6:7] offset:16
	s_add_u32 s6, s6, 0x400
	s_addc_u32 s7, s7, 0
	global_store_dwordx4 v179, v[114:117], s[6:7]
	global_store_dwordx4 v179, v[118:121], s[6:7] offset:16
	s_mov_b64 exec, -1
.Lpj_epi_end:
	s_cmp_lg_u32 s37, 0
	s_cbranch_scc1 .Lpj_ret_n
